# v-sweep: per-row index and weight via LDS broadcast reads, structured buffer idxen (no readlane)
# speedup vs baseline: 1.0002x; 1.0002x over previous
.LBB0_1012:
	v_cndmask_b32_e64 v103, v97, v93, s[0:1]
	v_cndmask_b32_e64 v104, v87, v85, s[0:1]
	v_cndmask_b32_e64 v105, v99, v95, s[0:1]
	v_cndmask_b32_e64 v106, v92, v86, s[0:1]
	v_cndmask_b32_e64 v107, v98, v94, s[0:1]
	v_cndmask_b32_e64 v108, v91, v89, s[0:1]
	v_cndmask_b32_e64 v109, v100, v96, s[0:1]
	v_cndmask_b32_e64 v110, v88, v90, s[0:1]
	s_xor_b64 s[8:9], s[0:1], -1
	s_lshl_b32 s0, s10, 11
	s_add_i32 s0, s26, s0
	v_mbcnt_lo_u32_b32 v150, -1, 0
	v_mbcnt_hi_u32_b32 v150, -1, v150
	v_lshl_add_u32 v111, v150, 2, s0
	v_mov_b32_e32 v115, s0
	v_lshlrev_b32_e32 v177, 4, v150
	v_lshlrev_b32_e32 v179, 4, v150
	v_lshlrev_b32_e32 v181, 4, v150
	v_lshlrev_b32_e32 v183, 4, v150
	v_lshrrev_b32_e32 v151, 7, v103
	ds_write_b32 v111, v151 offset:8192
	v_lshrrev_b32_e32 v152, 7, v107
	ds_write_b32 v111, v152 offset:8448
	v_lshrrev_b32_e32 v151, 7, v104
	ds_write_b32 v111, v151 offset:8704
	v_lshrrev_b32_e32 v152, 7, v108
	ds_write_b32 v111, v152 offset:8960
	v_lshrrev_b32_e32 v151, 7, v105
	ds_write_b32 v111, v151 offset:9216
	v_lshrrev_b32_e32 v152, 7, v109
	ds_write_b32 v111, v152 offset:9472
	v_lshrrev_b32_e32 v151, 7, v106
	ds_write_b32 v111, v151 offset:9728
	v_lshrrev_b32_e32 v152, 7, v110
	ds_write_b32 v111, v152 offset:9984
	s_add_u32 s12, s72, 0x4300000
	s_addc_u32 s13, s73, 0
	s_and_b32 s13, s13, 0xffff
	s_or_b32 s13, s13, 0x4000000
	s_movk_i32 s14, 0x4000
	s_mov_b32 s15, 0x20000
	v_mov_b32_e32 v139, 0
	v_mov_b32_e32 v138, 0
	v_mov_b32_e32 v136, 0
	v_mov_b32_e32 v135, 0
	v_mov_b32_e32 v134, 0
	v_mov_b32_e32 v133, 0
	v_mov_b32_e32 v132, 0
	v_mov_b32_e32 v131, 0
	v_mov_b32_e32 v130, 0
	v_mov_b32_e32 v129, 0
	v_mov_b32_e32 v128, 0
	v_mov_b32_e32 v127, 0
	v_mov_b32_e32 v126, 0
	v_mov_b32_e32 v114, 0
	v_mov_b32_e32 v140, 0
	v_mov_b32_e32 v137, 0
	v_mov_b32_e32 v124, 0
	v_mov_b32_e32 v123, 0
	v_mov_b32_e32 v121, 0
	v_mov_b32_e32 v120, 0
	v_mov_b32_e32 v119, 0
	v_mov_b32_e32 v118, 0
	v_mov_b32_e32 v117, 0
	v_mov_b32_e32 v116, 0
	v_mov_b32_e32 v113, 0
	v_mov_b32_e32 v112, 0
	v_mov_b32_e32 v67, 0
	v_mov_b32_e32 v66, 0
	v_mov_b32_e32 v65, 0
	v_mov_b32_e32 v64, 0
	v_mov_b32_e32 v125, 0
	v_mov_b32_e32 v122, 0
	v_mov_b32_e32 v74, 0
	v_mov_b32_e32 v73, 0
	v_mov_b32_e32 v71, 0
	v_mov_b32_e32 v70, 0
	v_mov_b32_e32 v69, 0
	v_mov_b32_e32 v68, 0
	v_mov_b32_e32 v63, 0
	v_mov_b32_e32 v62, 0
	v_mov_b32_e32 v61, 0
	v_mov_b32_e32 v60, 0
	v_mov_b32_e32 v59, 0
	v_mov_b32_e32 v58, 0
	v_mov_b32_e32 v57, 0
	v_mov_b32_e32 v56, 0
	v_mov_b32_e32 v75, 0
	v_mov_b32_e32 v72, 0
	v_mov_b32_e32 v162, 0
	v_mov_b32_e32 v161, 0
	v_mov_b32_e32 v160, 0
	v_mov_b32_e32 v159, 0
	v_mov_b32_e32 v158, 0
	v_mov_b32_e32 v157, 0
	v_mov_b32_e32 v156, 0
	v_mov_b32_e32 v147, 0
	v_mov_b32_e32 v146, 0
	v_mov_b32_e32 v145, 0
	v_mov_b32_e32 v144, 0
	v_mov_b32_e32 v143, 0
	v_mov_b32_e32 v142, 0
	v_mov_b32_e32 v141, 0
	v_mov_b32_e32 v149, 0
	v_mov_b32_e32 v148, 0
	s_waitcnt lgkmcnt(0)
	ds_read_b32 v176, v115 offset:8192
	ds_read_b32 v178, v115 offset:8704
	ds_read_b32 v180, v115 offset:9216
	ds_read_b32 v182, v115 offset:9728
	s_waitcnt lgkmcnt(0)
	buffer_load_dwordx4 v[0:3], v[176:177], s[12:15], 0 idxen offen
	buffer_load_dwordx4 v[4:7], v[178:179], s[12:15], 0 idxen offen
	buffer_load_dwordx4 v[8:11], v[180:181], s[12:15], 0 idxen offen
	buffer_load_dwordx4 v[12:15], v[182:183], s[12:15], 0 idxen offen
	ds_read_b32 v176, v115 offset:8196
	s_waitcnt lgkmcnt(0)
	buffer_load_dwordx4 v[16:19], v[176:177], s[12:15], 0 idxen offen
	ds_read_b32 v178, v115 offset:8708
	s_waitcnt lgkmcnt(0)
	buffer_load_dwordx4 v[20:23], v[178:179], s[12:15], 0 idxen offen
	ds_read_b32 v180, v115 offset:9220
	s_waitcnt lgkmcnt(0)
	buffer_load_dwordx4 v[24:27], v[180:181], s[12:15], 0 idxen offen
	ds_read_b32 v184, v115 offset:0
	ds_read_b32 v182, v115 offset:9732
	ds_read_b32 v185, v115 offset:512
	s_mov_b32 s11, 0
.Lmy_lblk:
	ds_read_b32 v176, v115 offset:8200
	ds_read_b32 v186, v115 offset:1024
	s_waitcnt vmcnt(6) lgkmcnt(3)
	v_cvt_scalef32_pk_f16_fp4 v32, v0, 1.0
	v_cvt_scalef32_pk_f16_fp4 v33, v0, 1.0 op_sel:[1,0,0]
	v_cvt_scalef32_pk_f16_fp4 v34, v0, 1.0 op_sel:[0,1,0]
	v_cvt_scalef32_pk_f16_fp4 v35, v0, 1.0 op_sel:[1,1,0]
	v_cvt_scalef32_pk_f16_fp4 v36, v1, 1.0
	v_cvt_scalef32_pk_f16_fp4 v37, v1, 1.0 op_sel:[1,0,0]
	v_cvt_scalef32_pk_f16_fp4 v38, v1, 1.0 op_sel:[0,1,0]
	v_cvt_scalef32_pk_f16_fp4 v39, v1, 1.0 op_sel:[1,1,0]
	v_cvt_scalef32_pk_f16_fp4 v40, v2, 1.0
	v_cvt_scalef32_pk_f16_fp4 v41, v2, 1.0 op_sel:[1,0,0]
	v_cvt_scalef32_pk_f16_fp4 v42, v2, 1.0 op_sel:[0,1,0]
	v_cvt_scalef32_pk_f16_fp4 v43, v2, 1.0 op_sel:[1,1,0]
	v_cvt_scalef32_pk_f16_fp4 v44, v3, 1.0
	v_cvt_scalef32_pk_f16_fp4 v45, v3, 1.0 op_sel:[1,0,0]
	v_cvt_scalef32_pk_f16_fp4 v46, v3, 1.0 op_sel:[0,1,0]
	v_cvt_scalef32_pk_f16_fp4 v47, v3, 1.0 op_sel:[1,1,0]
	buffer_load_dwordx4 v[28:31], v[182:183], s[12:15], 0 idxen offen
	v_pk_fma_f16 v139, v32, v184, v139
	v_pk_fma_f16 v138, v33, v184, v138
	v_pk_fma_f16 v136, v34, v184, v136
	v_pk_fma_f16 v135, v35, v184, v135
	v_pk_fma_f16 v134, v36, v184, v134
	v_pk_fma_f16 v133, v37, v184, v133
	v_pk_fma_f16 v132, v38, v184, v132
	v_pk_fma_f16 v131, v39, v184, v131
	v_pk_fma_f16 v130, v40, v184, v130
	v_pk_fma_f16 v129, v41, v184, v129
	v_pk_fma_f16 v128, v42, v184, v128
	v_pk_fma_f16 v127, v43, v184, v127
	v_pk_fma_f16 v126, v44, v184, v126
	v_pk_fma_f16 v114, v45, v184, v114
	v_pk_fma_f16 v140, v46, v184, v140
	v_pk_fma_f16 v137, v47, v184, v137
	ds_read_b32 v178, v115 offset:8712
	ds_read_b32 v187, v115 offset:1536
	s_waitcnt vmcnt(6) lgkmcnt(3)
	v_cvt_scalef32_pk_f16_fp4 v32, v4, 1.0
	v_cvt_scalef32_pk_f16_fp4 v33, v4, 1.0 op_sel:[1,0,0]
	v_cvt_scalef32_pk_f16_fp4 v34, v4, 1.0 op_sel:[0,1,0]
	v_cvt_scalef32_pk_f16_fp4 v35, v4, 1.0 op_sel:[1,1,0]
	v_cvt_scalef32_pk_f16_fp4 v36, v5, 1.0
	v_cvt_scalef32_pk_f16_fp4 v37, v5, 1.0 op_sel:[1,0,0]
	v_cvt_scalef32_pk_f16_fp4 v38, v5, 1.0 op_sel:[0,1,0]
	v_cvt_scalef32_pk_f16_fp4 v39, v5, 1.0 op_sel:[1,1,0]
	v_cvt_scalef32_pk_f16_fp4 v40, v6, 1.0
	v_cvt_scalef32_pk_f16_fp4 v41, v6, 1.0 op_sel:[1,0,0]
	v_cvt_scalef32_pk_f16_fp4 v42, v6, 1.0 op_sel:[0,1,0]
	v_cvt_scalef32_pk_f16_fp4 v43, v6, 1.0 op_sel:[1,1,0]
	v_cvt_scalef32_pk_f16_fp4 v44, v7, 1.0
	v_cvt_scalef32_pk_f16_fp4 v45, v7, 1.0 op_sel:[1,0,0]
	v_cvt_scalef32_pk_f16_fp4 v46, v7, 1.0 op_sel:[0,1,0]
	v_cvt_scalef32_pk_f16_fp4 v47, v7, 1.0 op_sel:[1,1,0]
	buffer_load_dwordx4 v[0:3], v[176:177], s[12:15], 0 idxen offen
	v_pk_fma_f16 v124, v32, v185, v124
	v_pk_fma_f16 v123, v33, v185, v123
	v_pk_fma_f16 v121, v34, v185, v121
	v_pk_fma_f16 v120, v35, v185, v120
	v_pk_fma_f16 v119, v36, v185, v119
	v_pk_fma_f16 v118, v37, v185, v118
	v_pk_fma_f16 v117, v38, v185, v117
	v_pk_fma_f16 v116, v39, v185, v116
	v_pk_fma_f16 v113, v40, v185, v113
	v_pk_fma_f16 v112, v41, v185, v112
	v_pk_fma_f16 v67, v42, v185, v67
	v_pk_fma_f16 v66, v43, v185, v66
	v_pk_fma_f16 v65, v44, v185, v65
	v_pk_fma_f16 v64, v45, v185, v64
	v_pk_fma_f16 v125, v46, v185, v125
	v_pk_fma_f16 v122, v47, v185, v122
	ds_read_b32 v180, v115 offset:9224
	ds_read_b32 v184, v115 offset:4
	s_waitcnt vmcnt(6) lgkmcnt(3)
	v_cvt_scalef32_pk_f16_fp4 v32, v8, 1.0
	v_cvt_scalef32_pk_f16_fp4 v33, v8, 1.0 op_sel:[1,0,0]
	v_cvt_scalef32_pk_f16_fp4 v34, v8, 1.0 op_sel:[0,1,0]
	v_cvt_scalef32_pk_f16_fp4 v35, v8, 1.0 op_sel:[1,1,0]
	v_cvt_scalef32_pk_f16_fp4 v36, v9, 1.0
	v_cvt_scalef32_pk_f16_fp4 v37, v9, 1.0 op_sel:[1,0,0]
	v_cvt_scalef32_pk_f16_fp4 v38, v9, 1.0 op_sel:[0,1,0]
	v_cvt_scalef32_pk_f16_fp4 v39, v9, 1.0 op_sel:[1,1,0]
	v_cvt_scalef32_pk_f16_fp4 v40, v10, 1.0
	v_cvt_scalef32_pk_f16_fp4 v41, v10, 1.0 op_sel:[1,0,0]
	v_cvt_scalef32_pk_f16_fp4 v42, v10, 1.0 op_sel:[0,1,0]
	v_cvt_scalef32_pk_f16_fp4 v43, v10, 1.0 op_sel:[1,1,0]
	v_cvt_scalef32_pk_f16_fp4 v44, v11, 1.0
	v_cvt_scalef32_pk_f16_fp4 v45, v11, 1.0 op_sel:[1,0,0]
	v_cvt_scalef32_pk_f16_fp4 v46, v11, 1.0 op_sel:[0,1,0]
	v_cvt_scalef32_pk_f16_fp4 v47, v11, 1.0 op_sel:[1,1,0]
	buffer_load_dwordx4 v[4:7], v[178:179], s[12:15], 0 idxen offen
	v_pk_fma_f16 v74, v32, v186, v74
	v_pk_fma_f16 v73, v33, v186, v73
	v_pk_fma_f16 v71, v34, v186, v71
	v_pk_fma_f16 v70, v35, v186, v70
	v_pk_fma_f16 v69, v36, v186, v69
	v_pk_fma_f16 v68, v37, v186, v68
	v_pk_fma_f16 v63, v38, v186, v63
	v_pk_fma_f16 v62, v39, v186, v62
	v_pk_fma_f16 v61, v40, v186, v61
	v_pk_fma_f16 v60, v41, v186, v60
	v_pk_fma_f16 v59, v42, v186, v59
	v_pk_fma_f16 v58, v43, v186, v58
	v_pk_fma_f16 v57, v44, v186, v57
	v_pk_fma_f16 v56, v45, v186, v56
	v_pk_fma_f16 v75, v46, v186, v75
	v_pk_fma_f16 v72, v47, v186, v72
	ds_read_b32 v182, v115 offset:9736
	ds_read_b32 v185, v115 offset:516
	s_waitcnt vmcnt(6) lgkmcnt(3)
	v_cvt_scalef32_pk_f16_fp4 v32, v12, 1.0
	v_cvt_scalef32_pk_f16_fp4 v33, v12, 1.0 op_sel:[1,0,0]
	v_cvt_scalef32_pk_f16_fp4 v34, v12, 1.0 op_sel:[0,1,0]
	v_cvt_scalef32_pk_f16_fp4 v35, v12, 1.0 op_sel:[1,1,0]
	v_cvt_scalef32_pk_f16_fp4 v36, v13, 1.0
	v_cvt_scalef32_pk_f16_fp4 v37, v13, 1.0 op_sel:[1,0,0]
	v_cvt_scalef32_pk_f16_fp4 v38, v13, 1.0 op_sel:[0,1,0]
	v_cvt_scalef32_pk_f16_fp4 v39, v13, 1.0 op_sel:[1,1,0]
	v_cvt_scalef32_pk_f16_fp4 v40, v14, 1.0
	v_cvt_scalef32_pk_f16_fp4 v41, v14, 1.0 op_sel:[1,0,0]
	v_cvt_scalef32_pk_f16_fp4 v42, v14, 1.0 op_sel:[0,1,0]
	v_cvt_scalef32_pk_f16_fp4 v43, v14, 1.0 op_sel:[1,1,0]
	v_cvt_scalef32_pk_f16_fp4 v44, v15, 1.0
	v_cvt_scalef32_pk_f16_fp4 v45, v15, 1.0 op_sel:[1,0,0]
	v_cvt_scalef32_pk_f16_fp4 v46, v15, 1.0 op_sel:[0,1,0]
	v_cvt_scalef32_pk_f16_fp4 v47, v15, 1.0 op_sel:[1,1,0]
	buffer_load_dwordx4 v[8:11], v[180:181], s[12:15], 0 idxen offen
	v_pk_fma_f16 v162, v32, v187, v162
	v_pk_fma_f16 v161, v33, v187, v161
	v_pk_fma_f16 v160, v34, v187, v160
	v_pk_fma_f16 v159, v35, v187, v159
	v_pk_fma_f16 v158, v36, v187, v158
	v_pk_fma_f16 v157, v37, v187, v157
	v_pk_fma_f16 v156, v38, v187, v156
	v_pk_fma_f16 v147, v39, v187, v147
	v_pk_fma_f16 v146, v40, v187, v146
	v_pk_fma_f16 v145, v41, v187, v145
	v_pk_fma_f16 v144, v42, v187, v144
	v_pk_fma_f16 v143, v43, v187, v143
	v_pk_fma_f16 v142, v44, v187, v142
	v_pk_fma_f16 v141, v45, v187, v141
	v_pk_fma_f16 v149, v46, v187, v149
	v_pk_fma_f16 v148, v47, v187, v148
	ds_read_b32 v176, v115 offset:8204
	ds_read_b32 v186, v115 offset:1028
	s_waitcnt vmcnt(6) lgkmcnt(3)
	v_cvt_scalef32_pk_f16_fp4 v32, v16, 1.0
	v_cvt_scalef32_pk_f16_fp4 v33, v16, 1.0 op_sel:[1,0,0]
	v_cvt_scalef32_pk_f16_fp4 v34, v16, 1.0 op_sel:[0,1,0]
	v_cvt_scalef32_pk_f16_fp4 v35, v16, 1.0 op_sel:[1,1,0]
	v_cvt_scalef32_pk_f16_fp4 v36, v17, 1.0
	v_cvt_scalef32_pk_f16_fp4 v37, v17, 1.0 op_sel:[1,0,0]
	v_cvt_scalef32_pk_f16_fp4 v38, v17, 1.0 op_sel:[0,1,0]
	v_cvt_scalef32_pk_f16_fp4 v39, v17, 1.0 op_sel:[1,1,0]
	v_cvt_scalef32_pk_f16_fp4 v40, v18, 1.0
	v_cvt_scalef32_pk_f16_fp4 v41, v18, 1.0 op_sel:[1,0,0]
	v_cvt_scalef32_pk_f16_fp4 v42, v18, 1.0 op_sel:[0,1,0]
	v_cvt_scalef32_pk_f16_fp4 v43, v18, 1.0 op_sel:[1,1,0]
	v_cvt_scalef32_pk_f16_fp4 v44, v19, 1.0
	v_cvt_scalef32_pk_f16_fp4 v45, v19, 1.0 op_sel:[1,0,0]
	v_cvt_scalef32_pk_f16_fp4 v46, v19, 1.0 op_sel:[0,1,0]
	v_cvt_scalef32_pk_f16_fp4 v47, v19, 1.0 op_sel:[1,1,0]
	buffer_load_dwordx4 v[12:15], v[182:183], s[12:15], 0 idxen offen
	v_pk_fma_f16 v139, v32, v184, v139
	v_pk_fma_f16 v138, v33, v184, v138
	v_pk_fma_f16 v136, v34, v184, v136
	v_pk_fma_f16 v135, v35, v184, v135
	v_pk_fma_f16 v134, v36, v184, v134
	v_pk_fma_f16 v133, v37, v184, v133
	v_pk_fma_f16 v132, v38, v184, v132
	v_pk_fma_f16 v131, v39, v184, v131
	v_pk_fma_f16 v130, v40, v184, v130
	v_pk_fma_f16 v129, v41, v184, v129
	v_pk_fma_f16 v128, v42, v184, v128
	v_pk_fma_f16 v127, v43, v184, v127
	v_pk_fma_f16 v126, v44, v184, v126
	v_pk_fma_f16 v114, v45, v184, v114
	v_pk_fma_f16 v140, v46, v184, v140
	v_pk_fma_f16 v137, v47, v184, v137
	ds_read_b32 v178, v115 offset:8716
	ds_read_b32 v187, v115 offset:1540
	s_waitcnt vmcnt(6) lgkmcnt(3)
	v_cvt_scalef32_pk_f16_fp4 v32, v20, 1.0
	v_cvt_scalef32_pk_f16_fp4 v33, v20, 1.0 op_sel:[1,0,0]
	v_cvt_scalef32_pk_f16_fp4 v34, v20, 1.0 op_sel:[0,1,0]
	v_cvt_scalef32_pk_f16_fp4 v35, v20, 1.0 op_sel:[1,1,0]
	v_cvt_scalef32_pk_f16_fp4 v36, v21, 1.0
	v_cvt_scalef32_pk_f16_fp4 v37, v21, 1.0 op_sel:[1,0,0]
	v_cvt_scalef32_pk_f16_fp4 v38, v21, 1.0 op_sel:[0,1,0]
	v_cvt_scalef32_pk_f16_fp4 v39, v21, 1.0 op_sel:[1,1,0]
	v_cvt_scalef32_pk_f16_fp4 v40, v22, 1.0
	v_cvt_scalef32_pk_f16_fp4 v41, v22, 1.0 op_sel:[1,0,0]
	v_cvt_scalef32_pk_f16_fp4 v42, v22, 1.0 op_sel:[0,1,0]
	v_cvt_scalef32_pk_f16_fp4 v43, v22, 1.0 op_sel:[1,1,0]
	v_cvt_scalef32_pk_f16_fp4 v44, v23, 1.0
	v_cvt_scalef32_pk_f16_fp4 v45, v23, 1.0 op_sel:[1,0,0]
	v_cvt_scalef32_pk_f16_fp4 v46, v23, 1.0 op_sel:[0,1,0]
	v_cvt_scalef32_pk_f16_fp4 v47, v23, 1.0 op_sel:[1,1,0]
	buffer_load_dwordx4 v[16:19], v[176:177], s[12:15], 0 idxen offen
	v_pk_fma_f16 v124, v32, v185, v124
	v_pk_fma_f16 v123, v33, v185, v123
	v_pk_fma_f16 v121, v34, v185, v121
	v_pk_fma_f16 v120, v35, v185, v120
	v_pk_fma_f16 v119, v36, v185, v119
	v_pk_fma_f16 v118, v37, v185, v118
	v_pk_fma_f16 v117, v38, v185, v117
	v_pk_fma_f16 v116, v39, v185, v116
	v_pk_fma_f16 v113, v40, v185, v113
	v_pk_fma_f16 v112, v41, v185, v112
	v_pk_fma_f16 v67, v42, v185, v67
	v_pk_fma_f16 v66, v43, v185, v66
	v_pk_fma_f16 v65, v44, v185, v65
	v_pk_fma_f16 v64, v45, v185, v64
	v_pk_fma_f16 v125, v46, v185, v125
	v_pk_fma_f16 v122, v47, v185, v122
	ds_read_b32 v180, v115 offset:9228
	ds_read_b32 v184, v115 offset:8
	s_waitcnt vmcnt(6) lgkmcnt(3)
	v_cvt_scalef32_pk_f16_fp4 v32, v24, 1.0
	v_cvt_scalef32_pk_f16_fp4 v33, v24, 1.0 op_sel:[1,0,0]
	v_cvt_scalef32_pk_f16_fp4 v34, v24, 1.0 op_sel:[0,1,0]
	v_cvt_scalef32_pk_f16_fp4 v35, v24, 1.0 op_sel:[1,1,0]
	v_cvt_scalef32_pk_f16_fp4 v36, v25, 1.0
	v_cvt_scalef32_pk_f16_fp4 v37, v25, 1.0 op_sel:[1,0,0]
	v_cvt_scalef32_pk_f16_fp4 v38, v25, 1.0 op_sel:[0,1,0]
	v_cvt_scalef32_pk_f16_fp4 v39, v25, 1.0 op_sel:[1,1,0]
	v_cvt_scalef32_pk_f16_fp4 v40, v26, 1.0
	v_cvt_scalef32_pk_f16_fp4 v41, v26, 1.0 op_sel:[1,0,0]
	v_cvt_scalef32_pk_f16_fp4 v42, v26, 1.0 op_sel:[0,1,0]
	v_cvt_scalef32_pk_f16_fp4 v43, v26, 1.0 op_sel:[1,1,0]
	v_cvt_scalef32_pk_f16_fp4 v44, v27, 1.0
	v_cvt_scalef32_pk_f16_fp4 v45, v27, 1.0 op_sel:[1,0,0]
	v_cvt_scalef32_pk_f16_fp4 v46, v27, 1.0 op_sel:[0,1,0]
	v_cvt_scalef32_pk_f16_fp4 v47, v27, 1.0 op_sel:[1,1,0]
	buffer_load_dwordx4 v[20:23], v[178:179], s[12:15], 0 idxen offen
	v_pk_fma_f16 v74, v32, v186, v74
	v_pk_fma_f16 v73, v33, v186, v73
	v_pk_fma_f16 v71, v34, v186, v71
	v_pk_fma_f16 v70, v35, v186, v70
	v_pk_fma_f16 v69, v36, v186, v69
	v_pk_fma_f16 v68, v37, v186, v68
	v_pk_fma_f16 v63, v38, v186, v63
	v_pk_fma_f16 v62, v39, v186, v62
	v_pk_fma_f16 v61, v40, v186, v61
	v_pk_fma_f16 v60, v41, v186, v60
	v_pk_fma_f16 v59, v42, v186, v59
	v_pk_fma_f16 v58, v43, v186, v58
	v_pk_fma_f16 v57, v44, v186, v57
	v_pk_fma_f16 v56, v45, v186, v56
	v_pk_fma_f16 v75, v46, v186, v75
	v_pk_fma_f16 v72, v47, v186, v72
	ds_read_b32 v182, v115 offset:9740
	ds_read_b32 v185, v115 offset:520
	s_waitcnt vmcnt(6) lgkmcnt(3)
	v_cvt_scalef32_pk_f16_fp4 v32, v28, 1.0
	v_cvt_scalef32_pk_f16_fp4 v33, v28, 1.0 op_sel:[1,0,0]
	v_cvt_scalef32_pk_f16_fp4 v34, v28, 1.0 op_sel:[0,1,0]
	v_cvt_scalef32_pk_f16_fp4 v35, v28, 1.0 op_sel:[1,1,0]
	v_cvt_scalef32_pk_f16_fp4 v36, v29, 1.0
	v_cvt_scalef32_pk_f16_fp4 v37, v29, 1.0 op_sel:[1,0,0]
	v_cvt_scalef32_pk_f16_fp4 v38, v29, 1.0 op_sel:[0,1,0]
	v_cvt_scalef32_pk_f16_fp4 v39, v29, 1.0 op_sel:[1,1,0]
	v_cvt_scalef32_pk_f16_fp4 v40, v30, 1.0
	v_cvt_scalef32_pk_f16_fp4 v41, v30, 1.0 op_sel:[1,0,0]
	v_cvt_scalef32_pk_f16_fp4 v42, v30, 1.0 op_sel:[0,1,0]
	v_cvt_scalef32_pk_f16_fp4 v43, v30, 1.0 op_sel:[1,1,0]
	v_cvt_scalef32_pk_f16_fp4 v44, v31, 1.0
	v_cvt_scalef32_pk_f16_fp4 v45, v31, 1.0 op_sel:[1,0,0]
	v_cvt_scalef32_pk_f16_fp4 v46, v31, 1.0 op_sel:[0,1,0]
	v_cvt_scalef32_pk_f16_fp4 v47, v31, 1.0 op_sel:[1,1,0]
	buffer_load_dwordx4 v[24:27], v[180:181], s[12:15], 0 idxen offen
	v_pk_fma_f16 v162, v32, v187, v162
	v_pk_fma_f16 v161, v33, v187, v161
	v_pk_fma_f16 v160, v34, v187, v160
	v_pk_fma_f16 v159, v35, v187, v159
	v_pk_fma_f16 v158, v36, v187, v158
	v_pk_fma_f16 v157, v37, v187, v157
	v_pk_fma_f16 v156, v38, v187, v156
	v_pk_fma_f16 v147, v39, v187, v147
	v_pk_fma_f16 v146, v40, v187, v146
	v_pk_fma_f16 v145, v41, v187, v145
	v_pk_fma_f16 v144, v42, v187, v144
	v_pk_fma_f16 v143, v43, v187, v143
	v_pk_fma_f16 v142, v44, v187, v142
	v_pk_fma_f16 v141, v45, v187, v141
	v_pk_fma_f16 v149, v46, v187, v149
	v_pk_fma_f16 v148, v47, v187, v148
	ds_read_b32 v176, v115 offset:8208
	ds_read_b32 v186, v115 offset:1032
	s_waitcnt vmcnt(6) lgkmcnt(3)
	v_cvt_scalef32_pk_f16_fp4 v32, v0, 1.0
	v_cvt_scalef32_pk_f16_fp4 v33, v0, 1.0 op_sel:[1,0,0]
	v_cvt_scalef32_pk_f16_fp4 v34, v0, 1.0 op_sel:[0,1,0]
	v_cvt_scalef32_pk_f16_fp4 v35, v0, 1.0 op_sel:[1,1,0]
	v_cvt_scalef32_pk_f16_fp4 v36, v1, 1.0
	v_cvt_scalef32_pk_f16_fp4 v37, v1, 1.0 op_sel:[1,0,0]
	v_cvt_scalef32_pk_f16_fp4 v38, v1, 1.0 op_sel:[0,1,0]
	v_cvt_scalef32_pk_f16_fp4 v39, v1, 1.0 op_sel:[1,1,0]
	v_cvt_scalef32_pk_f16_fp4 v40, v2, 1.0
	v_cvt_scalef32_pk_f16_fp4 v41, v2, 1.0 op_sel:[1,0,0]
	v_cvt_scalef32_pk_f16_fp4 v42, v2, 1.0 op_sel:[0,1,0]
	v_cvt_scalef32_pk_f16_fp4 v43, v2, 1.0 op_sel:[1,1,0]
	v_cvt_scalef32_pk_f16_fp4 v44, v3, 1.0
	v_cvt_scalef32_pk_f16_fp4 v45, v3, 1.0 op_sel:[1,0,0]
	v_cvt_scalef32_pk_f16_fp4 v46, v3, 1.0 op_sel:[0,1,0]
	v_cvt_scalef32_pk_f16_fp4 v47, v3, 1.0 op_sel:[1,1,0]
	buffer_load_dwordx4 v[28:31], v[182:183], s[12:15], 0 idxen offen
	v_pk_fma_f16 v139, v32, v184, v139
	v_pk_fma_f16 v138, v33, v184, v138
	v_pk_fma_f16 v136, v34, v184, v136
	v_pk_fma_f16 v135, v35, v184, v135
	v_pk_fma_f16 v134, v36, v184, v134
	v_pk_fma_f16 v133, v37, v184, v133
	v_pk_fma_f16 v132, v38, v184, v132
	v_pk_fma_f16 v131, v39, v184, v131
	v_pk_fma_f16 v130, v40, v184, v130
	v_pk_fma_f16 v129, v41, v184, v129
	v_pk_fma_f16 v128, v42, v184, v128
	v_pk_fma_f16 v127, v43, v184, v127
	v_pk_fma_f16 v126, v44, v184, v126
	v_pk_fma_f16 v114, v45, v184, v114
	v_pk_fma_f16 v140, v46, v184, v140
	v_pk_fma_f16 v137, v47, v184, v137
	ds_read_b32 v178, v115 offset:8720
	ds_read_b32 v187, v115 offset:1544
	s_waitcnt vmcnt(6) lgkmcnt(3)
	v_cvt_scalef32_pk_f16_fp4 v32, v4, 1.0
	v_cvt_scalef32_pk_f16_fp4 v33, v4, 1.0 op_sel:[1,0,0]
	v_cvt_scalef32_pk_f16_fp4 v34, v4, 1.0 op_sel:[0,1,0]
	v_cvt_scalef32_pk_f16_fp4 v35, v4, 1.0 op_sel:[1,1,0]
	v_cvt_scalef32_pk_f16_fp4 v36, v5, 1.0
	v_cvt_scalef32_pk_f16_fp4 v37, v5, 1.0 op_sel:[1,0,0]
	v_cvt_scalef32_pk_f16_fp4 v38, v5, 1.0 op_sel:[0,1,0]
	v_cvt_scalef32_pk_f16_fp4 v39, v5, 1.0 op_sel:[1,1,0]
	v_cvt_scalef32_pk_f16_fp4 v40, v6, 1.0
	v_cvt_scalef32_pk_f16_fp4 v41, v6, 1.0 op_sel:[1,0,0]
	v_cvt_scalef32_pk_f16_fp4 v42, v6, 1.0 op_sel:[0,1,0]
	v_cvt_scalef32_pk_f16_fp4 v43, v6, 1.0 op_sel:[1,1,0]
	v_cvt_scalef32_pk_f16_fp4 v44, v7, 1.0
	v_cvt_scalef32_pk_f16_fp4 v45, v7, 1.0 op_sel:[1,0,0]
	v_cvt_scalef32_pk_f16_fp4 v46, v7, 1.0 op_sel:[0,1,0]
	v_cvt_scalef32_pk_f16_fp4 v47, v7, 1.0 op_sel:[1,1,0]
	buffer_load_dwordx4 v[0:3], v[176:177], s[12:15], 0 idxen offen
	v_pk_fma_f16 v124, v32, v185, v124
	v_pk_fma_f16 v123, v33, v185, v123
	v_pk_fma_f16 v121, v34, v185, v121
	v_pk_fma_f16 v120, v35, v185, v120
	v_pk_fma_f16 v119, v36, v185, v119
	v_pk_fma_f16 v118, v37, v185, v118
	v_pk_fma_f16 v117, v38, v185, v117
	v_pk_fma_f16 v116, v39, v185, v116
	v_pk_fma_f16 v113, v40, v185, v113
	v_pk_fma_f16 v112, v41, v185, v112
	v_pk_fma_f16 v67, v42, v185, v67
	v_pk_fma_f16 v66, v43, v185, v66
	v_pk_fma_f16 v65, v44, v185, v65
	v_pk_fma_f16 v64, v45, v185, v64
	v_pk_fma_f16 v125, v46, v185, v125
	v_pk_fma_f16 v122, v47, v185, v122
	ds_read_b32 v180, v115 offset:9232
	ds_read_b32 v184, v115 offset:12
	s_waitcnt vmcnt(6) lgkmcnt(3)
	v_cvt_scalef32_pk_f16_fp4 v32, v8, 1.0
	v_cvt_scalef32_pk_f16_fp4 v33, v8, 1.0 op_sel:[1,0,0]
	v_cvt_scalef32_pk_f16_fp4 v34, v8, 1.0 op_sel:[0,1,0]
	v_cvt_scalef32_pk_f16_fp4 v35, v8, 1.0 op_sel:[1,1,0]
	v_cvt_scalef32_pk_f16_fp4 v36, v9, 1.0
	v_cvt_scalef32_pk_f16_fp4 v37, v9, 1.0 op_sel:[1,0,0]
	v_cvt_scalef32_pk_f16_fp4 v38, v9, 1.0 op_sel:[0,1,0]
	v_cvt_scalef32_pk_f16_fp4 v39, v9, 1.0 op_sel:[1,1,0]
	v_cvt_scalef32_pk_f16_fp4 v40, v10, 1.0
	v_cvt_scalef32_pk_f16_fp4 v41, v10, 1.0 op_sel:[1,0,0]
	v_cvt_scalef32_pk_f16_fp4 v42, v10, 1.0 op_sel:[0,1,0]
	v_cvt_scalef32_pk_f16_fp4 v43, v10, 1.0 op_sel:[1,1,0]
	v_cvt_scalef32_pk_f16_fp4 v44, v11, 1.0
	v_cvt_scalef32_pk_f16_fp4 v45, v11, 1.0 op_sel:[1,0,0]
	v_cvt_scalef32_pk_f16_fp4 v46, v11, 1.0 op_sel:[0,1,0]
	v_cvt_scalef32_pk_f16_fp4 v47, v11, 1.0 op_sel:[1,1,0]
	buffer_load_dwordx4 v[4:7], v[178:179], s[12:15], 0 idxen offen
	v_pk_fma_f16 v74, v32, v186, v74
	v_pk_fma_f16 v73, v33, v186, v73
	v_pk_fma_f16 v71, v34, v186, v71
	v_pk_fma_f16 v70, v35, v186, v70
	v_pk_fma_f16 v69, v36, v186, v69
	v_pk_fma_f16 v68, v37, v186, v68
	v_pk_fma_f16 v63, v38, v186, v63
	v_pk_fma_f16 v62, v39, v186, v62
	v_pk_fma_f16 v61, v40, v186, v61
	v_pk_fma_f16 v60, v41, v186, v60
	v_pk_fma_f16 v59, v42, v186, v59
	v_pk_fma_f16 v58, v43, v186, v58
	v_pk_fma_f16 v57, v44, v186, v57
	v_pk_fma_f16 v56, v45, v186, v56
	v_pk_fma_f16 v75, v46, v186, v75
	v_pk_fma_f16 v72, v47, v186, v72
	ds_read_b32 v182, v115 offset:9744
	ds_read_b32 v185, v115 offset:524
	s_waitcnt vmcnt(6) lgkmcnt(3)
	v_cvt_scalef32_pk_f16_fp4 v32, v12, 1.0
	v_cvt_scalef32_pk_f16_fp4 v33, v12, 1.0 op_sel:[1,0,0]
	v_cvt_scalef32_pk_f16_fp4 v34, v12, 1.0 op_sel:[0,1,0]
	v_cvt_scalef32_pk_f16_fp4 v35, v12, 1.0 op_sel:[1,1,0]
	v_cvt_scalef32_pk_f16_fp4 v36, v13, 1.0
	v_cvt_scalef32_pk_f16_fp4 v37, v13, 1.0 op_sel:[1,0,0]
	v_cvt_scalef32_pk_f16_fp4 v38, v13, 1.0 op_sel:[0,1,0]
	v_cvt_scalef32_pk_f16_fp4 v39, v13, 1.0 op_sel:[1,1,0]
	v_cvt_scalef32_pk_f16_fp4 v40, v14, 1.0
	v_cvt_scalef32_pk_f16_fp4 v41, v14, 1.0 op_sel:[1,0,0]
	v_cvt_scalef32_pk_f16_fp4 v42, v14, 1.0 op_sel:[0,1,0]
	v_cvt_scalef32_pk_f16_fp4 v43, v14, 1.0 op_sel:[1,1,0]
	v_cvt_scalef32_pk_f16_fp4 v44, v15, 1.0
	v_cvt_scalef32_pk_f16_fp4 v45, v15, 1.0 op_sel:[1,0,0]
	v_cvt_scalef32_pk_f16_fp4 v46, v15, 1.0 op_sel:[0,1,0]
	v_cvt_scalef32_pk_f16_fp4 v47, v15, 1.0 op_sel:[1,1,0]
	buffer_load_dwordx4 v[8:11], v[180:181], s[12:15], 0 idxen offen
	v_pk_fma_f16 v162, v32, v187, v162
	v_pk_fma_f16 v161, v33, v187, v161
	v_pk_fma_f16 v160, v34, v187, v160
	v_pk_fma_f16 v159, v35, v187, v159
	v_pk_fma_f16 v158, v36, v187, v158
	v_pk_fma_f16 v157, v37, v187, v157
	v_pk_fma_f16 v156, v38, v187, v156
	v_pk_fma_f16 v147, v39, v187, v147
	v_pk_fma_f16 v146, v40, v187, v146
	v_pk_fma_f16 v145, v41, v187, v145
	v_pk_fma_f16 v144, v42, v187, v144
	v_pk_fma_f16 v143, v43, v187, v143
	v_pk_fma_f16 v142, v44, v187, v142
	v_pk_fma_f16 v141, v45, v187, v141
	v_pk_fma_f16 v149, v46, v187, v149
	v_pk_fma_f16 v148, v47, v187, v148
	ds_read_b32 v176, v115 offset:8212
	ds_read_b32 v186, v115 offset:1036
	s_waitcnt vmcnt(6) lgkmcnt(3)
	v_cvt_scalef32_pk_f16_fp4 v32, v16, 1.0
	v_cvt_scalef32_pk_f16_fp4 v33, v16, 1.0 op_sel:[1,0,0]
	v_cvt_scalef32_pk_f16_fp4 v34, v16, 1.0 op_sel:[0,1,0]
	v_cvt_scalef32_pk_f16_fp4 v35, v16, 1.0 op_sel:[1,1,0]
	v_cvt_scalef32_pk_f16_fp4 v36, v17, 1.0
	v_cvt_scalef32_pk_f16_fp4 v37, v17, 1.0 op_sel:[1,0,0]
	v_cvt_scalef32_pk_f16_fp4 v38, v17, 1.0 op_sel:[0,1,0]
	v_cvt_scalef32_pk_f16_fp4 v39, v17, 1.0 op_sel:[1,1,0]
	v_cvt_scalef32_pk_f16_fp4 v40, v18, 1.0
	v_cvt_scalef32_pk_f16_fp4 v41, v18, 1.0 op_sel:[1,0,0]
	v_cvt_scalef32_pk_f16_fp4 v42, v18, 1.0 op_sel:[0,1,0]
	v_cvt_scalef32_pk_f16_fp4 v43, v18, 1.0 op_sel:[1,1,0]
	v_cvt_scalef32_pk_f16_fp4 v44, v19, 1.0
	v_cvt_scalef32_pk_f16_fp4 v45, v19, 1.0 op_sel:[1,0,0]
	v_cvt_scalef32_pk_f16_fp4 v46, v19, 1.0 op_sel:[0,1,0]
	v_cvt_scalef32_pk_f16_fp4 v47, v19, 1.0 op_sel:[1,1,0]
	buffer_load_dwordx4 v[12:15], v[182:183], s[12:15], 0 idxen offen
	v_pk_fma_f16 v139, v32, v184, v139
	v_pk_fma_f16 v138, v33, v184, v138
	v_pk_fma_f16 v136, v34, v184, v136
	v_pk_fma_f16 v135, v35, v184, v135
	v_pk_fma_f16 v134, v36, v184, v134
	v_pk_fma_f16 v133, v37, v184, v133
	v_pk_fma_f16 v132, v38, v184, v132
	v_pk_fma_f16 v131, v39, v184, v131
	v_pk_fma_f16 v130, v40, v184, v130
	v_pk_fma_f16 v129, v41, v184, v129
	v_pk_fma_f16 v128, v42, v184, v128
	v_pk_fma_f16 v127, v43, v184, v127
	v_pk_fma_f16 v126, v44, v184, v126
	v_pk_fma_f16 v114, v45, v184, v114
	v_pk_fma_f16 v140, v46, v184, v140
	v_pk_fma_f16 v137, v47, v184, v137
	ds_read_b32 v178, v115 offset:8724
	ds_read_b32 v187, v115 offset:1548
	s_waitcnt vmcnt(6) lgkmcnt(3)
	v_cvt_scalef32_pk_f16_fp4 v32, v20, 1.0
	v_cvt_scalef32_pk_f16_fp4 v33, v20, 1.0 op_sel:[1,0,0]
	v_cvt_scalef32_pk_f16_fp4 v34, v20, 1.0 op_sel:[0,1,0]
	v_cvt_scalef32_pk_f16_fp4 v35, v20, 1.0 op_sel:[1,1,0]
	v_cvt_scalef32_pk_f16_fp4 v36, v21, 1.0
	v_cvt_scalef32_pk_f16_fp4 v37, v21, 1.0 op_sel:[1,0,0]
	v_cvt_scalef32_pk_f16_fp4 v38, v21, 1.0 op_sel:[0,1,0]
	v_cvt_scalef32_pk_f16_fp4 v39, v21, 1.0 op_sel:[1,1,0]
	v_cvt_scalef32_pk_f16_fp4 v40, v22, 1.0
	v_cvt_scalef32_pk_f16_fp4 v41, v22, 1.0 op_sel:[1,0,0]
	v_cvt_scalef32_pk_f16_fp4 v42, v22, 1.0 op_sel:[0,1,0]
	v_cvt_scalef32_pk_f16_fp4 v43, v22, 1.0 op_sel:[1,1,0]
	v_cvt_scalef32_pk_f16_fp4 v44, v23, 1.0
	v_cvt_scalef32_pk_f16_fp4 v45, v23, 1.0 op_sel:[1,0,0]
	v_cvt_scalef32_pk_f16_fp4 v46, v23, 1.0 op_sel:[0,1,0]
	v_cvt_scalef32_pk_f16_fp4 v47, v23, 1.0 op_sel:[1,1,0]
	buffer_load_dwordx4 v[16:19], v[176:177], s[12:15], 0 idxen offen
	v_pk_fma_f16 v124, v32, v185, v124
	v_pk_fma_f16 v123, v33, v185, v123
	v_pk_fma_f16 v121, v34, v185, v121
	v_pk_fma_f16 v120, v35, v185, v120
	v_pk_fma_f16 v119, v36, v185, v119
	v_pk_fma_f16 v118, v37, v185, v118
	v_pk_fma_f16 v117, v38, v185, v117
	v_pk_fma_f16 v116, v39, v185, v116
	v_pk_fma_f16 v113, v40, v185, v113
	v_pk_fma_f16 v112, v41, v185, v112
	v_pk_fma_f16 v67, v42, v185, v67
	v_pk_fma_f16 v66, v43, v185, v66
	v_pk_fma_f16 v65, v44, v185, v65
	v_pk_fma_f16 v64, v45, v185, v64
	v_pk_fma_f16 v125, v46, v185, v125
	v_pk_fma_f16 v122, v47, v185, v122
	ds_read_b32 v180, v115 offset:9236
	ds_read_b32 v184, v115 offset:16
	s_waitcnt vmcnt(6) lgkmcnt(3)
	v_cvt_scalef32_pk_f16_fp4 v32, v24, 1.0
	v_cvt_scalef32_pk_f16_fp4 v33, v24, 1.0 op_sel:[1,0,0]
	v_cvt_scalef32_pk_f16_fp4 v34, v24, 1.0 op_sel:[0,1,0]
	v_cvt_scalef32_pk_f16_fp4 v35, v24, 1.0 op_sel:[1,1,0]
	v_cvt_scalef32_pk_f16_fp4 v36, v25, 1.0
	v_cvt_scalef32_pk_f16_fp4 v37, v25, 1.0 op_sel:[1,0,0]
	v_cvt_scalef32_pk_f16_fp4 v38, v25, 1.0 op_sel:[0,1,0]
	v_cvt_scalef32_pk_f16_fp4 v39, v25, 1.0 op_sel:[1,1,0]
	v_cvt_scalef32_pk_f16_fp4 v40, v26, 1.0
	v_cvt_scalef32_pk_f16_fp4 v41, v26, 1.0 op_sel:[1,0,0]
	v_cvt_scalef32_pk_f16_fp4 v42, v26, 1.0 op_sel:[0,1,0]
	v_cvt_scalef32_pk_f16_fp4 v43, v26, 1.0 op_sel:[1,1,0]
	v_cvt_scalef32_pk_f16_fp4 v44, v27, 1.0
	v_cvt_scalef32_pk_f16_fp4 v45, v27, 1.0 op_sel:[1,0,0]
	v_cvt_scalef32_pk_f16_fp4 v46, v27, 1.0 op_sel:[0,1,0]
	v_cvt_scalef32_pk_f16_fp4 v47, v27, 1.0 op_sel:[1,1,0]
	buffer_load_dwordx4 v[20:23], v[178:179], s[12:15], 0 idxen offen
	v_pk_fma_f16 v74, v32, v186, v74
	v_pk_fma_f16 v73, v33, v186, v73
	v_pk_fma_f16 v71, v34, v186, v71
	v_pk_fma_f16 v70, v35, v186, v70
	v_pk_fma_f16 v69, v36, v186, v69
	v_pk_fma_f16 v68, v37, v186, v68
	v_pk_fma_f16 v63, v38, v186, v63
	v_pk_fma_f16 v62, v39, v186, v62
	v_pk_fma_f16 v61, v40, v186, v61
	v_pk_fma_f16 v60, v41, v186, v60
	v_pk_fma_f16 v59, v42, v186, v59
	v_pk_fma_f16 v58, v43, v186, v58
	v_pk_fma_f16 v57, v44, v186, v57
	v_pk_fma_f16 v56, v45, v186, v56
	v_pk_fma_f16 v75, v46, v186, v75
	v_pk_fma_f16 v72, v47, v186, v72
	ds_read_b32 v182, v115 offset:9748
	ds_read_b32 v185, v115 offset:528
	s_waitcnt vmcnt(6) lgkmcnt(3)
	v_cvt_scalef32_pk_f16_fp4 v32, v28, 1.0
	v_cvt_scalef32_pk_f16_fp4 v33, v28, 1.0 op_sel:[1,0,0]
	v_cvt_scalef32_pk_f16_fp4 v34, v28, 1.0 op_sel:[0,1,0]
	v_cvt_scalef32_pk_f16_fp4 v35, v28, 1.0 op_sel:[1,1,0]
	v_cvt_scalef32_pk_f16_fp4 v36, v29, 1.0
	v_cvt_scalef32_pk_f16_fp4 v37, v29, 1.0 op_sel:[1,0,0]
	v_cvt_scalef32_pk_f16_fp4 v38, v29, 1.0 op_sel:[0,1,0]
	v_cvt_scalef32_pk_f16_fp4 v39, v29, 1.0 op_sel:[1,1,0]
	v_cvt_scalef32_pk_f16_fp4 v40, v30, 1.0
	v_cvt_scalef32_pk_f16_fp4 v41, v30, 1.0 op_sel:[1,0,0]
	v_cvt_scalef32_pk_f16_fp4 v42, v30, 1.0 op_sel:[0,1,0]
	v_cvt_scalef32_pk_f16_fp4 v43, v30, 1.0 op_sel:[1,1,0]
	v_cvt_scalef32_pk_f16_fp4 v44, v31, 1.0
	v_cvt_scalef32_pk_f16_fp4 v45, v31, 1.0 op_sel:[1,0,0]
	v_cvt_scalef32_pk_f16_fp4 v46, v31, 1.0 op_sel:[0,1,0]
	v_cvt_scalef32_pk_f16_fp4 v47, v31, 1.0 op_sel:[1,1,0]
	buffer_load_dwordx4 v[24:27], v[180:181], s[12:15], 0 idxen offen
	v_pk_fma_f16 v162, v32, v187, v162
	v_pk_fma_f16 v161, v33, v187, v161
	v_pk_fma_f16 v160, v34, v187, v160
	v_pk_fma_f16 v159, v35, v187, v159
	v_pk_fma_f16 v158, v36, v187, v158
	v_pk_fma_f16 v157, v37, v187, v157
	v_pk_fma_f16 v156, v38, v187, v156
	v_pk_fma_f16 v147, v39, v187, v147
	v_pk_fma_f16 v146, v40, v187, v146
	v_pk_fma_f16 v145, v41, v187, v145
	v_pk_fma_f16 v144, v42, v187, v144
	v_pk_fma_f16 v143, v43, v187, v143
	v_pk_fma_f16 v142, v44, v187, v142
	v_pk_fma_f16 v141, v45, v187, v141
	v_pk_fma_f16 v149, v46, v187, v149
	v_pk_fma_f16 v148, v47, v187, v148
	ds_read_b32 v176, v115 offset:8216
	ds_read_b32 v186, v115 offset:1040
	s_waitcnt vmcnt(6) lgkmcnt(3)
	v_cvt_scalef32_pk_f16_fp4 v32, v0, 1.0
	v_cvt_scalef32_pk_f16_fp4 v33, v0, 1.0 op_sel:[1,0,0]
	v_cvt_scalef32_pk_f16_fp4 v34, v0, 1.0 op_sel:[0,1,0]
	v_cvt_scalef32_pk_f16_fp4 v35, v0, 1.0 op_sel:[1,1,0]
	v_cvt_scalef32_pk_f16_fp4 v36, v1, 1.0
	v_cvt_scalef32_pk_f16_fp4 v37, v1, 1.0 op_sel:[1,0,0]
	v_cvt_scalef32_pk_f16_fp4 v38, v1, 1.0 op_sel:[0,1,0]
	v_cvt_scalef32_pk_f16_fp4 v39, v1, 1.0 op_sel:[1,1,0]
	v_cvt_scalef32_pk_f16_fp4 v40, v2, 1.0
	v_cvt_scalef32_pk_f16_fp4 v41, v2, 1.0 op_sel:[1,0,0]
	v_cvt_scalef32_pk_f16_fp4 v42, v2, 1.0 op_sel:[0,1,0]
	v_cvt_scalef32_pk_f16_fp4 v43, v2, 1.0 op_sel:[1,1,0]
	v_cvt_scalef32_pk_f16_fp4 v44, v3, 1.0
	v_cvt_scalef32_pk_f16_fp4 v45, v3, 1.0 op_sel:[1,0,0]
	v_cvt_scalef32_pk_f16_fp4 v46, v3, 1.0 op_sel:[0,1,0]
	v_cvt_scalef32_pk_f16_fp4 v47, v3, 1.0 op_sel:[1,1,0]
	buffer_load_dwordx4 v[28:31], v[182:183], s[12:15], 0 idxen offen
	v_pk_fma_f16 v139, v32, v184, v139
	v_pk_fma_f16 v138, v33, v184, v138
	v_pk_fma_f16 v136, v34, v184, v136
	v_pk_fma_f16 v135, v35, v184, v135
	v_pk_fma_f16 v134, v36, v184, v134
	v_pk_fma_f16 v133, v37, v184, v133
	v_pk_fma_f16 v132, v38, v184, v132
	v_pk_fma_f16 v131, v39, v184, v131
	v_pk_fma_f16 v130, v40, v184, v130
	v_pk_fma_f16 v129, v41, v184, v129
	v_pk_fma_f16 v128, v42, v184, v128
	v_pk_fma_f16 v127, v43, v184, v127
	v_pk_fma_f16 v126, v44, v184, v126
	v_pk_fma_f16 v114, v45, v184, v114
	v_pk_fma_f16 v140, v46, v184, v140
	v_pk_fma_f16 v137, v47, v184, v137
	ds_read_b32 v178, v115 offset:8728
	ds_read_b32 v187, v115 offset:1552
	s_waitcnt vmcnt(6) lgkmcnt(3)
	v_cvt_scalef32_pk_f16_fp4 v32, v4, 1.0
	v_cvt_scalef32_pk_f16_fp4 v33, v4, 1.0 op_sel:[1,0,0]
	v_cvt_scalef32_pk_f16_fp4 v34, v4, 1.0 op_sel:[0,1,0]
	v_cvt_scalef32_pk_f16_fp4 v35, v4, 1.0 op_sel:[1,1,0]
	v_cvt_scalef32_pk_f16_fp4 v36, v5, 1.0
	v_cvt_scalef32_pk_f16_fp4 v37, v5, 1.0 op_sel:[1,0,0]
	v_cvt_scalef32_pk_f16_fp4 v38, v5, 1.0 op_sel:[0,1,0]
	v_cvt_scalef32_pk_f16_fp4 v39, v5, 1.0 op_sel:[1,1,0]
	v_cvt_scalef32_pk_f16_fp4 v40, v6, 1.0
	v_cvt_scalef32_pk_f16_fp4 v41, v6, 1.0 op_sel:[1,0,0]
	v_cvt_scalef32_pk_f16_fp4 v42, v6, 1.0 op_sel:[0,1,0]
	v_cvt_scalef32_pk_f16_fp4 v43, v6, 1.0 op_sel:[1,1,0]
	v_cvt_scalef32_pk_f16_fp4 v44, v7, 1.0
	v_cvt_scalef32_pk_f16_fp4 v45, v7, 1.0 op_sel:[1,0,0]
	v_cvt_scalef32_pk_f16_fp4 v46, v7, 1.0 op_sel:[0,1,0]
	v_cvt_scalef32_pk_f16_fp4 v47, v7, 1.0 op_sel:[1,1,0]
	buffer_load_dwordx4 v[0:3], v[176:177], s[12:15], 0 idxen offen
	v_pk_fma_f16 v124, v32, v185, v124
	v_pk_fma_f16 v123, v33, v185, v123
	v_pk_fma_f16 v121, v34, v185, v121
	v_pk_fma_f16 v120, v35, v185, v120
	v_pk_fma_f16 v119, v36, v185, v119
	v_pk_fma_f16 v118, v37, v185, v118
	v_pk_fma_f16 v117, v38, v185, v117
	v_pk_fma_f16 v116, v39, v185, v116
	v_pk_fma_f16 v113, v40, v185, v113
	v_pk_fma_f16 v112, v41, v185, v112
	v_pk_fma_f16 v67, v42, v185, v67
	v_pk_fma_f16 v66, v43, v185, v66
	v_pk_fma_f16 v65, v44, v185, v65
	v_pk_fma_f16 v64, v45, v185, v64
	v_pk_fma_f16 v125, v46, v185, v125
	v_pk_fma_f16 v122, v47, v185, v122
	ds_read_b32 v180, v115 offset:9240
	ds_read_b32 v184, v115 offset:20
	s_waitcnt vmcnt(6) lgkmcnt(3)
	v_cvt_scalef32_pk_f16_fp4 v32, v8, 1.0
	v_cvt_scalef32_pk_f16_fp4 v33, v8, 1.0 op_sel:[1,0,0]
	v_cvt_scalef32_pk_f16_fp4 v34, v8, 1.0 op_sel:[0,1,0]
	v_cvt_scalef32_pk_f16_fp4 v35, v8, 1.0 op_sel:[1,1,0]
	v_cvt_scalef32_pk_f16_fp4 v36, v9, 1.0
	v_cvt_scalef32_pk_f16_fp4 v37, v9, 1.0 op_sel:[1,0,0]
	v_cvt_scalef32_pk_f16_fp4 v38, v9, 1.0 op_sel:[0,1,0]
	v_cvt_scalef32_pk_f16_fp4 v39, v9, 1.0 op_sel:[1,1,0]
	v_cvt_scalef32_pk_f16_fp4 v40, v10, 1.0
	v_cvt_scalef32_pk_f16_fp4 v41, v10, 1.0 op_sel:[1,0,0]
	v_cvt_scalef32_pk_f16_fp4 v42, v10, 1.0 op_sel:[0,1,0]
	v_cvt_scalef32_pk_f16_fp4 v43, v10, 1.0 op_sel:[1,1,0]
	v_cvt_scalef32_pk_f16_fp4 v44, v11, 1.0
	v_cvt_scalef32_pk_f16_fp4 v45, v11, 1.0 op_sel:[1,0,0]
	v_cvt_scalef32_pk_f16_fp4 v46, v11, 1.0 op_sel:[0,1,0]
	v_cvt_scalef32_pk_f16_fp4 v47, v11, 1.0 op_sel:[1,1,0]
	buffer_load_dwordx4 v[4:7], v[178:179], s[12:15], 0 idxen offen
	v_pk_fma_f16 v74, v32, v186, v74
	v_pk_fma_f16 v73, v33, v186, v73
	v_pk_fma_f16 v71, v34, v186, v71
	v_pk_fma_f16 v70, v35, v186, v70
	v_pk_fma_f16 v69, v36, v186, v69
	v_pk_fma_f16 v68, v37, v186, v68
	v_pk_fma_f16 v63, v38, v186, v63
	v_pk_fma_f16 v62, v39, v186, v62
	v_pk_fma_f16 v61, v40, v186, v61
	v_pk_fma_f16 v60, v41, v186, v60
	v_pk_fma_f16 v59, v42, v186, v59
	v_pk_fma_f16 v58, v43, v186, v58
	v_pk_fma_f16 v57, v44, v186, v57
	v_pk_fma_f16 v56, v45, v186, v56
	v_pk_fma_f16 v75, v46, v186, v75
	v_pk_fma_f16 v72, v47, v186, v72
	ds_read_b32 v182, v115 offset:9752
	ds_read_b32 v185, v115 offset:532
	s_waitcnt vmcnt(6) lgkmcnt(3)
	v_cvt_scalef32_pk_f16_fp4 v32, v12, 1.0
	v_cvt_scalef32_pk_f16_fp4 v33, v12, 1.0 op_sel:[1,0,0]
	v_cvt_scalef32_pk_f16_fp4 v34, v12, 1.0 op_sel:[0,1,0]
	v_cvt_scalef32_pk_f16_fp4 v35, v12, 1.0 op_sel:[1,1,0]
	v_cvt_scalef32_pk_f16_fp4 v36, v13, 1.0
	v_cvt_scalef32_pk_f16_fp4 v37, v13, 1.0 op_sel:[1,0,0]
	v_cvt_scalef32_pk_f16_fp4 v38, v13, 1.0 op_sel:[0,1,0]
	v_cvt_scalef32_pk_f16_fp4 v39, v13, 1.0 op_sel:[1,1,0]
	v_cvt_scalef32_pk_f16_fp4 v40, v14, 1.0
	v_cvt_scalef32_pk_f16_fp4 v41, v14, 1.0 op_sel:[1,0,0]
	v_cvt_scalef32_pk_f16_fp4 v42, v14, 1.0 op_sel:[0,1,0]
	v_cvt_scalef32_pk_f16_fp4 v43, v14, 1.0 op_sel:[1,1,0]
	v_cvt_scalef32_pk_f16_fp4 v44, v15, 1.0
	v_cvt_scalef32_pk_f16_fp4 v45, v15, 1.0 op_sel:[1,0,0]
	v_cvt_scalef32_pk_f16_fp4 v46, v15, 1.0 op_sel:[0,1,0]
	v_cvt_scalef32_pk_f16_fp4 v47, v15, 1.0 op_sel:[1,1,0]
	buffer_load_dwordx4 v[8:11], v[180:181], s[12:15], 0 idxen offen
	v_pk_fma_f16 v162, v32, v187, v162
	v_pk_fma_f16 v161, v33, v187, v161
	v_pk_fma_f16 v160, v34, v187, v160
	v_pk_fma_f16 v159, v35, v187, v159
	v_pk_fma_f16 v158, v36, v187, v158
	v_pk_fma_f16 v157, v37, v187, v157
	v_pk_fma_f16 v156, v38, v187, v156
	v_pk_fma_f16 v147, v39, v187, v147
	v_pk_fma_f16 v146, v40, v187, v146
	v_pk_fma_f16 v145, v41, v187, v145
	v_pk_fma_f16 v144, v42, v187, v144
	v_pk_fma_f16 v143, v43, v187, v143
	v_pk_fma_f16 v142, v44, v187, v142
	v_pk_fma_f16 v141, v45, v187, v141
	v_pk_fma_f16 v149, v46, v187, v149
	v_pk_fma_f16 v148, v47, v187, v148
	ds_read_b32 v176, v115 offset:8220
	ds_read_b32 v186, v115 offset:1044
	s_waitcnt vmcnt(6) lgkmcnt(3)
	v_cvt_scalef32_pk_f16_fp4 v32, v16, 1.0
	v_cvt_scalef32_pk_f16_fp4 v33, v16, 1.0 op_sel:[1,0,0]
	v_cvt_scalef32_pk_f16_fp4 v34, v16, 1.0 op_sel:[0,1,0]
	v_cvt_scalef32_pk_f16_fp4 v35, v16, 1.0 op_sel:[1,1,0]
	v_cvt_scalef32_pk_f16_fp4 v36, v17, 1.0
	v_cvt_scalef32_pk_f16_fp4 v37, v17, 1.0 op_sel:[1,0,0]
	v_cvt_scalef32_pk_f16_fp4 v38, v17, 1.0 op_sel:[0,1,0]
	v_cvt_scalef32_pk_f16_fp4 v39, v17, 1.0 op_sel:[1,1,0]
	v_cvt_scalef32_pk_f16_fp4 v40, v18, 1.0
	v_cvt_scalef32_pk_f16_fp4 v41, v18, 1.0 op_sel:[1,0,0]
	v_cvt_scalef32_pk_f16_fp4 v42, v18, 1.0 op_sel:[0,1,0]
	v_cvt_scalef32_pk_f16_fp4 v43, v18, 1.0 op_sel:[1,1,0]
	v_cvt_scalef32_pk_f16_fp4 v44, v19, 1.0
	v_cvt_scalef32_pk_f16_fp4 v45, v19, 1.0 op_sel:[1,0,0]
	v_cvt_scalef32_pk_f16_fp4 v46, v19, 1.0 op_sel:[0,1,0]
	v_cvt_scalef32_pk_f16_fp4 v47, v19, 1.0 op_sel:[1,1,0]
	buffer_load_dwordx4 v[12:15], v[182:183], s[12:15], 0 idxen offen
	v_pk_fma_f16 v139, v32, v184, v139
	v_pk_fma_f16 v138, v33, v184, v138
	v_pk_fma_f16 v136, v34, v184, v136
	v_pk_fma_f16 v135, v35, v184, v135
	v_pk_fma_f16 v134, v36, v184, v134
	v_pk_fma_f16 v133, v37, v184, v133
	v_pk_fma_f16 v132, v38, v184, v132
	v_pk_fma_f16 v131, v39, v184, v131
	v_pk_fma_f16 v130, v40, v184, v130
	v_pk_fma_f16 v129, v41, v184, v129
	v_pk_fma_f16 v128, v42, v184, v128
	v_pk_fma_f16 v127, v43, v184, v127
	v_pk_fma_f16 v126, v44, v184, v126
	v_pk_fma_f16 v114, v45, v184, v114
	v_pk_fma_f16 v140, v46, v184, v140
	v_pk_fma_f16 v137, v47, v184, v137
	ds_read_b32 v178, v115 offset:8732
	ds_read_b32 v187, v115 offset:1556
	s_waitcnt vmcnt(6) lgkmcnt(3)
	v_cvt_scalef32_pk_f16_fp4 v32, v20, 1.0
	v_cvt_scalef32_pk_f16_fp4 v33, v20, 1.0 op_sel:[1,0,0]
	v_cvt_scalef32_pk_f16_fp4 v34, v20, 1.0 op_sel:[0,1,0]
	v_cvt_scalef32_pk_f16_fp4 v35, v20, 1.0 op_sel:[1,1,0]
	v_cvt_scalef32_pk_f16_fp4 v36, v21, 1.0
	v_cvt_scalef32_pk_f16_fp4 v37, v21, 1.0 op_sel:[1,0,0]
	v_cvt_scalef32_pk_f16_fp4 v38, v21, 1.0 op_sel:[0,1,0]
	v_cvt_scalef32_pk_f16_fp4 v39, v21, 1.0 op_sel:[1,1,0]
	v_cvt_scalef32_pk_f16_fp4 v40, v22, 1.0
	v_cvt_scalef32_pk_f16_fp4 v41, v22, 1.0 op_sel:[1,0,0]
	v_cvt_scalef32_pk_f16_fp4 v42, v22, 1.0 op_sel:[0,1,0]
	v_cvt_scalef32_pk_f16_fp4 v43, v22, 1.0 op_sel:[1,1,0]
	v_cvt_scalef32_pk_f16_fp4 v44, v23, 1.0
	v_cvt_scalef32_pk_f16_fp4 v45, v23, 1.0 op_sel:[1,0,0]
	v_cvt_scalef32_pk_f16_fp4 v46, v23, 1.0 op_sel:[0,1,0]
	v_cvt_scalef32_pk_f16_fp4 v47, v23, 1.0 op_sel:[1,1,0]
	buffer_load_dwordx4 v[16:19], v[176:177], s[12:15], 0 idxen offen
	v_pk_fma_f16 v124, v32, v185, v124
	v_pk_fma_f16 v123, v33, v185, v123
	v_pk_fma_f16 v121, v34, v185, v121
	v_pk_fma_f16 v120, v35, v185, v120
	v_pk_fma_f16 v119, v36, v185, v119
	v_pk_fma_f16 v118, v37, v185, v118
	v_pk_fma_f16 v117, v38, v185, v117
	v_pk_fma_f16 v116, v39, v185, v116
	v_pk_fma_f16 v113, v40, v185, v113
	v_pk_fma_f16 v112, v41, v185, v112
	v_pk_fma_f16 v67, v42, v185, v67
	v_pk_fma_f16 v66, v43, v185, v66
	v_pk_fma_f16 v65, v44, v185, v65
	v_pk_fma_f16 v64, v45, v185, v64
	v_pk_fma_f16 v125, v46, v185, v125
	v_pk_fma_f16 v122, v47, v185, v122
	ds_read_b32 v180, v115 offset:9244
	ds_read_b32 v184, v115 offset:24
	s_waitcnt vmcnt(6) lgkmcnt(3)
	v_cvt_scalef32_pk_f16_fp4 v32, v24, 1.0
	v_cvt_scalef32_pk_f16_fp4 v33, v24, 1.0 op_sel:[1,0,0]
	v_cvt_scalef32_pk_f16_fp4 v34, v24, 1.0 op_sel:[0,1,0]
	v_cvt_scalef32_pk_f16_fp4 v35, v24, 1.0 op_sel:[1,1,0]
	v_cvt_scalef32_pk_f16_fp4 v36, v25, 1.0
	v_cvt_scalef32_pk_f16_fp4 v37, v25, 1.0 op_sel:[1,0,0]
	v_cvt_scalef32_pk_f16_fp4 v38, v25, 1.0 op_sel:[0,1,0]
	v_cvt_scalef32_pk_f16_fp4 v39, v25, 1.0 op_sel:[1,1,0]
	v_cvt_scalef32_pk_f16_fp4 v40, v26, 1.0
	v_cvt_scalef32_pk_f16_fp4 v41, v26, 1.0 op_sel:[1,0,0]
	v_cvt_scalef32_pk_f16_fp4 v42, v26, 1.0 op_sel:[0,1,0]
	v_cvt_scalef32_pk_f16_fp4 v43, v26, 1.0 op_sel:[1,1,0]
	v_cvt_scalef32_pk_f16_fp4 v44, v27, 1.0
	v_cvt_scalef32_pk_f16_fp4 v45, v27, 1.0 op_sel:[1,0,0]
	v_cvt_scalef32_pk_f16_fp4 v46, v27, 1.0 op_sel:[0,1,0]
	v_cvt_scalef32_pk_f16_fp4 v47, v27, 1.0 op_sel:[1,1,0]
	buffer_load_dwordx4 v[20:23], v[178:179], s[12:15], 0 idxen offen
	v_pk_fma_f16 v74, v32, v186, v74
	v_pk_fma_f16 v73, v33, v186, v73
	v_pk_fma_f16 v71, v34, v186, v71
	v_pk_fma_f16 v70, v35, v186, v70
	v_pk_fma_f16 v69, v36, v186, v69
	v_pk_fma_f16 v68, v37, v186, v68
	v_pk_fma_f16 v63, v38, v186, v63
	v_pk_fma_f16 v62, v39, v186, v62
	v_pk_fma_f16 v61, v40, v186, v61
	v_pk_fma_f16 v60, v41, v186, v60
	v_pk_fma_f16 v59, v42, v186, v59
	v_pk_fma_f16 v58, v43, v186, v58
	v_pk_fma_f16 v57, v44, v186, v57
	v_pk_fma_f16 v56, v45, v186, v56
	v_pk_fma_f16 v75, v46, v186, v75
	v_pk_fma_f16 v72, v47, v186, v72
	ds_read_b32 v182, v115 offset:9756
	ds_read_b32 v185, v115 offset:536
	s_waitcnt vmcnt(6) lgkmcnt(3)
	v_cvt_scalef32_pk_f16_fp4 v32, v28, 1.0
	v_cvt_scalef32_pk_f16_fp4 v33, v28, 1.0 op_sel:[1,0,0]
	v_cvt_scalef32_pk_f16_fp4 v34, v28, 1.0 op_sel:[0,1,0]
	v_cvt_scalef32_pk_f16_fp4 v35, v28, 1.0 op_sel:[1,1,0]
	v_cvt_scalef32_pk_f16_fp4 v36, v29, 1.0
	v_cvt_scalef32_pk_f16_fp4 v37, v29, 1.0 op_sel:[1,0,0]
	v_cvt_scalef32_pk_f16_fp4 v38, v29, 1.0 op_sel:[0,1,0]
	v_cvt_scalef32_pk_f16_fp4 v39, v29, 1.0 op_sel:[1,1,0]
	v_cvt_scalef32_pk_f16_fp4 v40, v30, 1.0
	v_cvt_scalef32_pk_f16_fp4 v41, v30, 1.0 op_sel:[1,0,0]
	v_cvt_scalef32_pk_f16_fp4 v42, v30, 1.0 op_sel:[0,1,0]
	v_cvt_scalef32_pk_f16_fp4 v43, v30, 1.0 op_sel:[1,1,0]
	v_cvt_scalef32_pk_f16_fp4 v44, v31, 1.0
	v_cvt_scalef32_pk_f16_fp4 v45, v31, 1.0 op_sel:[1,0,0]
	v_cvt_scalef32_pk_f16_fp4 v46, v31, 1.0 op_sel:[0,1,0]
	v_cvt_scalef32_pk_f16_fp4 v47, v31, 1.0 op_sel:[1,1,0]
	buffer_load_dwordx4 v[24:27], v[180:181], s[12:15], 0 idxen offen
	v_pk_fma_f16 v162, v32, v187, v162
	v_pk_fma_f16 v161, v33, v187, v161
	v_pk_fma_f16 v160, v34, v187, v160
	v_pk_fma_f16 v159, v35, v187, v159
	v_pk_fma_f16 v158, v36, v187, v158
	v_pk_fma_f16 v157, v37, v187, v157
	v_pk_fma_f16 v156, v38, v187, v156
	v_pk_fma_f16 v147, v39, v187, v147
	v_pk_fma_f16 v146, v40, v187, v146
	v_pk_fma_f16 v145, v41, v187, v145
	v_pk_fma_f16 v144, v42, v187, v144
	v_pk_fma_f16 v143, v43, v187, v143
	v_pk_fma_f16 v142, v44, v187, v142
	v_pk_fma_f16 v141, v45, v187, v141
	v_pk_fma_f16 v149, v46, v187, v149
	v_pk_fma_f16 v148, v47, v187, v148
	ds_read_b32 v176, v115 offset:8224
	ds_read_b32 v186, v115 offset:1048
	s_waitcnt vmcnt(6) lgkmcnt(3)
	v_cvt_scalef32_pk_f16_fp4 v32, v0, 1.0
	v_cvt_scalef32_pk_f16_fp4 v33, v0, 1.0 op_sel:[1,0,0]
	v_cvt_scalef32_pk_f16_fp4 v34, v0, 1.0 op_sel:[0,1,0]
	v_cvt_scalef32_pk_f16_fp4 v35, v0, 1.0 op_sel:[1,1,0]
	v_cvt_scalef32_pk_f16_fp4 v36, v1, 1.0
	v_cvt_scalef32_pk_f16_fp4 v37, v1, 1.0 op_sel:[1,0,0]
	v_cvt_scalef32_pk_f16_fp4 v38, v1, 1.0 op_sel:[0,1,0]
	v_cvt_scalef32_pk_f16_fp4 v39, v1, 1.0 op_sel:[1,1,0]
	v_cvt_scalef32_pk_f16_fp4 v40, v2, 1.0
	v_cvt_scalef32_pk_f16_fp4 v41, v2, 1.0 op_sel:[1,0,0]
	v_cvt_scalef32_pk_f16_fp4 v42, v2, 1.0 op_sel:[0,1,0]
	v_cvt_scalef32_pk_f16_fp4 v43, v2, 1.0 op_sel:[1,1,0]
	v_cvt_scalef32_pk_f16_fp4 v44, v3, 1.0
	v_cvt_scalef32_pk_f16_fp4 v45, v3, 1.0 op_sel:[1,0,0]
	v_cvt_scalef32_pk_f16_fp4 v46, v3, 1.0 op_sel:[0,1,0]
	v_cvt_scalef32_pk_f16_fp4 v47, v3, 1.0 op_sel:[1,1,0]
	buffer_load_dwordx4 v[28:31], v[182:183], s[12:15], 0 idxen offen
	v_pk_fma_f16 v139, v32, v184, v139
	v_pk_fma_f16 v138, v33, v184, v138
	v_pk_fma_f16 v136, v34, v184, v136
	v_pk_fma_f16 v135, v35, v184, v135
	v_pk_fma_f16 v134, v36, v184, v134
	v_pk_fma_f16 v133, v37, v184, v133
	v_pk_fma_f16 v132, v38, v184, v132
	v_pk_fma_f16 v131, v39, v184, v131
	v_pk_fma_f16 v130, v40, v184, v130
	v_pk_fma_f16 v129, v41, v184, v129
	v_pk_fma_f16 v128, v42, v184, v128
	v_pk_fma_f16 v127, v43, v184, v127
	v_pk_fma_f16 v126, v44, v184, v126
	v_pk_fma_f16 v114, v45, v184, v114
	v_pk_fma_f16 v140, v46, v184, v140
	v_pk_fma_f16 v137, v47, v184, v137
	ds_read_b32 v178, v115 offset:8736
	ds_read_b32 v187, v115 offset:1560
	s_waitcnt vmcnt(6) lgkmcnt(3)
	v_cvt_scalef32_pk_f16_fp4 v32, v4, 1.0
	v_cvt_scalef32_pk_f16_fp4 v33, v4, 1.0 op_sel:[1,0,0]
	v_cvt_scalef32_pk_f16_fp4 v34, v4, 1.0 op_sel:[0,1,0]
	v_cvt_scalef32_pk_f16_fp4 v35, v4, 1.0 op_sel:[1,1,0]
	v_cvt_scalef32_pk_f16_fp4 v36, v5, 1.0
	v_cvt_scalef32_pk_f16_fp4 v37, v5, 1.0 op_sel:[1,0,0]
	v_cvt_scalef32_pk_f16_fp4 v38, v5, 1.0 op_sel:[0,1,0]
	v_cvt_scalef32_pk_f16_fp4 v39, v5, 1.0 op_sel:[1,1,0]
	v_cvt_scalef32_pk_f16_fp4 v40, v6, 1.0
	v_cvt_scalef32_pk_f16_fp4 v41, v6, 1.0 op_sel:[1,0,0]
	v_cvt_scalef32_pk_f16_fp4 v42, v6, 1.0 op_sel:[0,1,0]
	v_cvt_scalef32_pk_f16_fp4 v43, v6, 1.0 op_sel:[1,1,0]
	v_cvt_scalef32_pk_f16_fp4 v44, v7, 1.0
	v_cvt_scalef32_pk_f16_fp4 v45, v7, 1.0 op_sel:[1,0,0]
	v_cvt_scalef32_pk_f16_fp4 v46, v7, 1.0 op_sel:[0,1,0]
	v_cvt_scalef32_pk_f16_fp4 v47, v7, 1.0 op_sel:[1,1,0]
	buffer_load_dwordx4 v[0:3], v[176:177], s[12:15], 0 idxen offen
	v_pk_fma_f16 v124, v32, v185, v124
	v_pk_fma_f16 v123, v33, v185, v123
	v_pk_fma_f16 v121, v34, v185, v121
	v_pk_fma_f16 v120, v35, v185, v120
	v_pk_fma_f16 v119, v36, v185, v119
	v_pk_fma_f16 v118, v37, v185, v118
	v_pk_fma_f16 v117, v38, v185, v117
	v_pk_fma_f16 v116, v39, v185, v116
	v_pk_fma_f16 v113, v40, v185, v113
	v_pk_fma_f16 v112, v41, v185, v112
	v_pk_fma_f16 v67, v42, v185, v67
	v_pk_fma_f16 v66, v43, v185, v66
	v_pk_fma_f16 v65, v44, v185, v65
	v_pk_fma_f16 v64, v45, v185, v64
	v_pk_fma_f16 v125, v46, v185, v125
	v_pk_fma_f16 v122, v47, v185, v122
	ds_read_b32 v180, v115 offset:9248
	ds_read_b32 v184, v115 offset:28
	s_waitcnt vmcnt(6) lgkmcnt(3)
	v_cvt_scalef32_pk_f16_fp4 v32, v8, 1.0
	v_cvt_scalef32_pk_f16_fp4 v33, v8, 1.0 op_sel:[1,0,0]
	v_cvt_scalef32_pk_f16_fp4 v34, v8, 1.0 op_sel:[0,1,0]
	v_cvt_scalef32_pk_f16_fp4 v35, v8, 1.0 op_sel:[1,1,0]
	v_cvt_scalef32_pk_f16_fp4 v36, v9, 1.0
	v_cvt_scalef32_pk_f16_fp4 v37, v9, 1.0 op_sel:[1,0,0]
	v_cvt_scalef32_pk_f16_fp4 v38, v9, 1.0 op_sel:[0,1,0]
	v_cvt_scalef32_pk_f16_fp4 v39, v9, 1.0 op_sel:[1,1,0]
	v_cvt_scalef32_pk_f16_fp4 v40, v10, 1.0
	v_cvt_scalef32_pk_f16_fp4 v41, v10, 1.0 op_sel:[1,0,0]
	v_cvt_scalef32_pk_f16_fp4 v42, v10, 1.0 op_sel:[0,1,0]
	v_cvt_scalef32_pk_f16_fp4 v43, v10, 1.0 op_sel:[1,1,0]
	v_cvt_scalef32_pk_f16_fp4 v44, v11, 1.0
	v_cvt_scalef32_pk_f16_fp4 v45, v11, 1.0 op_sel:[1,0,0]
	v_cvt_scalef32_pk_f16_fp4 v46, v11, 1.0 op_sel:[0,1,0]
	v_cvt_scalef32_pk_f16_fp4 v47, v11, 1.0 op_sel:[1,1,0]
	buffer_load_dwordx4 v[4:7], v[178:179], s[12:15], 0 idxen offen
	v_pk_fma_f16 v74, v32, v186, v74
	v_pk_fma_f16 v73, v33, v186, v73
	v_pk_fma_f16 v71, v34, v186, v71
	v_pk_fma_f16 v70, v35, v186, v70
	v_pk_fma_f16 v69, v36, v186, v69
	v_pk_fma_f16 v68, v37, v186, v68
	v_pk_fma_f16 v63, v38, v186, v63
	v_pk_fma_f16 v62, v39, v186, v62
	v_pk_fma_f16 v61, v40, v186, v61
	v_pk_fma_f16 v60, v41, v186, v60
	v_pk_fma_f16 v59, v42, v186, v59
	v_pk_fma_f16 v58, v43, v186, v58
	v_pk_fma_f16 v57, v44, v186, v57
	v_pk_fma_f16 v56, v45, v186, v56
	v_pk_fma_f16 v75, v46, v186, v75
	v_pk_fma_f16 v72, v47, v186, v72
	ds_read_b32 v182, v115 offset:9760
	ds_read_b32 v185, v115 offset:540
	s_waitcnt vmcnt(6) lgkmcnt(3)
	v_cvt_scalef32_pk_f16_fp4 v32, v12, 1.0
	v_cvt_scalef32_pk_f16_fp4 v33, v12, 1.0 op_sel:[1,0,0]
	v_cvt_scalef32_pk_f16_fp4 v34, v12, 1.0 op_sel:[0,1,0]
	v_cvt_scalef32_pk_f16_fp4 v35, v12, 1.0 op_sel:[1,1,0]
	v_cvt_scalef32_pk_f16_fp4 v36, v13, 1.0
	v_cvt_scalef32_pk_f16_fp4 v37, v13, 1.0 op_sel:[1,0,0]
	v_cvt_scalef32_pk_f16_fp4 v38, v13, 1.0 op_sel:[0,1,0]
	v_cvt_scalef32_pk_f16_fp4 v39, v13, 1.0 op_sel:[1,1,0]
	v_cvt_scalef32_pk_f16_fp4 v40, v14, 1.0
	v_cvt_scalef32_pk_f16_fp4 v41, v14, 1.0 op_sel:[1,0,0]
	v_cvt_scalef32_pk_f16_fp4 v42, v14, 1.0 op_sel:[0,1,0]
	v_cvt_scalef32_pk_f16_fp4 v43, v14, 1.0 op_sel:[1,1,0]
	v_cvt_scalef32_pk_f16_fp4 v44, v15, 1.0
	v_cvt_scalef32_pk_f16_fp4 v45, v15, 1.0 op_sel:[1,0,0]
	v_cvt_scalef32_pk_f16_fp4 v46, v15, 1.0 op_sel:[0,1,0]
	v_cvt_scalef32_pk_f16_fp4 v47, v15, 1.0 op_sel:[1,1,0]
	buffer_load_dwordx4 v[8:11], v[180:181], s[12:15], 0 idxen offen
	v_pk_fma_f16 v162, v32, v187, v162
	v_pk_fma_f16 v161, v33, v187, v161
	v_pk_fma_f16 v160, v34, v187, v160
	v_pk_fma_f16 v159, v35, v187, v159
	v_pk_fma_f16 v158, v36, v187, v158
	v_pk_fma_f16 v157, v37, v187, v157
	v_pk_fma_f16 v156, v38, v187, v156
	v_pk_fma_f16 v147, v39, v187, v147
	v_pk_fma_f16 v146, v40, v187, v146
	v_pk_fma_f16 v145, v41, v187, v145
	v_pk_fma_f16 v144, v42, v187, v144
	v_pk_fma_f16 v143, v43, v187, v143
	v_pk_fma_f16 v142, v44, v187, v142
	v_pk_fma_f16 v141, v45, v187, v141
	v_pk_fma_f16 v149, v46, v187, v149
	v_pk_fma_f16 v148, v47, v187, v148
	ds_read_b32 v176, v115 offset:8228
	ds_read_b32 v186, v115 offset:1052
	s_waitcnt vmcnt(6) lgkmcnt(3)
	v_cvt_scalef32_pk_f16_fp4 v32, v16, 1.0
	v_cvt_scalef32_pk_f16_fp4 v33, v16, 1.0 op_sel:[1,0,0]
	v_cvt_scalef32_pk_f16_fp4 v34, v16, 1.0 op_sel:[0,1,0]
	v_cvt_scalef32_pk_f16_fp4 v35, v16, 1.0 op_sel:[1,1,0]
	v_cvt_scalef32_pk_f16_fp4 v36, v17, 1.0
	v_cvt_scalef32_pk_f16_fp4 v37, v17, 1.0 op_sel:[1,0,0]
	v_cvt_scalef32_pk_f16_fp4 v38, v17, 1.0 op_sel:[0,1,0]
	v_cvt_scalef32_pk_f16_fp4 v39, v17, 1.0 op_sel:[1,1,0]
	v_cvt_scalef32_pk_f16_fp4 v40, v18, 1.0
	v_cvt_scalef32_pk_f16_fp4 v41, v18, 1.0 op_sel:[1,0,0]
	v_cvt_scalef32_pk_f16_fp4 v42, v18, 1.0 op_sel:[0,1,0]
	v_cvt_scalef32_pk_f16_fp4 v43, v18, 1.0 op_sel:[1,1,0]
	v_cvt_scalef32_pk_f16_fp4 v44, v19, 1.0
	v_cvt_scalef32_pk_f16_fp4 v45, v19, 1.0 op_sel:[1,0,0]
	v_cvt_scalef32_pk_f16_fp4 v46, v19, 1.0 op_sel:[0,1,0]
	v_cvt_scalef32_pk_f16_fp4 v47, v19, 1.0 op_sel:[1,1,0]
	buffer_load_dwordx4 v[12:15], v[182:183], s[12:15], 0 idxen offen
	v_pk_fma_f16 v139, v32, v184, v139
	v_pk_fma_f16 v138, v33, v184, v138
	v_pk_fma_f16 v136, v34, v184, v136
	v_pk_fma_f16 v135, v35, v184, v135
	v_pk_fma_f16 v134, v36, v184, v134
	v_pk_fma_f16 v133, v37, v184, v133
	v_pk_fma_f16 v132, v38, v184, v132
	v_pk_fma_f16 v131, v39, v184, v131
	v_pk_fma_f16 v130, v40, v184, v130
	v_pk_fma_f16 v129, v41, v184, v129
	v_pk_fma_f16 v128, v42, v184, v128
	v_pk_fma_f16 v127, v43, v184, v127
	v_pk_fma_f16 v126, v44, v184, v126
	v_pk_fma_f16 v114, v45, v184, v114
	v_pk_fma_f16 v140, v46, v184, v140
	v_pk_fma_f16 v137, v47, v184, v137
	ds_read_b32 v178, v115 offset:8740
	ds_read_b32 v187, v115 offset:1564
	s_waitcnt vmcnt(6) lgkmcnt(3)
	v_cvt_scalef32_pk_f16_fp4 v32, v20, 1.0
	v_cvt_scalef32_pk_f16_fp4 v33, v20, 1.0 op_sel:[1,0,0]
	v_cvt_scalef32_pk_f16_fp4 v34, v20, 1.0 op_sel:[0,1,0]
	v_cvt_scalef32_pk_f16_fp4 v35, v20, 1.0 op_sel:[1,1,0]
	v_cvt_scalef32_pk_f16_fp4 v36, v21, 1.0
	v_cvt_scalef32_pk_f16_fp4 v37, v21, 1.0 op_sel:[1,0,0]
	v_cvt_scalef32_pk_f16_fp4 v38, v21, 1.0 op_sel:[0,1,0]
	v_cvt_scalef32_pk_f16_fp4 v39, v21, 1.0 op_sel:[1,1,0]
	v_cvt_scalef32_pk_f16_fp4 v40, v22, 1.0
	v_cvt_scalef32_pk_f16_fp4 v41, v22, 1.0 op_sel:[1,0,0]
	v_cvt_scalef32_pk_f16_fp4 v42, v22, 1.0 op_sel:[0,1,0]
	v_cvt_scalef32_pk_f16_fp4 v43, v22, 1.0 op_sel:[1,1,0]
	v_cvt_scalef32_pk_f16_fp4 v44, v23, 1.0
	v_cvt_scalef32_pk_f16_fp4 v45, v23, 1.0 op_sel:[1,0,0]
	v_cvt_scalef32_pk_f16_fp4 v46, v23, 1.0 op_sel:[0,1,0]
	v_cvt_scalef32_pk_f16_fp4 v47, v23, 1.0 op_sel:[1,1,0]
	buffer_load_dwordx4 v[16:19], v[176:177], s[12:15], 0 idxen offen
	v_pk_fma_f16 v124, v32, v185, v124
	v_pk_fma_f16 v123, v33, v185, v123
	v_pk_fma_f16 v121, v34, v185, v121
	v_pk_fma_f16 v120, v35, v185, v120
	v_pk_fma_f16 v119, v36, v185, v119
	v_pk_fma_f16 v118, v37, v185, v118
	v_pk_fma_f16 v117, v38, v185, v117
	v_pk_fma_f16 v116, v39, v185, v116
	v_pk_fma_f16 v113, v40, v185, v113
	v_pk_fma_f16 v112, v41, v185, v112
	v_pk_fma_f16 v67, v42, v185, v67
	v_pk_fma_f16 v66, v43, v185, v66
	v_pk_fma_f16 v65, v44, v185, v65
	v_pk_fma_f16 v64, v45, v185, v64
	v_pk_fma_f16 v125, v46, v185, v125
	v_pk_fma_f16 v122, v47, v185, v122
	ds_read_b32 v180, v115 offset:9252
	ds_read_b32 v184, v115 offset:32
	s_waitcnt vmcnt(6) lgkmcnt(3)
	v_cvt_scalef32_pk_f16_fp4 v32, v24, 1.0
	v_cvt_scalef32_pk_f16_fp4 v33, v24, 1.0 op_sel:[1,0,0]
	v_cvt_scalef32_pk_f16_fp4 v34, v24, 1.0 op_sel:[0,1,0]
	v_cvt_scalef32_pk_f16_fp4 v35, v24, 1.0 op_sel:[1,1,0]
	v_cvt_scalef32_pk_f16_fp4 v36, v25, 1.0
	v_cvt_scalef32_pk_f16_fp4 v37, v25, 1.0 op_sel:[1,0,0]
	v_cvt_scalef32_pk_f16_fp4 v38, v25, 1.0 op_sel:[0,1,0]
	v_cvt_scalef32_pk_f16_fp4 v39, v25, 1.0 op_sel:[1,1,0]
	v_cvt_scalef32_pk_f16_fp4 v40, v26, 1.0
	v_cvt_scalef32_pk_f16_fp4 v41, v26, 1.0 op_sel:[1,0,0]
	v_cvt_scalef32_pk_f16_fp4 v42, v26, 1.0 op_sel:[0,1,0]
	v_cvt_scalef32_pk_f16_fp4 v43, v26, 1.0 op_sel:[1,1,0]
	v_cvt_scalef32_pk_f16_fp4 v44, v27, 1.0
	v_cvt_scalef32_pk_f16_fp4 v45, v27, 1.0 op_sel:[1,0,0]
	v_cvt_scalef32_pk_f16_fp4 v46, v27, 1.0 op_sel:[0,1,0]
	v_cvt_scalef32_pk_f16_fp4 v47, v27, 1.0 op_sel:[1,1,0]
	buffer_load_dwordx4 v[20:23], v[178:179], s[12:15], 0 idxen offen
	v_pk_fma_f16 v74, v32, v186, v74
	v_pk_fma_f16 v73, v33, v186, v73
	v_pk_fma_f16 v71, v34, v186, v71
	v_pk_fma_f16 v70, v35, v186, v70
	v_pk_fma_f16 v69, v36, v186, v69
	v_pk_fma_f16 v68, v37, v186, v68
	v_pk_fma_f16 v63, v38, v186, v63
	v_pk_fma_f16 v62, v39, v186, v62
	v_pk_fma_f16 v61, v40, v186, v61
	v_pk_fma_f16 v60, v41, v186, v60
	v_pk_fma_f16 v59, v42, v186, v59
	v_pk_fma_f16 v58, v43, v186, v58
	v_pk_fma_f16 v57, v44, v186, v57
	v_pk_fma_f16 v56, v45, v186, v56
	v_pk_fma_f16 v75, v46, v186, v75
	v_pk_fma_f16 v72, v47, v186, v72
	ds_read_b32 v182, v115 offset:9764
	ds_read_b32 v185, v115 offset:544
	s_waitcnt vmcnt(6) lgkmcnt(3)
	v_cvt_scalef32_pk_f16_fp4 v32, v28, 1.0
	v_cvt_scalef32_pk_f16_fp4 v33, v28, 1.0 op_sel:[1,0,0]
	v_cvt_scalef32_pk_f16_fp4 v34, v28, 1.0 op_sel:[0,1,0]
	v_cvt_scalef32_pk_f16_fp4 v35, v28, 1.0 op_sel:[1,1,0]
	v_cvt_scalef32_pk_f16_fp4 v36, v29, 1.0
	v_cvt_scalef32_pk_f16_fp4 v37, v29, 1.0 op_sel:[1,0,0]
	v_cvt_scalef32_pk_f16_fp4 v38, v29, 1.0 op_sel:[0,1,0]
	v_cvt_scalef32_pk_f16_fp4 v39, v29, 1.0 op_sel:[1,1,0]
	v_cvt_scalef32_pk_f16_fp4 v40, v30, 1.0
	v_cvt_scalef32_pk_f16_fp4 v41, v30, 1.0 op_sel:[1,0,0]
	v_cvt_scalef32_pk_f16_fp4 v42, v30, 1.0 op_sel:[0,1,0]
	v_cvt_scalef32_pk_f16_fp4 v43, v30, 1.0 op_sel:[1,1,0]
	v_cvt_scalef32_pk_f16_fp4 v44, v31, 1.0
	v_cvt_scalef32_pk_f16_fp4 v45, v31, 1.0 op_sel:[1,0,0]
	v_cvt_scalef32_pk_f16_fp4 v46, v31, 1.0 op_sel:[0,1,0]
	v_cvt_scalef32_pk_f16_fp4 v47, v31, 1.0 op_sel:[1,1,0]
	buffer_load_dwordx4 v[24:27], v[180:181], s[12:15], 0 idxen offen
	v_pk_fma_f16 v162, v32, v187, v162
	v_pk_fma_f16 v161, v33, v187, v161
	v_pk_fma_f16 v160, v34, v187, v160
	v_pk_fma_f16 v159, v35, v187, v159
	v_pk_fma_f16 v158, v36, v187, v158
	v_pk_fma_f16 v157, v37, v187, v157
	v_pk_fma_f16 v156, v38, v187, v156
	v_pk_fma_f16 v147, v39, v187, v147
	v_pk_fma_f16 v146, v40, v187, v146
	v_pk_fma_f16 v145, v41, v187, v145
	v_pk_fma_f16 v144, v42, v187, v144
	v_pk_fma_f16 v143, v43, v187, v143
	v_pk_fma_f16 v142, v44, v187, v142
	v_pk_fma_f16 v141, v45, v187, v141
	v_pk_fma_f16 v149, v46, v187, v149
	v_pk_fma_f16 v148, v47, v187, v148
	ds_read_b32 v176, v115 offset:8232
	ds_read_b32 v186, v115 offset:1056
	s_waitcnt vmcnt(6) lgkmcnt(3)
	v_cvt_scalef32_pk_f16_fp4 v32, v0, 1.0
	v_cvt_scalef32_pk_f16_fp4 v33, v0, 1.0 op_sel:[1,0,0]
	v_cvt_scalef32_pk_f16_fp4 v34, v0, 1.0 op_sel:[0,1,0]
	v_cvt_scalef32_pk_f16_fp4 v35, v0, 1.0 op_sel:[1,1,0]
	v_cvt_scalef32_pk_f16_fp4 v36, v1, 1.0
	v_cvt_scalef32_pk_f16_fp4 v37, v1, 1.0 op_sel:[1,0,0]
	v_cvt_scalef32_pk_f16_fp4 v38, v1, 1.0 op_sel:[0,1,0]
	v_cvt_scalef32_pk_f16_fp4 v39, v1, 1.0 op_sel:[1,1,0]
	v_cvt_scalef32_pk_f16_fp4 v40, v2, 1.0
	v_cvt_scalef32_pk_f16_fp4 v41, v2, 1.0 op_sel:[1,0,0]
	v_cvt_scalef32_pk_f16_fp4 v42, v2, 1.0 op_sel:[0,1,0]
	v_cvt_scalef32_pk_f16_fp4 v43, v2, 1.0 op_sel:[1,1,0]
	v_cvt_scalef32_pk_f16_fp4 v44, v3, 1.0
	v_cvt_scalef32_pk_f16_fp4 v45, v3, 1.0 op_sel:[1,0,0]
	v_cvt_scalef32_pk_f16_fp4 v46, v3, 1.0 op_sel:[0,1,0]
	v_cvt_scalef32_pk_f16_fp4 v47, v3, 1.0 op_sel:[1,1,0]
	buffer_load_dwordx4 v[28:31], v[182:183], s[12:15], 0 idxen offen
	v_pk_fma_f16 v139, v32, v184, v139
	v_pk_fma_f16 v138, v33, v184, v138
	v_pk_fma_f16 v136, v34, v184, v136
	v_pk_fma_f16 v135, v35, v184, v135
	v_pk_fma_f16 v134, v36, v184, v134
	v_pk_fma_f16 v133, v37, v184, v133
	v_pk_fma_f16 v132, v38, v184, v132
	v_pk_fma_f16 v131, v39, v184, v131
	v_pk_fma_f16 v130, v40, v184, v130
	v_pk_fma_f16 v129, v41, v184, v129
	v_pk_fma_f16 v128, v42, v184, v128
	v_pk_fma_f16 v127, v43, v184, v127
	v_pk_fma_f16 v126, v44, v184, v126
	v_pk_fma_f16 v114, v45, v184, v114
	v_pk_fma_f16 v140, v46, v184, v140
	v_pk_fma_f16 v137, v47, v184, v137
	ds_read_b32 v178, v115 offset:8744
	ds_read_b32 v187, v115 offset:1568
	s_waitcnt vmcnt(6) lgkmcnt(3)
	v_cvt_scalef32_pk_f16_fp4 v32, v4, 1.0
	v_cvt_scalef32_pk_f16_fp4 v33, v4, 1.0 op_sel:[1,0,0]
	v_cvt_scalef32_pk_f16_fp4 v34, v4, 1.0 op_sel:[0,1,0]
	v_cvt_scalef32_pk_f16_fp4 v35, v4, 1.0 op_sel:[1,1,0]
	v_cvt_scalef32_pk_f16_fp4 v36, v5, 1.0
	v_cvt_scalef32_pk_f16_fp4 v37, v5, 1.0 op_sel:[1,0,0]
	v_cvt_scalef32_pk_f16_fp4 v38, v5, 1.0 op_sel:[0,1,0]
	v_cvt_scalef32_pk_f16_fp4 v39, v5, 1.0 op_sel:[1,1,0]
	v_cvt_scalef32_pk_f16_fp4 v40, v6, 1.0
	v_cvt_scalef32_pk_f16_fp4 v41, v6, 1.0 op_sel:[1,0,0]
	v_cvt_scalef32_pk_f16_fp4 v42, v6, 1.0 op_sel:[0,1,0]
	v_cvt_scalef32_pk_f16_fp4 v43, v6, 1.0 op_sel:[1,1,0]
	v_cvt_scalef32_pk_f16_fp4 v44, v7, 1.0
	v_cvt_scalef32_pk_f16_fp4 v45, v7, 1.0 op_sel:[1,0,0]
	v_cvt_scalef32_pk_f16_fp4 v46, v7, 1.0 op_sel:[0,1,0]
	v_cvt_scalef32_pk_f16_fp4 v47, v7, 1.0 op_sel:[1,1,0]
	buffer_load_dwordx4 v[0:3], v[176:177], s[12:15], 0 idxen offen
	v_pk_fma_f16 v124, v32, v185, v124
	v_pk_fma_f16 v123, v33, v185, v123
	v_pk_fma_f16 v121, v34, v185, v121
	v_pk_fma_f16 v120, v35, v185, v120
	v_pk_fma_f16 v119, v36, v185, v119
	v_pk_fma_f16 v118, v37, v185, v118
	v_pk_fma_f16 v117, v38, v185, v117
	v_pk_fma_f16 v116, v39, v185, v116
	v_pk_fma_f16 v113, v40, v185, v113
	v_pk_fma_f16 v112, v41, v185, v112
	v_pk_fma_f16 v67, v42, v185, v67
	v_pk_fma_f16 v66, v43, v185, v66
	v_pk_fma_f16 v65, v44, v185, v65
	v_pk_fma_f16 v64, v45, v185, v64
	v_pk_fma_f16 v125, v46, v185, v125
	v_pk_fma_f16 v122, v47, v185, v122
	ds_read_b32 v180, v115 offset:9256
	ds_read_b32 v184, v115 offset:36
	s_waitcnt vmcnt(6) lgkmcnt(3)
	v_cvt_scalef32_pk_f16_fp4 v32, v8, 1.0
	v_cvt_scalef32_pk_f16_fp4 v33, v8, 1.0 op_sel:[1,0,0]
	v_cvt_scalef32_pk_f16_fp4 v34, v8, 1.0 op_sel:[0,1,0]
	v_cvt_scalef32_pk_f16_fp4 v35, v8, 1.0 op_sel:[1,1,0]
	v_cvt_scalef32_pk_f16_fp4 v36, v9, 1.0
	v_cvt_scalef32_pk_f16_fp4 v37, v9, 1.0 op_sel:[1,0,0]
	v_cvt_scalef32_pk_f16_fp4 v38, v9, 1.0 op_sel:[0,1,0]
	v_cvt_scalef32_pk_f16_fp4 v39, v9, 1.0 op_sel:[1,1,0]
	v_cvt_scalef32_pk_f16_fp4 v40, v10, 1.0
	v_cvt_scalef32_pk_f16_fp4 v41, v10, 1.0 op_sel:[1,0,0]
	v_cvt_scalef32_pk_f16_fp4 v42, v10, 1.0 op_sel:[0,1,0]
	v_cvt_scalef32_pk_f16_fp4 v43, v10, 1.0 op_sel:[1,1,0]
	v_cvt_scalef32_pk_f16_fp4 v44, v11, 1.0
	v_cvt_scalef32_pk_f16_fp4 v45, v11, 1.0 op_sel:[1,0,0]
	v_cvt_scalef32_pk_f16_fp4 v46, v11, 1.0 op_sel:[0,1,0]
	v_cvt_scalef32_pk_f16_fp4 v47, v11, 1.0 op_sel:[1,1,0]
	buffer_load_dwordx4 v[4:7], v[178:179], s[12:15], 0 idxen offen
	v_pk_fma_f16 v74, v32, v186, v74
	v_pk_fma_f16 v73, v33, v186, v73
	v_pk_fma_f16 v71, v34, v186, v71
	v_pk_fma_f16 v70, v35, v186, v70
	v_pk_fma_f16 v69, v36, v186, v69
	v_pk_fma_f16 v68, v37, v186, v68
	v_pk_fma_f16 v63, v38, v186, v63
	v_pk_fma_f16 v62, v39, v186, v62
	v_pk_fma_f16 v61, v40, v186, v61
	v_pk_fma_f16 v60, v41, v186, v60
	v_pk_fma_f16 v59, v42, v186, v59
	v_pk_fma_f16 v58, v43, v186, v58
	v_pk_fma_f16 v57, v44, v186, v57
	v_pk_fma_f16 v56, v45, v186, v56
	v_pk_fma_f16 v75, v46, v186, v75
	v_pk_fma_f16 v72, v47, v186, v72
	ds_read_b32 v182, v115 offset:9768
	ds_read_b32 v185, v115 offset:548
	s_waitcnt vmcnt(6) lgkmcnt(3)
	v_cvt_scalef32_pk_f16_fp4 v32, v12, 1.0
	v_cvt_scalef32_pk_f16_fp4 v33, v12, 1.0 op_sel:[1,0,0]
	v_cvt_scalef32_pk_f16_fp4 v34, v12, 1.0 op_sel:[0,1,0]
	v_cvt_scalef32_pk_f16_fp4 v35, v12, 1.0 op_sel:[1,1,0]
	v_cvt_scalef32_pk_f16_fp4 v36, v13, 1.0
	v_cvt_scalef32_pk_f16_fp4 v37, v13, 1.0 op_sel:[1,0,0]
	v_cvt_scalef32_pk_f16_fp4 v38, v13, 1.0 op_sel:[0,1,0]
	v_cvt_scalef32_pk_f16_fp4 v39, v13, 1.0 op_sel:[1,1,0]
	v_cvt_scalef32_pk_f16_fp4 v40, v14, 1.0
	v_cvt_scalef32_pk_f16_fp4 v41, v14, 1.0 op_sel:[1,0,0]
	v_cvt_scalef32_pk_f16_fp4 v42, v14, 1.0 op_sel:[0,1,0]
	v_cvt_scalef32_pk_f16_fp4 v43, v14, 1.0 op_sel:[1,1,0]
	v_cvt_scalef32_pk_f16_fp4 v44, v15, 1.0
	v_cvt_scalef32_pk_f16_fp4 v45, v15, 1.0 op_sel:[1,0,0]
	v_cvt_scalef32_pk_f16_fp4 v46, v15, 1.0 op_sel:[0,1,0]
	v_cvt_scalef32_pk_f16_fp4 v47, v15, 1.0 op_sel:[1,1,0]
	buffer_load_dwordx4 v[8:11], v[180:181], s[12:15], 0 idxen offen
	v_pk_fma_f16 v162, v32, v187, v162
	v_pk_fma_f16 v161, v33, v187, v161
	v_pk_fma_f16 v160, v34, v187, v160
	v_pk_fma_f16 v159, v35, v187, v159
	v_pk_fma_f16 v158, v36, v187, v158
	v_pk_fma_f16 v157, v37, v187, v157
	v_pk_fma_f16 v156, v38, v187, v156
	v_pk_fma_f16 v147, v39, v187, v147
	v_pk_fma_f16 v146, v40, v187, v146
	v_pk_fma_f16 v145, v41, v187, v145
	v_pk_fma_f16 v144, v42, v187, v144
	v_pk_fma_f16 v143, v43, v187, v143
	v_pk_fma_f16 v142, v44, v187, v142
	v_pk_fma_f16 v141, v45, v187, v141
	v_pk_fma_f16 v149, v46, v187, v149
	v_pk_fma_f16 v148, v47, v187, v148
	ds_read_b32 v176, v115 offset:8236
	ds_read_b32 v186, v115 offset:1060
	s_waitcnt vmcnt(6) lgkmcnt(3)
	v_cvt_scalef32_pk_f16_fp4 v32, v16, 1.0
	v_cvt_scalef32_pk_f16_fp4 v33, v16, 1.0 op_sel:[1,0,0]
	v_cvt_scalef32_pk_f16_fp4 v34, v16, 1.0 op_sel:[0,1,0]
	v_cvt_scalef32_pk_f16_fp4 v35, v16, 1.0 op_sel:[1,1,0]
	v_cvt_scalef32_pk_f16_fp4 v36, v17, 1.0
	v_cvt_scalef32_pk_f16_fp4 v37, v17, 1.0 op_sel:[1,0,0]
	v_cvt_scalef32_pk_f16_fp4 v38, v17, 1.0 op_sel:[0,1,0]
	v_cvt_scalef32_pk_f16_fp4 v39, v17, 1.0 op_sel:[1,1,0]
	v_cvt_scalef32_pk_f16_fp4 v40, v18, 1.0
	v_cvt_scalef32_pk_f16_fp4 v41, v18, 1.0 op_sel:[1,0,0]
	v_cvt_scalef32_pk_f16_fp4 v42, v18, 1.0 op_sel:[0,1,0]
	v_cvt_scalef32_pk_f16_fp4 v43, v18, 1.0 op_sel:[1,1,0]
	v_cvt_scalef32_pk_f16_fp4 v44, v19, 1.0
	v_cvt_scalef32_pk_f16_fp4 v45, v19, 1.0 op_sel:[1,0,0]
	v_cvt_scalef32_pk_f16_fp4 v46, v19, 1.0 op_sel:[0,1,0]
	v_cvt_scalef32_pk_f16_fp4 v47, v19, 1.0 op_sel:[1,1,0]
	buffer_load_dwordx4 v[12:15], v[182:183], s[12:15], 0 idxen offen
	v_pk_fma_f16 v139, v32, v184, v139
	v_pk_fma_f16 v138, v33, v184, v138
	v_pk_fma_f16 v136, v34, v184, v136
	v_pk_fma_f16 v135, v35, v184, v135
	v_pk_fma_f16 v134, v36, v184, v134
	v_pk_fma_f16 v133, v37, v184, v133
	v_pk_fma_f16 v132, v38, v184, v132
	v_pk_fma_f16 v131, v39, v184, v131
	v_pk_fma_f16 v130, v40, v184, v130
	v_pk_fma_f16 v129, v41, v184, v129
	v_pk_fma_f16 v128, v42, v184, v128
	v_pk_fma_f16 v127, v43, v184, v127
	v_pk_fma_f16 v126, v44, v184, v126
	v_pk_fma_f16 v114, v45, v184, v114
	v_pk_fma_f16 v140, v46, v184, v140
	v_pk_fma_f16 v137, v47, v184, v137
	ds_read_b32 v178, v115 offset:8748
	ds_read_b32 v187, v115 offset:1572
	s_waitcnt vmcnt(6) lgkmcnt(3)
	v_cvt_scalef32_pk_f16_fp4 v32, v20, 1.0
	v_cvt_scalef32_pk_f16_fp4 v33, v20, 1.0 op_sel:[1,0,0]
	v_cvt_scalef32_pk_f16_fp4 v34, v20, 1.0 op_sel:[0,1,0]
	v_cvt_scalef32_pk_f16_fp4 v35, v20, 1.0 op_sel:[1,1,0]
	v_cvt_scalef32_pk_f16_fp4 v36, v21, 1.0
	v_cvt_scalef32_pk_f16_fp4 v37, v21, 1.0 op_sel:[1,0,0]
	v_cvt_scalef32_pk_f16_fp4 v38, v21, 1.0 op_sel:[0,1,0]
	v_cvt_scalef32_pk_f16_fp4 v39, v21, 1.0 op_sel:[1,1,0]
	v_cvt_scalef32_pk_f16_fp4 v40, v22, 1.0
	v_cvt_scalef32_pk_f16_fp4 v41, v22, 1.0 op_sel:[1,0,0]
	v_cvt_scalef32_pk_f16_fp4 v42, v22, 1.0 op_sel:[0,1,0]
	v_cvt_scalef32_pk_f16_fp4 v43, v22, 1.0 op_sel:[1,1,0]
	v_cvt_scalef32_pk_f16_fp4 v44, v23, 1.0
	v_cvt_scalef32_pk_f16_fp4 v45, v23, 1.0 op_sel:[1,0,0]
	v_cvt_scalef32_pk_f16_fp4 v46, v23, 1.0 op_sel:[0,1,0]
	v_cvt_scalef32_pk_f16_fp4 v47, v23, 1.0 op_sel:[1,1,0]
	buffer_load_dwordx4 v[16:19], v[176:177], s[12:15], 0 idxen offen
	v_pk_fma_f16 v124, v32, v185, v124
	v_pk_fma_f16 v123, v33, v185, v123
	v_pk_fma_f16 v121, v34, v185, v121
	v_pk_fma_f16 v120, v35, v185, v120
	v_pk_fma_f16 v119, v36, v185, v119
	v_pk_fma_f16 v118, v37, v185, v118
	v_pk_fma_f16 v117, v38, v185, v117
	v_pk_fma_f16 v116, v39, v185, v116
	v_pk_fma_f16 v113, v40, v185, v113
	v_pk_fma_f16 v112, v41, v185, v112
	v_pk_fma_f16 v67, v42, v185, v67
	v_pk_fma_f16 v66, v43, v185, v66
	v_pk_fma_f16 v65, v44, v185, v65
	v_pk_fma_f16 v64, v45, v185, v64
	v_pk_fma_f16 v125, v46, v185, v125
	v_pk_fma_f16 v122, v47, v185, v122
	ds_read_b32 v180, v115 offset:9260
	ds_read_b32 v184, v115 offset:40
	s_waitcnt vmcnt(6) lgkmcnt(3)
	v_cvt_scalef32_pk_f16_fp4 v32, v24, 1.0
	v_cvt_scalef32_pk_f16_fp4 v33, v24, 1.0 op_sel:[1,0,0]
	v_cvt_scalef32_pk_f16_fp4 v34, v24, 1.0 op_sel:[0,1,0]
	v_cvt_scalef32_pk_f16_fp4 v35, v24, 1.0 op_sel:[1,1,0]
	v_cvt_scalef32_pk_f16_fp4 v36, v25, 1.0
	v_cvt_scalef32_pk_f16_fp4 v37, v25, 1.0 op_sel:[1,0,0]
	v_cvt_scalef32_pk_f16_fp4 v38, v25, 1.0 op_sel:[0,1,0]
	v_cvt_scalef32_pk_f16_fp4 v39, v25, 1.0 op_sel:[1,1,0]
	v_cvt_scalef32_pk_f16_fp4 v40, v26, 1.0
	v_cvt_scalef32_pk_f16_fp4 v41, v26, 1.0 op_sel:[1,0,0]
	v_cvt_scalef32_pk_f16_fp4 v42, v26, 1.0 op_sel:[0,1,0]
	v_cvt_scalef32_pk_f16_fp4 v43, v26, 1.0 op_sel:[1,1,0]
	v_cvt_scalef32_pk_f16_fp4 v44, v27, 1.0
	v_cvt_scalef32_pk_f16_fp4 v45, v27, 1.0 op_sel:[1,0,0]
	v_cvt_scalef32_pk_f16_fp4 v46, v27, 1.0 op_sel:[0,1,0]
	v_cvt_scalef32_pk_f16_fp4 v47, v27, 1.0 op_sel:[1,1,0]
	buffer_load_dwordx4 v[20:23], v[178:179], s[12:15], 0 idxen offen
	v_pk_fma_f16 v74, v32, v186, v74
	v_pk_fma_f16 v73, v33, v186, v73
	v_pk_fma_f16 v71, v34, v186, v71
	v_pk_fma_f16 v70, v35, v186, v70
	v_pk_fma_f16 v69, v36, v186, v69
	v_pk_fma_f16 v68, v37, v186, v68
	v_pk_fma_f16 v63, v38, v186, v63
	v_pk_fma_f16 v62, v39, v186, v62
	v_pk_fma_f16 v61, v40, v186, v61
	v_pk_fma_f16 v60, v41, v186, v60
	v_pk_fma_f16 v59, v42, v186, v59
	v_pk_fma_f16 v58, v43, v186, v58
	v_pk_fma_f16 v57, v44, v186, v57
	v_pk_fma_f16 v56, v45, v186, v56
	v_pk_fma_f16 v75, v46, v186, v75
	v_pk_fma_f16 v72, v47, v186, v72
	ds_read_b32 v182, v115 offset:9772
	ds_read_b32 v185, v115 offset:552
	s_waitcnt vmcnt(6) lgkmcnt(3)
	v_cvt_scalef32_pk_f16_fp4 v32, v28, 1.0
	v_cvt_scalef32_pk_f16_fp4 v33, v28, 1.0 op_sel:[1,0,0]
	v_cvt_scalef32_pk_f16_fp4 v34, v28, 1.0 op_sel:[0,1,0]
	v_cvt_scalef32_pk_f16_fp4 v35, v28, 1.0 op_sel:[1,1,0]
	v_cvt_scalef32_pk_f16_fp4 v36, v29, 1.0
	v_cvt_scalef32_pk_f16_fp4 v37, v29, 1.0 op_sel:[1,0,0]
	v_cvt_scalef32_pk_f16_fp4 v38, v29, 1.0 op_sel:[0,1,0]
	v_cvt_scalef32_pk_f16_fp4 v39, v29, 1.0 op_sel:[1,1,0]
	v_cvt_scalef32_pk_f16_fp4 v40, v30, 1.0
	v_cvt_scalef32_pk_f16_fp4 v41, v30, 1.0 op_sel:[1,0,0]
	v_cvt_scalef32_pk_f16_fp4 v42, v30, 1.0 op_sel:[0,1,0]
	v_cvt_scalef32_pk_f16_fp4 v43, v30, 1.0 op_sel:[1,1,0]
	v_cvt_scalef32_pk_f16_fp4 v44, v31, 1.0
	v_cvt_scalef32_pk_f16_fp4 v45, v31, 1.0 op_sel:[1,0,0]
	v_cvt_scalef32_pk_f16_fp4 v46, v31, 1.0 op_sel:[0,1,0]
	v_cvt_scalef32_pk_f16_fp4 v47, v31, 1.0 op_sel:[1,1,0]
	buffer_load_dwordx4 v[24:27], v[180:181], s[12:15], 0 idxen offen
	v_pk_fma_f16 v162, v32, v187, v162
	v_pk_fma_f16 v161, v33, v187, v161
	v_pk_fma_f16 v160, v34, v187, v160
	v_pk_fma_f16 v159, v35, v187, v159
	v_pk_fma_f16 v158, v36, v187, v158
	v_pk_fma_f16 v157, v37, v187, v157
	v_pk_fma_f16 v156, v38, v187, v156
	v_pk_fma_f16 v147, v39, v187, v147
	v_pk_fma_f16 v146, v40, v187, v146
	v_pk_fma_f16 v145, v41, v187, v145
	v_pk_fma_f16 v144, v42, v187, v144
	v_pk_fma_f16 v143, v43, v187, v143
	v_pk_fma_f16 v142, v44, v187, v142
	v_pk_fma_f16 v141, v45, v187, v141
	v_pk_fma_f16 v149, v46, v187, v149
	v_pk_fma_f16 v148, v47, v187, v148
	ds_read_b32 v176, v115 offset:8240
	ds_read_b32 v186, v115 offset:1064
	s_waitcnt vmcnt(6) lgkmcnt(3)
	v_cvt_scalef32_pk_f16_fp4 v32, v0, 1.0
	v_cvt_scalef32_pk_f16_fp4 v33, v0, 1.0 op_sel:[1,0,0]
	v_cvt_scalef32_pk_f16_fp4 v34, v0, 1.0 op_sel:[0,1,0]
	v_cvt_scalef32_pk_f16_fp4 v35, v0, 1.0 op_sel:[1,1,0]
	v_cvt_scalef32_pk_f16_fp4 v36, v1, 1.0
	v_cvt_scalef32_pk_f16_fp4 v37, v1, 1.0 op_sel:[1,0,0]
	v_cvt_scalef32_pk_f16_fp4 v38, v1, 1.0 op_sel:[0,1,0]
	v_cvt_scalef32_pk_f16_fp4 v39, v1, 1.0 op_sel:[1,1,0]
	v_cvt_scalef32_pk_f16_fp4 v40, v2, 1.0
	v_cvt_scalef32_pk_f16_fp4 v41, v2, 1.0 op_sel:[1,0,0]
	v_cvt_scalef32_pk_f16_fp4 v42, v2, 1.0 op_sel:[0,1,0]
	v_cvt_scalef32_pk_f16_fp4 v43, v2, 1.0 op_sel:[1,1,0]
	v_cvt_scalef32_pk_f16_fp4 v44, v3, 1.0
	v_cvt_scalef32_pk_f16_fp4 v45, v3, 1.0 op_sel:[1,0,0]
	v_cvt_scalef32_pk_f16_fp4 v46, v3, 1.0 op_sel:[0,1,0]
	v_cvt_scalef32_pk_f16_fp4 v47, v3, 1.0 op_sel:[1,1,0]
	buffer_load_dwordx4 v[28:31], v[182:183], s[12:15], 0 idxen offen
	v_pk_fma_f16 v139, v32, v184, v139
	v_pk_fma_f16 v138, v33, v184, v138
	v_pk_fma_f16 v136, v34, v184, v136
	v_pk_fma_f16 v135, v35, v184, v135
	v_pk_fma_f16 v134, v36, v184, v134
	v_pk_fma_f16 v133, v37, v184, v133
	v_pk_fma_f16 v132, v38, v184, v132
	v_pk_fma_f16 v131, v39, v184, v131
	v_pk_fma_f16 v130, v40, v184, v130
	v_pk_fma_f16 v129, v41, v184, v129
	v_pk_fma_f16 v128, v42, v184, v128
	v_pk_fma_f16 v127, v43, v184, v127
	v_pk_fma_f16 v126, v44, v184, v126
	v_pk_fma_f16 v114, v45, v184, v114
	v_pk_fma_f16 v140, v46, v184, v140
	v_pk_fma_f16 v137, v47, v184, v137
	ds_read_b32 v178, v115 offset:8752
	ds_read_b32 v187, v115 offset:1576
	s_waitcnt vmcnt(6) lgkmcnt(3)
	v_cvt_scalef32_pk_f16_fp4 v32, v4, 1.0
	v_cvt_scalef32_pk_f16_fp4 v33, v4, 1.0 op_sel:[1,0,0]
	v_cvt_scalef32_pk_f16_fp4 v34, v4, 1.0 op_sel:[0,1,0]
	v_cvt_scalef32_pk_f16_fp4 v35, v4, 1.0 op_sel:[1,1,0]
	v_cvt_scalef32_pk_f16_fp4 v36, v5, 1.0
	v_cvt_scalef32_pk_f16_fp4 v37, v5, 1.0 op_sel:[1,0,0]
	v_cvt_scalef32_pk_f16_fp4 v38, v5, 1.0 op_sel:[0,1,0]
	v_cvt_scalef32_pk_f16_fp4 v39, v5, 1.0 op_sel:[1,1,0]
	v_cvt_scalef32_pk_f16_fp4 v40, v6, 1.0
	v_cvt_scalef32_pk_f16_fp4 v41, v6, 1.0 op_sel:[1,0,0]
	v_cvt_scalef32_pk_f16_fp4 v42, v6, 1.0 op_sel:[0,1,0]
	v_cvt_scalef32_pk_f16_fp4 v43, v6, 1.0 op_sel:[1,1,0]
	v_cvt_scalef32_pk_f16_fp4 v44, v7, 1.0
	v_cvt_scalef32_pk_f16_fp4 v45, v7, 1.0 op_sel:[1,0,0]
	v_cvt_scalef32_pk_f16_fp4 v46, v7, 1.0 op_sel:[0,1,0]
	v_cvt_scalef32_pk_f16_fp4 v47, v7, 1.0 op_sel:[1,1,0]
	buffer_load_dwordx4 v[0:3], v[176:177], s[12:15], 0 idxen offen
	v_pk_fma_f16 v124, v32, v185, v124
	v_pk_fma_f16 v123, v33, v185, v123
	v_pk_fma_f16 v121, v34, v185, v121
	v_pk_fma_f16 v120, v35, v185, v120
	v_pk_fma_f16 v119, v36, v185, v119
	v_pk_fma_f16 v118, v37, v185, v118
	v_pk_fma_f16 v117, v38, v185, v117
	v_pk_fma_f16 v116, v39, v185, v116
	v_pk_fma_f16 v113, v40, v185, v113
	v_pk_fma_f16 v112, v41, v185, v112
	v_pk_fma_f16 v67, v42, v185, v67
	v_pk_fma_f16 v66, v43, v185, v66
	v_pk_fma_f16 v65, v44, v185, v65
	v_pk_fma_f16 v64, v45, v185, v64
	v_pk_fma_f16 v125, v46, v185, v125
	v_pk_fma_f16 v122, v47, v185, v122
	ds_read_b32 v180, v115 offset:9264
	ds_read_b32 v184, v115 offset:44
	s_waitcnt vmcnt(6) lgkmcnt(3)
	v_cvt_scalef32_pk_f16_fp4 v32, v8, 1.0
	v_cvt_scalef32_pk_f16_fp4 v33, v8, 1.0 op_sel:[1,0,0]
	v_cvt_scalef32_pk_f16_fp4 v34, v8, 1.0 op_sel:[0,1,0]
	v_cvt_scalef32_pk_f16_fp4 v35, v8, 1.0 op_sel:[1,1,0]
	v_cvt_scalef32_pk_f16_fp4 v36, v9, 1.0
	v_cvt_scalef32_pk_f16_fp4 v37, v9, 1.0 op_sel:[1,0,0]
	v_cvt_scalef32_pk_f16_fp4 v38, v9, 1.0 op_sel:[0,1,0]
	v_cvt_scalef32_pk_f16_fp4 v39, v9, 1.0 op_sel:[1,1,0]
	v_cvt_scalef32_pk_f16_fp4 v40, v10, 1.0
	v_cvt_scalef32_pk_f16_fp4 v41, v10, 1.0 op_sel:[1,0,0]
	v_cvt_scalef32_pk_f16_fp4 v42, v10, 1.0 op_sel:[0,1,0]
	v_cvt_scalef32_pk_f16_fp4 v43, v10, 1.0 op_sel:[1,1,0]
	v_cvt_scalef32_pk_f16_fp4 v44, v11, 1.0
	v_cvt_scalef32_pk_f16_fp4 v45, v11, 1.0 op_sel:[1,0,0]
	v_cvt_scalef32_pk_f16_fp4 v46, v11, 1.0 op_sel:[0,1,0]
	v_cvt_scalef32_pk_f16_fp4 v47, v11, 1.0 op_sel:[1,1,0]
	buffer_load_dwordx4 v[4:7], v[178:179], s[12:15], 0 idxen offen
	v_pk_fma_f16 v74, v32, v186, v74
	v_pk_fma_f16 v73, v33, v186, v73
	v_pk_fma_f16 v71, v34, v186, v71
	v_pk_fma_f16 v70, v35, v186, v70
	v_pk_fma_f16 v69, v36, v186, v69
	v_pk_fma_f16 v68, v37, v186, v68
	v_pk_fma_f16 v63, v38, v186, v63
	v_pk_fma_f16 v62, v39, v186, v62
	v_pk_fma_f16 v61, v40, v186, v61
	v_pk_fma_f16 v60, v41, v186, v60
	v_pk_fma_f16 v59, v42, v186, v59
	v_pk_fma_f16 v58, v43, v186, v58
	v_pk_fma_f16 v57, v44, v186, v57
	v_pk_fma_f16 v56, v45, v186, v56
	v_pk_fma_f16 v75, v46, v186, v75
	v_pk_fma_f16 v72, v47, v186, v72
	ds_read_b32 v182, v115 offset:9776
	ds_read_b32 v185, v115 offset:556
	s_waitcnt vmcnt(6) lgkmcnt(3)
	v_cvt_scalef32_pk_f16_fp4 v32, v12, 1.0
	v_cvt_scalef32_pk_f16_fp4 v33, v12, 1.0 op_sel:[1,0,0]
	v_cvt_scalef32_pk_f16_fp4 v34, v12, 1.0 op_sel:[0,1,0]
	v_cvt_scalef32_pk_f16_fp4 v35, v12, 1.0 op_sel:[1,1,0]
	v_cvt_scalef32_pk_f16_fp4 v36, v13, 1.0
	v_cvt_scalef32_pk_f16_fp4 v37, v13, 1.0 op_sel:[1,0,0]
	v_cvt_scalef32_pk_f16_fp4 v38, v13, 1.0 op_sel:[0,1,0]
	v_cvt_scalef32_pk_f16_fp4 v39, v13, 1.0 op_sel:[1,1,0]
	v_cvt_scalef32_pk_f16_fp4 v40, v14, 1.0
	v_cvt_scalef32_pk_f16_fp4 v41, v14, 1.0 op_sel:[1,0,0]
	v_cvt_scalef32_pk_f16_fp4 v42, v14, 1.0 op_sel:[0,1,0]
	v_cvt_scalef32_pk_f16_fp4 v43, v14, 1.0 op_sel:[1,1,0]
	v_cvt_scalef32_pk_f16_fp4 v44, v15, 1.0
	v_cvt_scalef32_pk_f16_fp4 v45, v15, 1.0 op_sel:[1,0,0]
	v_cvt_scalef32_pk_f16_fp4 v46, v15, 1.0 op_sel:[0,1,0]
	v_cvt_scalef32_pk_f16_fp4 v47, v15, 1.0 op_sel:[1,1,0]
	buffer_load_dwordx4 v[8:11], v[180:181], s[12:15], 0 idxen offen
	v_pk_fma_f16 v162, v32, v187, v162
	v_pk_fma_f16 v161, v33, v187, v161
	v_pk_fma_f16 v160, v34, v187, v160
	v_pk_fma_f16 v159, v35, v187, v159
	v_pk_fma_f16 v158, v36, v187, v158
	v_pk_fma_f16 v157, v37, v187, v157
	v_pk_fma_f16 v156, v38, v187, v156
	v_pk_fma_f16 v147, v39, v187, v147
	v_pk_fma_f16 v146, v40, v187, v146
	v_pk_fma_f16 v145, v41, v187, v145
	v_pk_fma_f16 v144, v42, v187, v144
	v_pk_fma_f16 v143, v43, v187, v143
	v_pk_fma_f16 v142, v44, v187, v142
	v_pk_fma_f16 v141, v45, v187, v141
	v_pk_fma_f16 v149, v46, v187, v149
	v_pk_fma_f16 v148, v47, v187, v148
	ds_read_b32 v176, v115 offset:8244
	ds_read_b32 v186, v115 offset:1068
	s_waitcnt vmcnt(6) lgkmcnt(3)
	v_cvt_scalef32_pk_f16_fp4 v32, v16, 1.0
	v_cvt_scalef32_pk_f16_fp4 v33, v16, 1.0 op_sel:[1,0,0]
	v_cvt_scalef32_pk_f16_fp4 v34, v16, 1.0 op_sel:[0,1,0]
	v_cvt_scalef32_pk_f16_fp4 v35, v16, 1.0 op_sel:[1,1,0]
	v_cvt_scalef32_pk_f16_fp4 v36, v17, 1.0
	v_cvt_scalef32_pk_f16_fp4 v37, v17, 1.0 op_sel:[1,0,0]
	v_cvt_scalef32_pk_f16_fp4 v38, v17, 1.0 op_sel:[0,1,0]
	v_cvt_scalef32_pk_f16_fp4 v39, v17, 1.0 op_sel:[1,1,0]
	v_cvt_scalef32_pk_f16_fp4 v40, v18, 1.0
	v_cvt_scalef32_pk_f16_fp4 v41, v18, 1.0 op_sel:[1,0,0]
	v_cvt_scalef32_pk_f16_fp4 v42, v18, 1.0 op_sel:[0,1,0]
	v_cvt_scalef32_pk_f16_fp4 v43, v18, 1.0 op_sel:[1,1,0]
	v_cvt_scalef32_pk_f16_fp4 v44, v19, 1.0
	v_cvt_scalef32_pk_f16_fp4 v45, v19, 1.0 op_sel:[1,0,0]
	v_cvt_scalef32_pk_f16_fp4 v46, v19, 1.0 op_sel:[0,1,0]
	v_cvt_scalef32_pk_f16_fp4 v47, v19, 1.0 op_sel:[1,1,0]
	buffer_load_dwordx4 v[12:15], v[182:183], s[12:15], 0 idxen offen
	v_pk_fma_f16 v139, v32, v184, v139
	v_pk_fma_f16 v138, v33, v184, v138
	v_pk_fma_f16 v136, v34, v184, v136
	v_pk_fma_f16 v135, v35, v184, v135
	v_pk_fma_f16 v134, v36, v184, v134
	v_pk_fma_f16 v133, v37, v184, v133
	v_pk_fma_f16 v132, v38, v184, v132
	v_pk_fma_f16 v131, v39, v184, v131
	v_pk_fma_f16 v130, v40, v184, v130
	v_pk_fma_f16 v129, v41, v184, v129
	v_pk_fma_f16 v128, v42, v184, v128
	v_pk_fma_f16 v127, v43, v184, v127
	v_pk_fma_f16 v126, v44, v184, v126
	v_pk_fma_f16 v114, v45, v184, v114
	v_pk_fma_f16 v140, v46, v184, v140
	v_pk_fma_f16 v137, v47, v184, v137
	ds_read_b32 v178, v115 offset:8756
	ds_read_b32 v187, v115 offset:1580
	s_waitcnt vmcnt(6) lgkmcnt(3)
	v_cvt_scalef32_pk_f16_fp4 v32, v20, 1.0
	v_cvt_scalef32_pk_f16_fp4 v33, v20, 1.0 op_sel:[1,0,0]
	v_cvt_scalef32_pk_f16_fp4 v34, v20, 1.0 op_sel:[0,1,0]
	v_cvt_scalef32_pk_f16_fp4 v35, v20, 1.0 op_sel:[1,1,0]
	v_cvt_scalef32_pk_f16_fp4 v36, v21, 1.0
	v_cvt_scalef32_pk_f16_fp4 v37, v21, 1.0 op_sel:[1,0,0]
	v_cvt_scalef32_pk_f16_fp4 v38, v21, 1.0 op_sel:[0,1,0]
	v_cvt_scalef32_pk_f16_fp4 v39, v21, 1.0 op_sel:[1,1,0]
	v_cvt_scalef32_pk_f16_fp4 v40, v22, 1.0
	v_cvt_scalef32_pk_f16_fp4 v41, v22, 1.0 op_sel:[1,0,0]
	v_cvt_scalef32_pk_f16_fp4 v42, v22, 1.0 op_sel:[0,1,0]
	v_cvt_scalef32_pk_f16_fp4 v43, v22, 1.0 op_sel:[1,1,0]
	v_cvt_scalef32_pk_f16_fp4 v44, v23, 1.0
	v_cvt_scalef32_pk_f16_fp4 v45, v23, 1.0 op_sel:[1,0,0]
	v_cvt_scalef32_pk_f16_fp4 v46, v23, 1.0 op_sel:[0,1,0]
	v_cvt_scalef32_pk_f16_fp4 v47, v23, 1.0 op_sel:[1,1,0]
	buffer_load_dwordx4 v[16:19], v[176:177], s[12:15], 0 idxen offen
	v_pk_fma_f16 v124, v32, v185, v124
	v_pk_fma_f16 v123, v33, v185, v123
	v_pk_fma_f16 v121, v34, v185, v121
	v_pk_fma_f16 v120, v35, v185, v120
	v_pk_fma_f16 v119, v36, v185, v119
	v_pk_fma_f16 v118, v37, v185, v118
	v_pk_fma_f16 v117, v38, v185, v117
	v_pk_fma_f16 v116, v39, v185, v116
	v_pk_fma_f16 v113, v40, v185, v113
	v_pk_fma_f16 v112, v41, v185, v112
	v_pk_fma_f16 v67, v42, v185, v67
	v_pk_fma_f16 v66, v43, v185, v66
	v_pk_fma_f16 v65, v44, v185, v65
	v_pk_fma_f16 v64, v45, v185, v64
	v_pk_fma_f16 v125, v46, v185, v125
	v_pk_fma_f16 v122, v47, v185, v122
	ds_read_b32 v180, v115 offset:9268
	ds_read_b32 v184, v115 offset:48
	s_waitcnt vmcnt(6) lgkmcnt(3)
	v_cvt_scalef32_pk_f16_fp4 v32, v24, 1.0
	v_cvt_scalef32_pk_f16_fp4 v33, v24, 1.0 op_sel:[1,0,0]
	v_cvt_scalef32_pk_f16_fp4 v34, v24, 1.0 op_sel:[0,1,0]
	v_cvt_scalef32_pk_f16_fp4 v35, v24, 1.0 op_sel:[1,1,0]
	v_cvt_scalef32_pk_f16_fp4 v36, v25, 1.0
	v_cvt_scalef32_pk_f16_fp4 v37, v25, 1.0 op_sel:[1,0,0]
	v_cvt_scalef32_pk_f16_fp4 v38, v25, 1.0 op_sel:[0,1,0]
	v_cvt_scalef32_pk_f16_fp4 v39, v25, 1.0 op_sel:[1,1,0]
	v_cvt_scalef32_pk_f16_fp4 v40, v26, 1.0
	v_cvt_scalef32_pk_f16_fp4 v41, v26, 1.0 op_sel:[1,0,0]
	v_cvt_scalef32_pk_f16_fp4 v42, v26, 1.0 op_sel:[0,1,0]
	v_cvt_scalef32_pk_f16_fp4 v43, v26, 1.0 op_sel:[1,1,0]
	v_cvt_scalef32_pk_f16_fp4 v44, v27, 1.0
	v_cvt_scalef32_pk_f16_fp4 v45, v27, 1.0 op_sel:[1,0,0]
	v_cvt_scalef32_pk_f16_fp4 v46, v27, 1.0 op_sel:[0,1,0]
	v_cvt_scalef32_pk_f16_fp4 v47, v27, 1.0 op_sel:[1,1,0]
	buffer_load_dwordx4 v[20:23], v[178:179], s[12:15], 0 idxen offen
	v_pk_fma_f16 v74, v32, v186, v74
	v_pk_fma_f16 v73, v33, v186, v73
	v_pk_fma_f16 v71, v34, v186, v71
	v_pk_fma_f16 v70, v35, v186, v70
	v_pk_fma_f16 v69, v36, v186, v69
	v_pk_fma_f16 v68, v37, v186, v68
	v_pk_fma_f16 v63, v38, v186, v63
	v_pk_fma_f16 v62, v39, v186, v62
	v_pk_fma_f16 v61, v40, v186, v61
	v_pk_fma_f16 v60, v41, v186, v60
	v_pk_fma_f16 v59, v42, v186, v59
	v_pk_fma_f16 v58, v43, v186, v58
	v_pk_fma_f16 v57, v44, v186, v57
	v_pk_fma_f16 v56, v45, v186, v56
	v_pk_fma_f16 v75, v46, v186, v75
	v_pk_fma_f16 v72, v47, v186, v72
	ds_read_b32 v182, v115 offset:9780
	ds_read_b32 v185, v115 offset:560
	s_waitcnt vmcnt(6) lgkmcnt(3)
	v_cvt_scalef32_pk_f16_fp4 v32, v28, 1.0
	v_cvt_scalef32_pk_f16_fp4 v33, v28, 1.0 op_sel:[1,0,0]
	v_cvt_scalef32_pk_f16_fp4 v34, v28, 1.0 op_sel:[0,1,0]
	v_cvt_scalef32_pk_f16_fp4 v35, v28, 1.0 op_sel:[1,1,0]
	v_cvt_scalef32_pk_f16_fp4 v36, v29, 1.0
	v_cvt_scalef32_pk_f16_fp4 v37, v29, 1.0 op_sel:[1,0,0]
	v_cvt_scalef32_pk_f16_fp4 v38, v29, 1.0 op_sel:[0,1,0]
	v_cvt_scalef32_pk_f16_fp4 v39, v29, 1.0 op_sel:[1,1,0]
	v_cvt_scalef32_pk_f16_fp4 v40, v30, 1.0
	v_cvt_scalef32_pk_f16_fp4 v41, v30, 1.0 op_sel:[1,0,0]
	v_cvt_scalef32_pk_f16_fp4 v42, v30, 1.0 op_sel:[0,1,0]
	v_cvt_scalef32_pk_f16_fp4 v43, v30, 1.0 op_sel:[1,1,0]
	v_cvt_scalef32_pk_f16_fp4 v44, v31, 1.0
	v_cvt_scalef32_pk_f16_fp4 v45, v31, 1.0 op_sel:[1,0,0]
	v_cvt_scalef32_pk_f16_fp4 v46, v31, 1.0 op_sel:[0,1,0]
	v_cvt_scalef32_pk_f16_fp4 v47, v31, 1.0 op_sel:[1,1,0]
	buffer_load_dwordx4 v[24:27], v[180:181], s[12:15], 0 idxen offen
	v_pk_fma_f16 v162, v32, v187, v162
	v_pk_fma_f16 v161, v33, v187, v161
	v_pk_fma_f16 v160, v34, v187, v160
	v_pk_fma_f16 v159, v35, v187, v159
	v_pk_fma_f16 v158, v36, v187, v158
	v_pk_fma_f16 v157, v37, v187, v157
	v_pk_fma_f16 v156, v38, v187, v156
	v_pk_fma_f16 v147, v39, v187, v147
	v_pk_fma_f16 v146, v40, v187, v146
	v_pk_fma_f16 v145, v41, v187, v145
	v_pk_fma_f16 v144, v42, v187, v144
	v_pk_fma_f16 v143, v43, v187, v143
	v_pk_fma_f16 v142, v44, v187, v142
	v_pk_fma_f16 v141, v45, v187, v141
	v_pk_fma_f16 v149, v46, v187, v149
	v_pk_fma_f16 v148, v47, v187, v148
	ds_read_b32 v176, v115 offset:8248
	ds_read_b32 v186, v115 offset:1072
	s_waitcnt vmcnt(6) lgkmcnt(3)
	v_cvt_scalef32_pk_f16_fp4 v32, v0, 1.0
	v_cvt_scalef32_pk_f16_fp4 v33, v0, 1.0 op_sel:[1,0,0]
	v_cvt_scalef32_pk_f16_fp4 v34, v0, 1.0 op_sel:[0,1,0]
	v_cvt_scalef32_pk_f16_fp4 v35, v0, 1.0 op_sel:[1,1,0]
	v_cvt_scalef32_pk_f16_fp4 v36, v1, 1.0
	v_cvt_scalef32_pk_f16_fp4 v37, v1, 1.0 op_sel:[1,0,0]
	v_cvt_scalef32_pk_f16_fp4 v38, v1, 1.0 op_sel:[0,1,0]
	v_cvt_scalef32_pk_f16_fp4 v39, v1, 1.0 op_sel:[1,1,0]
	v_cvt_scalef32_pk_f16_fp4 v40, v2, 1.0
	v_cvt_scalef32_pk_f16_fp4 v41, v2, 1.0 op_sel:[1,0,0]
	v_cvt_scalef32_pk_f16_fp4 v42, v2, 1.0 op_sel:[0,1,0]
	v_cvt_scalef32_pk_f16_fp4 v43, v2, 1.0 op_sel:[1,1,0]
	v_cvt_scalef32_pk_f16_fp4 v44, v3, 1.0
	v_cvt_scalef32_pk_f16_fp4 v45, v3, 1.0 op_sel:[1,0,0]
	v_cvt_scalef32_pk_f16_fp4 v46, v3, 1.0 op_sel:[0,1,0]
	v_cvt_scalef32_pk_f16_fp4 v47, v3, 1.0 op_sel:[1,1,0]
	buffer_load_dwordx4 v[28:31], v[182:183], s[12:15], 0 idxen offen
	v_pk_fma_f16 v139, v32, v184, v139
	v_pk_fma_f16 v138, v33, v184, v138
	v_pk_fma_f16 v136, v34, v184, v136
	v_pk_fma_f16 v135, v35, v184, v135
	v_pk_fma_f16 v134, v36, v184, v134
	v_pk_fma_f16 v133, v37, v184, v133
	v_pk_fma_f16 v132, v38, v184, v132
	v_pk_fma_f16 v131, v39, v184, v131
	v_pk_fma_f16 v130, v40, v184, v130
	v_pk_fma_f16 v129, v41, v184, v129
	v_pk_fma_f16 v128, v42, v184, v128
	v_pk_fma_f16 v127, v43, v184, v127
	v_pk_fma_f16 v126, v44, v184, v126
	v_pk_fma_f16 v114, v45, v184, v114
	v_pk_fma_f16 v140, v46, v184, v140
	v_pk_fma_f16 v137, v47, v184, v137
	ds_read_b32 v178, v115 offset:8760
	ds_read_b32 v187, v115 offset:1584
	s_waitcnt vmcnt(6) lgkmcnt(3)
	v_cvt_scalef32_pk_f16_fp4 v32, v4, 1.0
	v_cvt_scalef32_pk_f16_fp4 v33, v4, 1.0 op_sel:[1,0,0]
	v_cvt_scalef32_pk_f16_fp4 v34, v4, 1.0 op_sel:[0,1,0]
	v_cvt_scalef32_pk_f16_fp4 v35, v4, 1.0 op_sel:[1,1,0]
	v_cvt_scalef32_pk_f16_fp4 v36, v5, 1.0
	v_cvt_scalef32_pk_f16_fp4 v37, v5, 1.0 op_sel:[1,0,0]
	v_cvt_scalef32_pk_f16_fp4 v38, v5, 1.0 op_sel:[0,1,0]
	v_cvt_scalef32_pk_f16_fp4 v39, v5, 1.0 op_sel:[1,1,0]
	v_cvt_scalef32_pk_f16_fp4 v40, v6, 1.0
	v_cvt_scalef32_pk_f16_fp4 v41, v6, 1.0 op_sel:[1,0,0]
	v_cvt_scalef32_pk_f16_fp4 v42, v6, 1.0 op_sel:[0,1,0]
	v_cvt_scalef32_pk_f16_fp4 v43, v6, 1.0 op_sel:[1,1,0]
	v_cvt_scalef32_pk_f16_fp4 v44, v7, 1.0
	v_cvt_scalef32_pk_f16_fp4 v45, v7, 1.0 op_sel:[1,0,0]
	v_cvt_scalef32_pk_f16_fp4 v46, v7, 1.0 op_sel:[0,1,0]
	v_cvt_scalef32_pk_f16_fp4 v47, v7, 1.0 op_sel:[1,1,0]
	buffer_load_dwordx4 v[0:3], v[176:177], s[12:15], 0 idxen offen
	v_pk_fma_f16 v124, v32, v185, v124
	v_pk_fma_f16 v123, v33, v185, v123
	v_pk_fma_f16 v121, v34, v185, v121
	v_pk_fma_f16 v120, v35, v185, v120
	v_pk_fma_f16 v119, v36, v185, v119
	v_pk_fma_f16 v118, v37, v185, v118
	v_pk_fma_f16 v117, v38, v185, v117
	v_pk_fma_f16 v116, v39, v185, v116
	v_pk_fma_f16 v113, v40, v185, v113
	v_pk_fma_f16 v112, v41, v185, v112
	v_pk_fma_f16 v67, v42, v185, v67
	v_pk_fma_f16 v66, v43, v185, v66
	v_pk_fma_f16 v65, v44, v185, v65
	v_pk_fma_f16 v64, v45, v185, v64
	v_pk_fma_f16 v125, v46, v185, v125
	v_pk_fma_f16 v122, v47, v185, v122
	ds_read_b32 v180, v115 offset:9272
	ds_read_b32 v184, v115 offset:52
	s_waitcnt vmcnt(6) lgkmcnt(3)
	v_cvt_scalef32_pk_f16_fp4 v32, v8, 1.0
	v_cvt_scalef32_pk_f16_fp4 v33, v8, 1.0 op_sel:[1,0,0]
	v_cvt_scalef32_pk_f16_fp4 v34, v8, 1.0 op_sel:[0,1,0]
	v_cvt_scalef32_pk_f16_fp4 v35, v8, 1.0 op_sel:[1,1,0]
	v_cvt_scalef32_pk_f16_fp4 v36, v9, 1.0
	v_cvt_scalef32_pk_f16_fp4 v37, v9, 1.0 op_sel:[1,0,0]
	v_cvt_scalef32_pk_f16_fp4 v38, v9, 1.0 op_sel:[0,1,0]
	v_cvt_scalef32_pk_f16_fp4 v39, v9, 1.0 op_sel:[1,1,0]
	v_cvt_scalef32_pk_f16_fp4 v40, v10, 1.0
	v_cvt_scalef32_pk_f16_fp4 v41, v10, 1.0 op_sel:[1,0,0]
	v_cvt_scalef32_pk_f16_fp4 v42, v10, 1.0 op_sel:[0,1,0]
	v_cvt_scalef32_pk_f16_fp4 v43, v10, 1.0 op_sel:[1,1,0]
	v_cvt_scalef32_pk_f16_fp4 v44, v11, 1.0
	v_cvt_scalef32_pk_f16_fp4 v45, v11, 1.0 op_sel:[1,0,0]
	v_cvt_scalef32_pk_f16_fp4 v46, v11, 1.0 op_sel:[0,1,0]
	v_cvt_scalef32_pk_f16_fp4 v47, v11, 1.0 op_sel:[1,1,0]
	buffer_load_dwordx4 v[4:7], v[178:179], s[12:15], 0 idxen offen
	v_pk_fma_f16 v74, v32, v186, v74
	v_pk_fma_f16 v73, v33, v186, v73
	v_pk_fma_f16 v71, v34, v186, v71
	v_pk_fma_f16 v70, v35, v186, v70
	v_pk_fma_f16 v69, v36, v186, v69
	v_pk_fma_f16 v68, v37, v186, v68
	v_pk_fma_f16 v63, v38, v186, v63
	v_pk_fma_f16 v62, v39, v186, v62
	v_pk_fma_f16 v61, v40, v186, v61
	v_pk_fma_f16 v60, v41, v186, v60
	v_pk_fma_f16 v59, v42, v186, v59
	v_pk_fma_f16 v58, v43, v186, v58
	v_pk_fma_f16 v57, v44, v186, v57
	v_pk_fma_f16 v56, v45, v186, v56
	v_pk_fma_f16 v75, v46, v186, v75
	v_pk_fma_f16 v72, v47, v186, v72
	ds_read_b32 v182, v115 offset:9784
	ds_read_b32 v185, v115 offset:564
	s_waitcnt vmcnt(6) lgkmcnt(3)
	v_cvt_scalef32_pk_f16_fp4 v32, v12, 1.0
	v_cvt_scalef32_pk_f16_fp4 v33, v12, 1.0 op_sel:[1,0,0]
	v_cvt_scalef32_pk_f16_fp4 v34, v12, 1.0 op_sel:[0,1,0]
	v_cvt_scalef32_pk_f16_fp4 v35, v12, 1.0 op_sel:[1,1,0]
	v_cvt_scalef32_pk_f16_fp4 v36, v13, 1.0
	v_cvt_scalef32_pk_f16_fp4 v37, v13, 1.0 op_sel:[1,0,0]
	v_cvt_scalef32_pk_f16_fp4 v38, v13, 1.0 op_sel:[0,1,0]
	v_cvt_scalef32_pk_f16_fp4 v39, v13, 1.0 op_sel:[1,1,0]
	v_cvt_scalef32_pk_f16_fp4 v40, v14, 1.0
	v_cvt_scalef32_pk_f16_fp4 v41, v14, 1.0 op_sel:[1,0,0]
	v_cvt_scalef32_pk_f16_fp4 v42, v14, 1.0 op_sel:[0,1,0]
	v_cvt_scalef32_pk_f16_fp4 v43, v14, 1.0 op_sel:[1,1,0]
	v_cvt_scalef32_pk_f16_fp4 v44, v15, 1.0
	v_cvt_scalef32_pk_f16_fp4 v45, v15, 1.0 op_sel:[1,0,0]
	v_cvt_scalef32_pk_f16_fp4 v46, v15, 1.0 op_sel:[0,1,0]
	v_cvt_scalef32_pk_f16_fp4 v47, v15, 1.0 op_sel:[1,1,0]
	buffer_load_dwordx4 v[8:11], v[180:181], s[12:15], 0 idxen offen
	v_pk_fma_f16 v162, v32, v187, v162
	v_pk_fma_f16 v161, v33, v187, v161
	v_pk_fma_f16 v160, v34, v187, v160
	v_pk_fma_f16 v159, v35, v187, v159
	v_pk_fma_f16 v158, v36, v187, v158
	v_pk_fma_f16 v157, v37, v187, v157
	v_pk_fma_f16 v156, v38, v187, v156
	v_pk_fma_f16 v147, v39, v187, v147
	v_pk_fma_f16 v146, v40, v187, v146
	v_pk_fma_f16 v145, v41, v187, v145
	v_pk_fma_f16 v144, v42, v187, v144
	v_pk_fma_f16 v143, v43, v187, v143
	v_pk_fma_f16 v142, v44, v187, v142
	v_pk_fma_f16 v141, v45, v187, v141
	v_pk_fma_f16 v149, v46, v187, v149
	v_pk_fma_f16 v148, v47, v187, v148
	ds_read_b32 v176, v115 offset:8252
	ds_read_b32 v186, v115 offset:1076
	s_waitcnt vmcnt(6) lgkmcnt(3)
	v_cvt_scalef32_pk_f16_fp4 v32, v16, 1.0
	v_cvt_scalef32_pk_f16_fp4 v33, v16, 1.0 op_sel:[1,0,0]
	v_cvt_scalef32_pk_f16_fp4 v34, v16, 1.0 op_sel:[0,1,0]
	v_cvt_scalef32_pk_f16_fp4 v35, v16, 1.0 op_sel:[1,1,0]
	v_cvt_scalef32_pk_f16_fp4 v36, v17, 1.0
	v_cvt_scalef32_pk_f16_fp4 v37, v17, 1.0 op_sel:[1,0,0]
	v_cvt_scalef32_pk_f16_fp4 v38, v17, 1.0 op_sel:[0,1,0]
	v_cvt_scalef32_pk_f16_fp4 v39, v17, 1.0 op_sel:[1,1,0]
	v_cvt_scalef32_pk_f16_fp4 v40, v18, 1.0
	v_cvt_scalef32_pk_f16_fp4 v41, v18, 1.0 op_sel:[1,0,0]
	v_cvt_scalef32_pk_f16_fp4 v42, v18, 1.0 op_sel:[0,1,0]
	v_cvt_scalef32_pk_f16_fp4 v43, v18, 1.0 op_sel:[1,1,0]
	v_cvt_scalef32_pk_f16_fp4 v44, v19, 1.0
	v_cvt_scalef32_pk_f16_fp4 v45, v19, 1.0 op_sel:[1,0,0]
	v_cvt_scalef32_pk_f16_fp4 v46, v19, 1.0 op_sel:[0,1,0]
	v_cvt_scalef32_pk_f16_fp4 v47, v19, 1.0 op_sel:[1,1,0]
	buffer_load_dwordx4 v[12:15], v[182:183], s[12:15], 0 idxen offen
	v_pk_fma_f16 v139, v32, v184, v139
	v_pk_fma_f16 v138, v33, v184, v138
	v_pk_fma_f16 v136, v34, v184, v136
	v_pk_fma_f16 v135, v35, v184, v135
	v_pk_fma_f16 v134, v36, v184, v134
	v_pk_fma_f16 v133, v37, v184, v133
	v_pk_fma_f16 v132, v38, v184, v132
	v_pk_fma_f16 v131, v39, v184, v131
	v_pk_fma_f16 v130, v40, v184, v130
	v_pk_fma_f16 v129, v41, v184, v129
	v_pk_fma_f16 v128, v42, v184, v128
	v_pk_fma_f16 v127, v43, v184, v127
	v_pk_fma_f16 v126, v44, v184, v126
	v_pk_fma_f16 v114, v45, v184, v114
	v_pk_fma_f16 v140, v46, v184, v140
	v_pk_fma_f16 v137, v47, v184, v137
	ds_read_b32 v178, v115 offset:8764
	ds_read_b32 v187, v115 offset:1588
	s_waitcnt vmcnt(6) lgkmcnt(3)
	v_cvt_scalef32_pk_f16_fp4 v32, v20, 1.0
	v_cvt_scalef32_pk_f16_fp4 v33, v20, 1.0 op_sel:[1,0,0]
	v_cvt_scalef32_pk_f16_fp4 v34, v20, 1.0 op_sel:[0,1,0]
	v_cvt_scalef32_pk_f16_fp4 v35, v20, 1.0 op_sel:[1,1,0]
	v_cvt_scalef32_pk_f16_fp4 v36, v21, 1.0
	v_cvt_scalef32_pk_f16_fp4 v37, v21, 1.0 op_sel:[1,0,0]
	v_cvt_scalef32_pk_f16_fp4 v38, v21, 1.0 op_sel:[0,1,0]
	v_cvt_scalef32_pk_f16_fp4 v39, v21, 1.0 op_sel:[1,1,0]
	v_cvt_scalef32_pk_f16_fp4 v40, v22, 1.0
	v_cvt_scalef32_pk_f16_fp4 v41, v22, 1.0 op_sel:[1,0,0]
	v_cvt_scalef32_pk_f16_fp4 v42, v22, 1.0 op_sel:[0,1,0]
	v_cvt_scalef32_pk_f16_fp4 v43, v22, 1.0 op_sel:[1,1,0]
	v_cvt_scalef32_pk_f16_fp4 v44, v23, 1.0
	v_cvt_scalef32_pk_f16_fp4 v45, v23, 1.0 op_sel:[1,0,0]
	v_cvt_scalef32_pk_f16_fp4 v46, v23, 1.0 op_sel:[0,1,0]
	v_cvt_scalef32_pk_f16_fp4 v47, v23, 1.0 op_sel:[1,1,0]
	buffer_load_dwordx4 v[16:19], v[176:177], s[12:15], 0 idxen offen
	v_pk_fma_f16 v124, v32, v185, v124
	v_pk_fma_f16 v123, v33, v185, v123
	v_pk_fma_f16 v121, v34, v185, v121
	v_pk_fma_f16 v120, v35, v185, v120
	v_pk_fma_f16 v119, v36, v185, v119
	v_pk_fma_f16 v118, v37, v185, v118
	v_pk_fma_f16 v117, v38, v185, v117
	v_pk_fma_f16 v116, v39, v185, v116
	v_pk_fma_f16 v113, v40, v185, v113
	v_pk_fma_f16 v112, v41, v185, v112
	v_pk_fma_f16 v67, v42, v185, v67
	v_pk_fma_f16 v66, v43, v185, v66
	v_pk_fma_f16 v65, v44, v185, v65
	v_pk_fma_f16 v64, v45, v185, v64
	v_pk_fma_f16 v125, v46, v185, v125
	v_pk_fma_f16 v122, v47, v185, v122
	ds_read_b32 v180, v115 offset:9276
	ds_read_b32 v184, v115 offset:56
	s_waitcnt vmcnt(6) lgkmcnt(3)
	v_cvt_scalef32_pk_f16_fp4 v32, v24, 1.0
	v_cvt_scalef32_pk_f16_fp4 v33, v24, 1.0 op_sel:[1,0,0]
	v_cvt_scalef32_pk_f16_fp4 v34, v24, 1.0 op_sel:[0,1,0]
	v_cvt_scalef32_pk_f16_fp4 v35, v24, 1.0 op_sel:[1,1,0]
	v_cvt_scalef32_pk_f16_fp4 v36, v25, 1.0
	v_cvt_scalef32_pk_f16_fp4 v37, v25, 1.0 op_sel:[1,0,0]
	v_cvt_scalef32_pk_f16_fp4 v38, v25, 1.0 op_sel:[0,1,0]
	v_cvt_scalef32_pk_f16_fp4 v39, v25, 1.0 op_sel:[1,1,0]
	v_cvt_scalef32_pk_f16_fp4 v40, v26, 1.0
	v_cvt_scalef32_pk_f16_fp4 v41, v26, 1.0 op_sel:[1,0,0]
	v_cvt_scalef32_pk_f16_fp4 v42, v26, 1.0 op_sel:[0,1,0]
	v_cvt_scalef32_pk_f16_fp4 v43, v26, 1.0 op_sel:[1,1,0]
	v_cvt_scalef32_pk_f16_fp4 v44, v27, 1.0
	v_cvt_scalef32_pk_f16_fp4 v45, v27, 1.0 op_sel:[1,0,0]
	v_cvt_scalef32_pk_f16_fp4 v46, v27, 1.0 op_sel:[0,1,0]
	v_cvt_scalef32_pk_f16_fp4 v47, v27, 1.0 op_sel:[1,1,0]
	buffer_load_dwordx4 v[20:23], v[178:179], s[12:15], 0 idxen offen
	v_pk_fma_f16 v74, v32, v186, v74
	v_pk_fma_f16 v73, v33, v186, v73
	v_pk_fma_f16 v71, v34, v186, v71
	v_pk_fma_f16 v70, v35, v186, v70
	v_pk_fma_f16 v69, v36, v186, v69
	v_pk_fma_f16 v68, v37, v186, v68
	v_pk_fma_f16 v63, v38, v186, v63
	v_pk_fma_f16 v62, v39, v186, v62
	v_pk_fma_f16 v61, v40, v186, v61
	v_pk_fma_f16 v60, v41, v186, v60
	v_pk_fma_f16 v59, v42, v186, v59
	v_pk_fma_f16 v58, v43, v186, v58
	v_pk_fma_f16 v57, v44, v186, v57
	v_pk_fma_f16 v56, v45, v186, v56
	v_pk_fma_f16 v75, v46, v186, v75
	v_pk_fma_f16 v72, v47, v186, v72
	ds_read_b32 v182, v115 offset:9788
	ds_read_b32 v185, v115 offset:568
	s_waitcnt vmcnt(6) lgkmcnt(3)
	v_cvt_scalef32_pk_f16_fp4 v32, v28, 1.0
	v_cvt_scalef32_pk_f16_fp4 v33, v28, 1.0 op_sel:[1,0,0]
	v_cvt_scalef32_pk_f16_fp4 v34, v28, 1.0 op_sel:[0,1,0]
	v_cvt_scalef32_pk_f16_fp4 v35, v28, 1.0 op_sel:[1,1,0]
	v_cvt_scalef32_pk_f16_fp4 v36, v29, 1.0
	v_cvt_scalef32_pk_f16_fp4 v37, v29, 1.0 op_sel:[1,0,0]
	v_cvt_scalef32_pk_f16_fp4 v38, v29, 1.0 op_sel:[0,1,0]
	v_cvt_scalef32_pk_f16_fp4 v39, v29, 1.0 op_sel:[1,1,0]
	v_cvt_scalef32_pk_f16_fp4 v40, v30, 1.0
	v_cvt_scalef32_pk_f16_fp4 v41, v30, 1.0 op_sel:[1,0,0]
	v_cvt_scalef32_pk_f16_fp4 v42, v30, 1.0 op_sel:[0,1,0]
	v_cvt_scalef32_pk_f16_fp4 v43, v30, 1.0 op_sel:[1,1,0]
	v_cvt_scalef32_pk_f16_fp4 v44, v31, 1.0
	v_cvt_scalef32_pk_f16_fp4 v45, v31, 1.0 op_sel:[1,0,0]
	v_cvt_scalef32_pk_f16_fp4 v46, v31, 1.0 op_sel:[0,1,0]
	v_cvt_scalef32_pk_f16_fp4 v47, v31, 1.0 op_sel:[1,1,0]
	buffer_load_dwordx4 v[24:27], v[180:181], s[12:15], 0 idxen offen
	v_pk_fma_f16 v162, v32, v187, v162
	v_pk_fma_f16 v161, v33, v187, v161
	v_pk_fma_f16 v160, v34, v187, v160
	v_pk_fma_f16 v159, v35, v187, v159
	v_pk_fma_f16 v158, v36, v187, v158
	v_pk_fma_f16 v157, v37, v187, v157
	v_pk_fma_f16 v156, v38, v187, v156
	v_pk_fma_f16 v147, v39, v187, v147
	v_pk_fma_f16 v146, v40, v187, v146
	v_pk_fma_f16 v145, v41, v187, v145
	v_pk_fma_f16 v144, v42, v187, v144
	v_pk_fma_f16 v143, v43, v187, v143
	v_pk_fma_f16 v142, v44, v187, v142
	v_pk_fma_f16 v141, v45, v187, v141
	v_pk_fma_f16 v149, v46, v187, v149
	v_pk_fma_f16 v148, v47, v187, v148
	ds_read_b32 v176, v115 offset:8256
	ds_read_b32 v186, v115 offset:1080
	s_waitcnt vmcnt(6) lgkmcnt(3)
	v_cvt_scalef32_pk_f16_fp4 v32, v0, 1.0
	v_cvt_scalef32_pk_f16_fp4 v33, v0, 1.0 op_sel:[1,0,0]
	v_cvt_scalef32_pk_f16_fp4 v34, v0, 1.0 op_sel:[0,1,0]
	v_cvt_scalef32_pk_f16_fp4 v35, v0, 1.0 op_sel:[1,1,0]
	v_cvt_scalef32_pk_f16_fp4 v36, v1, 1.0
	v_cvt_scalef32_pk_f16_fp4 v37, v1, 1.0 op_sel:[1,0,0]
	v_cvt_scalef32_pk_f16_fp4 v38, v1, 1.0 op_sel:[0,1,0]
	v_cvt_scalef32_pk_f16_fp4 v39, v1, 1.0 op_sel:[1,1,0]
	v_cvt_scalef32_pk_f16_fp4 v40, v2, 1.0
	v_cvt_scalef32_pk_f16_fp4 v41, v2, 1.0 op_sel:[1,0,0]
	v_cvt_scalef32_pk_f16_fp4 v42, v2, 1.0 op_sel:[0,1,0]
	v_cvt_scalef32_pk_f16_fp4 v43, v2, 1.0 op_sel:[1,1,0]
	v_cvt_scalef32_pk_f16_fp4 v44, v3, 1.0
	v_cvt_scalef32_pk_f16_fp4 v45, v3, 1.0 op_sel:[1,0,0]
	v_cvt_scalef32_pk_f16_fp4 v46, v3, 1.0 op_sel:[0,1,0]
	v_cvt_scalef32_pk_f16_fp4 v47, v3, 1.0 op_sel:[1,1,0]
	buffer_load_dwordx4 v[28:31], v[182:183], s[12:15], 0 idxen offen
	v_pk_fma_f16 v139, v32, v184, v139
	v_pk_fma_f16 v138, v33, v184, v138
	v_pk_fma_f16 v136, v34, v184, v136
	v_pk_fma_f16 v135, v35, v184, v135
	v_pk_fma_f16 v134, v36, v184, v134
	v_pk_fma_f16 v133, v37, v184, v133
	v_pk_fma_f16 v132, v38, v184, v132
	v_pk_fma_f16 v131, v39, v184, v131
	v_pk_fma_f16 v130, v40, v184, v130
	v_pk_fma_f16 v129, v41, v184, v129
	v_pk_fma_f16 v128, v42, v184, v128
	v_pk_fma_f16 v127, v43, v184, v127
	v_pk_fma_f16 v126, v44, v184, v126
	v_pk_fma_f16 v114, v45, v184, v114
	v_pk_fma_f16 v140, v46, v184, v140
	v_pk_fma_f16 v137, v47, v184, v137
	ds_read_b32 v178, v115 offset:8768
	ds_read_b32 v187, v115 offset:1592
	s_waitcnt vmcnt(6) lgkmcnt(3)
	v_cvt_scalef32_pk_f16_fp4 v32, v4, 1.0
	v_cvt_scalef32_pk_f16_fp4 v33, v4, 1.0 op_sel:[1,0,0]
	v_cvt_scalef32_pk_f16_fp4 v34, v4, 1.0 op_sel:[0,1,0]
	v_cvt_scalef32_pk_f16_fp4 v35, v4, 1.0 op_sel:[1,1,0]
	v_cvt_scalef32_pk_f16_fp4 v36, v5, 1.0
	v_cvt_scalef32_pk_f16_fp4 v37, v5, 1.0 op_sel:[1,0,0]
	v_cvt_scalef32_pk_f16_fp4 v38, v5, 1.0 op_sel:[0,1,0]
	v_cvt_scalef32_pk_f16_fp4 v39, v5, 1.0 op_sel:[1,1,0]
	v_cvt_scalef32_pk_f16_fp4 v40, v6, 1.0
	v_cvt_scalef32_pk_f16_fp4 v41, v6, 1.0 op_sel:[1,0,0]
	v_cvt_scalef32_pk_f16_fp4 v42, v6, 1.0 op_sel:[0,1,0]
	v_cvt_scalef32_pk_f16_fp4 v43, v6, 1.0 op_sel:[1,1,0]
	v_cvt_scalef32_pk_f16_fp4 v44, v7, 1.0
	v_cvt_scalef32_pk_f16_fp4 v45, v7, 1.0 op_sel:[1,0,0]
	v_cvt_scalef32_pk_f16_fp4 v46, v7, 1.0 op_sel:[0,1,0]
	v_cvt_scalef32_pk_f16_fp4 v47, v7, 1.0 op_sel:[1,1,0]
	buffer_load_dwordx4 v[0:3], v[176:177], s[12:15], 0 idxen offen
	v_pk_fma_f16 v124, v32, v185, v124
	v_pk_fma_f16 v123, v33, v185, v123
	v_pk_fma_f16 v121, v34, v185, v121
	v_pk_fma_f16 v120, v35, v185, v120
	v_pk_fma_f16 v119, v36, v185, v119
	v_pk_fma_f16 v118, v37, v185, v118
	v_pk_fma_f16 v117, v38, v185, v117
	v_pk_fma_f16 v116, v39, v185, v116
	v_pk_fma_f16 v113, v40, v185, v113
	v_pk_fma_f16 v112, v41, v185, v112
	v_pk_fma_f16 v67, v42, v185, v67
	v_pk_fma_f16 v66, v43, v185, v66
	v_pk_fma_f16 v65, v44, v185, v65
	v_pk_fma_f16 v64, v45, v185, v64
	v_pk_fma_f16 v125, v46, v185, v125
	v_pk_fma_f16 v122, v47, v185, v122
	ds_read_b32 v180, v115 offset:9280
	ds_read_b32 v184, v115 offset:60
	s_waitcnt vmcnt(6) lgkmcnt(3)
	v_cvt_scalef32_pk_f16_fp4 v32, v8, 1.0
	v_cvt_scalef32_pk_f16_fp4 v33, v8, 1.0 op_sel:[1,0,0]
	v_cvt_scalef32_pk_f16_fp4 v34, v8, 1.0 op_sel:[0,1,0]
	v_cvt_scalef32_pk_f16_fp4 v35, v8, 1.0 op_sel:[1,1,0]
	v_cvt_scalef32_pk_f16_fp4 v36, v9, 1.0
	v_cvt_scalef32_pk_f16_fp4 v37, v9, 1.0 op_sel:[1,0,0]
	v_cvt_scalef32_pk_f16_fp4 v38, v9, 1.0 op_sel:[0,1,0]
	v_cvt_scalef32_pk_f16_fp4 v39, v9, 1.0 op_sel:[1,1,0]
	v_cvt_scalef32_pk_f16_fp4 v40, v10, 1.0
	v_cvt_scalef32_pk_f16_fp4 v41, v10, 1.0 op_sel:[1,0,0]
	v_cvt_scalef32_pk_f16_fp4 v42, v10, 1.0 op_sel:[0,1,0]
	v_cvt_scalef32_pk_f16_fp4 v43, v10, 1.0 op_sel:[1,1,0]
	v_cvt_scalef32_pk_f16_fp4 v44, v11, 1.0
	v_cvt_scalef32_pk_f16_fp4 v45, v11, 1.0 op_sel:[1,0,0]
	v_cvt_scalef32_pk_f16_fp4 v46, v11, 1.0 op_sel:[0,1,0]
	v_cvt_scalef32_pk_f16_fp4 v47, v11, 1.0 op_sel:[1,1,0]
	buffer_load_dwordx4 v[4:7], v[178:179], s[12:15], 0 idxen offen
	v_pk_fma_f16 v74, v32, v186, v74
	v_pk_fma_f16 v73, v33, v186, v73
	v_pk_fma_f16 v71, v34, v186, v71
	v_pk_fma_f16 v70, v35, v186, v70
	v_pk_fma_f16 v69, v36, v186, v69
	v_pk_fma_f16 v68, v37, v186, v68
	v_pk_fma_f16 v63, v38, v186, v63
	v_pk_fma_f16 v62, v39, v186, v62
	v_pk_fma_f16 v61, v40, v186, v61
	v_pk_fma_f16 v60, v41, v186, v60
	v_pk_fma_f16 v59, v42, v186, v59
	v_pk_fma_f16 v58, v43, v186, v58
	v_pk_fma_f16 v57, v44, v186, v57
	v_pk_fma_f16 v56, v45, v186, v56
	v_pk_fma_f16 v75, v46, v186, v75
	v_pk_fma_f16 v72, v47, v186, v72
	ds_read_b32 v182, v115 offset:9792
	ds_read_b32 v185, v115 offset:572
	s_waitcnt vmcnt(6) lgkmcnt(3)
	v_cvt_scalef32_pk_f16_fp4 v32, v12, 1.0
	v_cvt_scalef32_pk_f16_fp4 v33, v12, 1.0 op_sel:[1,0,0]
	v_cvt_scalef32_pk_f16_fp4 v34, v12, 1.0 op_sel:[0,1,0]
	v_cvt_scalef32_pk_f16_fp4 v35, v12, 1.0 op_sel:[1,1,0]
	v_cvt_scalef32_pk_f16_fp4 v36, v13, 1.0
	v_cvt_scalef32_pk_f16_fp4 v37, v13, 1.0 op_sel:[1,0,0]
	v_cvt_scalef32_pk_f16_fp4 v38, v13, 1.0 op_sel:[0,1,0]
	v_cvt_scalef32_pk_f16_fp4 v39, v13, 1.0 op_sel:[1,1,0]
	v_cvt_scalef32_pk_f16_fp4 v40, v14, 1.0
	v_cvt_scalef32_pk_f16_fp4 v41, v14, 1.0 op_sel:[1,0,0]
	v_cvt_scalef32_pk_f16_fp4 v42, v14, 1.0 op_sel:[0,1,0]
	v_cvt_scalef32_pk_f16_fp4 v43, v14, 1.0 op_sel:[1,1,0]
	v_cvt_scalef32_pk_f16_fp4 v44, v15, 1.0
	v_cvt_scalef32_pk_f16_fp4 v45, v15, 1.0 op_sel:[1,0,0]
	v_cvt_scalef32_pk_f16_fp4 v46, v15, 1.0 op_sel:[0,1,0]
	v_cvt_scalef32_pk_f16_fp4 v47, v15, 1.0 op_sel:[1,1,0]
	buffer_load_dwordx4 v[8:11], v[180:181], s[12:15], 0 idxen offen
	v_pk_fma_f16 v162, v32, v187, v162
	v_pk_fma_f16 v161, v33, v187, v161
	v_pk_fma_f16 v160, v34, v187, v160
	v_pk_fma_f16 v159, v35, v187, v159
	v_pk_fma_f16 v158, v36, v187, v158
	v_pk_fma_f16 v157, v37, v187, v157
	v_pk_fma_f16 v156, v38, v187, v156
	v_pk_fma_f16 v147, v39, v187, v147
	v_pk_fma_f16 v146, v40, v187, v146
	v_pk_fma_f16 v145, v41, v187, v145
	v_pk_fma_f16 v144, v42, v187, v144
	v_pk_fma_f16 v143, v43, v187, v143
	v_pk_fma_f16 v142, v44, v187, v142
	v_pk_fma_f16 v141, v45, v187, v141
	v_pk_fma_f16 v149, v46, v187, v149
	v_pk_fma_f16 v148, v47, v187, v148
	ds_read_b32 v176, v115 offset:8260
	ds_read_b32 v186, v115 offset:1084
	s_waitcnt vmcnt(6) lgkmcnt(3)
	v_cvt_scalef32_pk_f16_fp4 v32, v16, 1.0
	v_cvt_scalef32_pk_f16_fp4 v33, v16, 1.0 op_sel:[1,0,0]
	v_cvt_scalef32_pk_f16_fp4 v34, v16, 1.0 op_sel:[0,1,0]
	v_cvt_scalef32_pk_f16_fp4 v35, v16, 1.0 op_sel:[1,1,0]
	v_cvt_scalef32_pk_f16_fp4 v36, v17, 1.0
	v_cvt_scalef32_pk_f16_fp4 v37, v17, 1.0 op_sel:[1,0,0]
	v_cvt_scalef32_pk_f16_fp4 v38, v17, 1.0 op_sel:[0,1,0]
	v_cvt_scalef32_pk_f16_fp4 v39, v17, 1.0 op_sel:[1,1,0]
	v_cvt_scalef32_pk_f16_fp4 v40, v18, 1.0
	v_cvt_scalef32_pk_f16_fp4 v41, v18, 1.0 op_sel:[1,0,0]
	v_cvt_scalef32_pk_f16_fp4 v42, v18, 1.0 op_sel:[0,1,0]
	v_cvt_scalef32_pk_f16_fp4 v43, v18, 1.0 op_sel:[1,1,0]
	v_cvt_scalef32_pk_f16_fp4 v44, v19, 1.0
	v_cvt_scalef32_pk_f16_fp4 v45, v19, 1.0 op_sel:[1,0,0]
	v_cvt_scalef32_pk_f16_fp4 v46, v19, 1.0 op_sel:[0,1,0]
	v_cvt_scalef32_pk_f16_fp4 v47, v19, 1.0 op_sel:[1,1,0]
	buffer_load_dwordx4 v[12:15], v[182:183], s[12:15], 0 idxen offen
	v_pk_fma_f16 v139, v32, v184, v139
	v_pk_fma_f16 v138, v33, v184, v138
	v_pk_fma_f16 v136, v34, v184, v136
	v_pk_fma_f16 v135, v35, v184, v135
	v_pk_fma_f16 v134, v36, v184, v134
	v_pk_fma_f16 v133, v37, v184, v133
	v_pk_fma_f16 v132, v38, v184, v132
	v_pk_fma_f16 v131, v39, v184, v131
	v_pk_fma_f16 v130, v40, v184, v130
	v_pk_fma_f16 v129, v41, v184, v129
	v_pk_fma_f16 v128, v42, v184, v128
	v_pk_fma_f16 v127, v43, v184, v127
	v_pk_fma_f16 v126, v44, v184, v126
	v_pk_fma_f16 v114, v45, v184, v114
	v_pk_fma_f16 v140, v46, v184, v140
	v_pk_fma_f16 v137, v47, v184, v137
	ds_read_b32 v178, v115 offset:8772
	ds_read_b32 v187, v115 offset:1596
	s_waitcnt vmcnt(6) lgkmcnt(3)
	v_cvt_scalef32_pk_f16_fp4 v32, v20, 1.0
	v_cvt_scalef32_pk_f16_fp4 v33, v20, 1.0 op_sel:[1,0,0]
	v_cvt_scalef32_pk_f16_fp4 v34, v20, 1.0 op_sel:[0,1,0]
	v_cvt_scalef32_pk_f16_fp4 v35, v20, 1.0 op_sel:[1,1,0]
	v_cvt_scalef32_pk_f16_fp4 v36, v21, 1.0
	v_cvt_scalef32_pk_f16_fp4 v37, v21, 1.0 op_sel:[1,0,0]
	v_cvt_scalef32_pk_f16_fp4 v38, v21, 1.0 op_sel:[0,1,0]
	v_cvt_scalef32_pk_f16_fp4 v39, v21, 1.0 op_sel:[1,1,0]
	v_cvt_scalef32_pk_f16_fp4 v40, v22, 1.0
	v_cvt_scalef32_pk_f16_fp4 v41, v22, 1.0 op_sel:[1,0,0]
	v_cvt_scalef32_pk_f16_fp4 v42, v22, 1.0 op_sel:[0,1,0]
	v_cvt_scalef32_pk_f16_fp4 v43, v22, 1.0 op_sel:[1,1,0]
	v_cvt_scalef32_pk_f16_fp4 v44, v23, 1.0
	v_cvt_scalef32_pk_f16_fp4 v45, v23, 1.0 op_sel:[1,0,0]
	v_cvt_scalef32_pk_f16_fp4 v46, v23, 1.0 op_sel:[0,1,0]
	v_cvt_scalef32_pk_f16_fp4 v47, v23, 1.0 op_sel:[1,1,0]
	buffer_load_dwordx4 v[16:19], v[176:177], s[12:15], 0 idxen offen
	v_pk_fma_f16 v124, v32, v185, v124
	v_pk_fma_f16 v123, v33, v185, v123
	v_pk_fma_f16 v121, v34, v185, v121
	v_pk_fma_f16 v120, v35, v185, v120
	v_pk_fma_f16 v119, v36, v185, v119
	v_pk_fma_f16 v118, v37, v185, v118
	v_pk_fma_f16 v117, v38, v185, v117
	v_pk_fma_f16 v116, v39, v185, v116
	v_pk_fma_f16 v113, v40, v185, v113
	v_pk_fma_f16 v112, v41, v185, v112
	v_pk_fma_f16 v67, v42, v185, v67
	v_pk_fma_f16 v66, v43, v185, v66
	v_pk_fma_f16 v65, v44, v185, v65
	v_pk_fma_f16 v64, v45, v185, v64
	v_pk_fma_f16 v125, v46, v185, v125
	v_pk_fma_f16 v122, v47, v185, v122
	ds_read_b32 v180, v115 offset:9284
	ds_read_b32 v184, v115 offset:64
	s_waitcnt vmcnt(6) lgkmcnt(3)
	v_cvt_scalef32_pk_f16_fp4 v32, v24, 1.0
	v_cvt_scalef32_pk_f16_fp4 v33, v24, 1.0 op_sel:[1,0,0]
	v_cvt_scalef32_pk_f16_fp4 v34, v24, 1.0 op_sel:[0,1,0]
	v_cvt_scalef32_pk_f16_fp4 v35, v24, 1.0 op_sel:[1,1,0]
	v_cvt_scalef32_pk_f16_fp4 v36, v25, 1.0
	v_cvt_scalef32_pk_f16_fp4 v37, v25, 1.0 op_sel:[1,0,0]
	v_cvt_scalef32_pk_f16_fp4 v38, v25, 1.0 op_sel:[0,1,0]
	v_cvt_scalef32_pk_f16_fp4 v39, v25, 1.0 op_sel:[1,1,0]
	v_cvt_scalef32_pk_f16_fp4 v40, v26, 1.0
	v_cvt_scalef32_pk_f16_fp4 v41, v26, 1.0 op_sel:[1,0,0]
	v_cvt_scalef32_pk_f16_fp4 v42, v26, 1.0 op_sel:[0,1,0]
	v_cvt_scalef32_pk_f16_fp4 v43, v26, 1.0 op_sel:[1,1,0]
	v_cvt_scalef32_pk_f16_fp4 v44, v27, 1.0
	v_cvt_scalef32_pk_f16_fp4 v45, v27, 1.0 op_sel:[1,0,0]
	v_cvt_scalef32_pk_f16_fp4 v46, v27, 1.0 op_sel:[0,1,0]
	v_cvt_scalef32_pk_f16_fp4 v47, v27, 1.0 op_sel:[1,1,0]
	buffer_load_dwordx4 v[20:23], v[178:179], s[12:15], 0 idxen offen
	v_pk_fma_f16 v74, v32, v186, v74
	v_pk_fma_f16 v73, v33, v186, v73
	v_pk_fma_f16 v71, v34, v186, v71
	v_pk_fma_f16 v70, v35, v186, v70
	v_pk_fma_f16 v69, v36, v186, v69
	v_pk_fma_f16 v68, v37, v186, v68
	v_pk_fma_f16 v63, v38, v186, v63
	v_pk_fma_f16 v62, v39, v186, v62
	v_pk_fma_f16 v61, v40, v186, v61
	v_pk_fma_f16 v60, v41, v186, v60
	v_pk_fma_f16 v59, v42, v186, v59
	v_pk_fma_f16 v58, v43, v186, v58
	v_pk_fma_f16 v57, v44, v186, v57
	v_pk_fma_f16 v56, v45, v186, v56
	v_pk_fma_f16 v75, v46, v186, v75
	v_pk_fma_f16 v72, v47, v186, v72
	ds_read_b32 v182, v115 offset:9796
	ds_read_b32 v185, v115 offset:576
	s_waitcnt vmcnt(6) lgkmcnt(3)
	v_cvt_scalef32_pk_f16_fp4 v32, v28, 1.0
	v_cvt_scalef32_pk_f16_fp4 v33, v28, 1.0 op_sel:[1,0,0]
	v_cvt_scalef32_pk_f16_fp4 v34, v28, 1.0 op_sel:[0,1,0]
	v_cvt_scalef32_pk_f16_fp4 v35, v28, 1.0 op_sel:[1,1,0]
	v_cvt_scalef32_pk_f16_fp4 v36, v29, 1.0
	v_cvt_scalef32_pk_f16_fp4 v37, v29, 1.0 op_sel:[1,0,0]
	v_cvt_scalef32_pk_f16_fp4 v38, v29, 1.0 op_sel:[0,1,0]
	v_cvt_scalef32_pk_f16_fp4 v39, v29, 1.0 op_sel:[1,1,0]
	v_cvt_scalef32_pk_f16_fp4 v40, v30, 1.0
	v_cvt_scalef32_pk_f16_fp4 v41, v30, 1.0 op_sel:[1,0,0]
	v_cvt_scalef32_pk_f16_fp4 v42, v30, 1.0 op_sel:[0,1,0]
	v_cvt_scalef32_pk_f16_fp4 v43, v30, 1.0 op_sel:[1,1,0]
	v_cvt_scalef32_pk_f16_fp4 v44, v31, 1.0
	v_cvt_scalef32_pk_f16_fp4 v45, v31, 1.0 op_sel:[1,0,0]
	v_cvt_scalef32_pk_f16_fp4 v46, v31, 1.0 op_sel:[0,1,0]
	v_cvt_scalef32_pk_f16_fp4 v47, v31, 1.0 op_sel:[1,1,0]
	buffer_load_dwordx4 v[24:27], v[180:181], s[12:15], 0 idxen offen
	v_pk_fma_f16 v162, v32, v187, v162
	v_pk_fma_f16 v161, v33, v187, v161
	v_pk_fma_f16 v160, v34, v187, v160
	v_pk_fma_f16 v159, v35, v187, v159
	v_pk_fma_f16 v158, v36, v187, v158
	v_pk_fma_f16 v157, v37, v187, v157
	v_pk_fma_f16 v156, v38, v187, v156
	v_pk_fma_f16 v147, v39, v187, v147
	v_pk_fma_f16 v146, v40, v187, v146
	v_pk_fma_f16 v145, v41, v187, v145
	v_pk_fma_f16 v144, v42, v187, v144
	v_pk_fma_f16 v143, v43, v187, v143
	v_pk_fma_f16 v142, v44, v187, v142
	v_pk_fma_f16 v141, v45, v187, v141
	v_pk_fma_f16 v149, v46, v187, v149
	v_pk_fma_f16 v148, v47, v187, v148
	v_add_u32_e32 v115, 64, v115
	s_add_i32 s11, s11, 1
	s_cmp_eq_u32 s11, 8
	s_cbranch_scc0 .Lmy_lblk
	s_waitcnt vmcnt(0) lgkmcnt(0)
	s_movk_i32 s12, 0x1000
	v_lshlrev_b32_e32 v236, 6, v78
	v_add_u32_e32 v237, 0x1000, v236
	global_load_dwordx4 v[172:175], v236, s[16:17] offset:0
	global_load_dwordx4 v[204:207], v236, s[18:19] offset:0
	global_load_dwordx4 v[176:179], v236, s[16:17] offset:16
	global_load_dwordx4 v[208:211], v236, s[18:19] offset:16
	global_load_dwordx4 v[180:183], v236, s[16:17] offset:32
	global_load_dwordx4 v[212:215], v236, s[18:19] offset:32
	global_load_dwordx4 v[184:187], v236, s[16:17] offset:48
	global_load_dwordx4 v[216:219], v236, s[18:19] offset:48
	global_load_dwordx4 v[188:191], v237, s[16:17] offset:0
	global_load_dwordx4 v[220:223], v237, s[18:19] offset:0
	global_load_dwordx4 v[192:195], v237, s[16:17] offset:16
	global_load_dwordx4 v[224:227], v237, s[18:19] offset:16
	global_load_dwordx4 v[196:199], v237, s[16:17] offset:32
	global_load_dwordx4 v[228:231], v237, s[18:19] offset:32
	global_load_dwordx4 v[200:203], v237, s[16:17] offset:48
	global_load_dwordx4 v[232:235], v237, s[18:19] offset:48
	s_lshl_b32 s0, s10, 2
	s_waitcnt vmcnt(11)
	v_mov_b32_e32 v0, v78
	s_or_b32 s10, s0, s22
	s_waitcnt vmcnt(0) lgkmcnt(0)
	s_ashr_i32 s11, s10, 31
	s_waitcnt vmcnt(2)
	v_lshlrev_b32_e32 v42, 4, v0
	v_ashrrev_i32_e32 v43, 31, v42
	s_lshl_b64 s[0:1], s[10:11], 11
	v_lshl_add_u64 v[0:1], s[0:1], 0, v[42:43]
	v_lshlrev_b64 v[0:1], 1, v[0:1]
	v_lshl_add_u64 v[28:29], s[70:71], 0, v[0:1]
	global_load_dwordx4 v[4:7], v[28:29], off offset:2064
	v_lshl_add_u64 v[24:25], s[2:3], 0, v[0:1]
	global_load_dwordx4 v[0:3], v[24:25], off offset:2064
	global_load_dwordx4 v[8:11], v[28:29], off
	global_load_dwordx4 v[12:15], v[24:25], off
	global_load_dwordx4 v[16:19], v[28:29], off offset:16
	global_load_dwordx4 v[20:23], v[24:25], off offset:16
	s_nop 0
	global_load_dwordx4 v[24:27], v[24:25], off offset:2048
	s_nop 0
	global_load_dwordx4 v[28:31], v[28:29], off offset:2048
	v_cvt_f32_f16_sdwa v35, v139 dst_sel:DWORD dst_unused:UNUSED_PAD src0_sel:WORD_1
	v_cvt_f32_f16_e32 v34, v139
	v_cvt_f32_f16_sdwa v41, v136 dst_sel:DWORD dst_unused:UNUSED_PAD src0_sel:WORD_1
	v_cvt_f32_f16_e32 v40, v136
	v_cvt_f32_f16_sdwa v37, v138 dst_sel:DWORD dst_unused:UNUSED_PAD src0_sel:WORD_1
	v_cvt_f32_f16_e32 v36, v138
	s_waitcnt vmcnt(9)
	v_cvt_f32_f16_sdwa v45, v135 dst_sel:DWORD dst_unused:UNUSED_PAD src0_sel:WORD_1
	v_cvt_f32_f16_e32 v44, v135
	v_cvt_f32_f16_sdwa v47, v134 dst_sel:DWORD dst_unused:UNUSED_PAD src0_sel:WORD_1
	v_cvt_f32_f16_e32 v46, v134
	v_cvt_f32_f16_sdwa v49, v133 dst_sel:DWORD dst_unused:UNUSED_PAD src0_sel:WORD_1
	v_cvt_f32_f16_e32 v48, v133
	v_cvt_f32_f16_sdwa v51, v132 dst_sel:DWORD dst_unused:UNUSED_PAD src0_sel:WORD_1
	v_cvt_f32_f16_e32 v50, v132
	v_cvt_f32_f16_sdwa v39, v137 dst_sel:DWORD dst_unused:UNUSED_PAD src0_sel:WORD_1
	v_cvt_f32_f16_e32 v38, v137
	v_cvt_f32_f16_sdwa v33, v140 dst_sel:DWORD dst_unused:UNUSED_PAD src0_sel:WORD_1
	v_cvt_f32_f16_e32 v32, v140
	s_lshl_b64 s[14:15], s[10:11], 13
	s_waitcnt vmcnt(6)
	v_and_b32_e32 v55, 0xffff0000, v2
	v_lshlrev_b32_e32 v54, 16, v2
	v_and_b32_e32 v53, 0xffff0000, v6
	v_lshlrev_b32_e32 v52, 16, v6
	s_waitcnt vmcnt(5)
	v_lshlrev_b32_e32 v104, 16, v8
	v_and_b32_e32 v105, 0xffff0000, v8
	s_waitcnt vmcnt(4)
	v_lshlrev_b32_e32 v106, 16, v12
	v_and_b32_e32 v107, 0xffff0000, v12
	v_and_b32_e32 v109, 0xffff0000, v7
	v_lshlrev_b32_e32 v108, 16, v7
	v_and_b32_e32 v7, 0xffff0000, v3
	v_lshlrev_b32_e32 v6, 16, v3
	v_lshlrev_b32_e32 v2, 16, v10
	v_and_b32_e32 v3, 0xffff0000, v10
	v_lshlrev_b32_e32 v110, 16, v14
	v_and_b32_e32 v111, 0xffff0000, v14
	v_lshlrev_b32_e32 v10, 16, v11
	v_and_b32_e32 v11, 0xffff0000, v11
	v_lshlrev_b32_e32 v14, 16, v15
	v_and_b32_e32 v15, 0xffff0000, v15
	s_waitcnt vmcnt(3)
	v_lshlrev_b32_e32 v132, 16, v16
	v_and_b32_e32 v133, 0xffff0000, v16
	s_waitcnt vmcnt(2)
	v_lshlrev_b32_e32 v134, 16, v20
	v_and_b32_e32 v135, 0xffff0000, v20
	v_lshlrev_b32_e32 v16, 16, v17
	v_and_b32_e32 v17, 0xffff0000, v17
	v_lshlrev_b32_e32 v20, 16, v21
	v_and_b32_e32 v21, 0xffff0000, v21
	v_pk_fma_f32 v[52:53], v[52:53], s[6:7], v[54:55] op_sel_hi:[1,0,1]
	v_pk_fma_f32 v[54:55], v[104:105], s[6:7], v[106:107] op_sel_hi:[1,0,1]
	v_lshlrev_b32_e32 v8, 16, v9
	v_and_b32_e32 v9, 0xffff0000, v9
	v_lshlrev_b32_e32 v12, 16, v13
	v_and_b32_e32 v13, 0xffff0000, v13
	v_pk_fma_f32 v[2:3], v[2:3], s[6:7], v[110:111] op_sel_hi:[1,0,1]
	v_pk_fma_f32 v[10:11], v[10:11], s[6:7], v[14:15] op_sel_hi:[1,0,1]
	v_pk_fma_f32 v[14:15], v[16:17], s[6:7], v[20:21] op_sel_hi:[1,0,1]
	v_pk_add_f32 v[20:21], v[54:55], v[34:35]
	v_pk_fma_f32 v[8:9], v[8:9], s[6:7], v[12:13] op_sel_hi:[1,0,1]
	v_pk_add_f32 v[40:41], v[2:3], v[40:41]
	v_add_f32_e32 v2, 0, v20
	v_pk_add_f32 v[8:9], v[8:9], v[36:37]
	v_add_f32_e32 v2, v21, v2
	v_add_f32_e32 v2, v8, v2
	v_add_f32_e32 v2, v9, v2
	v_add_f32_e32 v2, v40, v2
	v_pk_add_f32 v[10:11], v[10:11], v[44:45]
	v_add_f32_e32 v2, v41, v2
	v_pk_fma_f32 v[12:13], v[132:133], s[6:7], v[134:135] op_sel_hi:[1,0,1]
	v_add_f32_e32 v2, v10, v2
	v_pk_add_f32 v[12:13], v[12:13], v[46:47]
	v_add_f32_e32 v2, v11, v2
	v_add_f32_e32 v2, v12, v2
	v_pk_add_f32 v[14:15], v[14:15], v[48:49]
	v_add_f32_e32 v2, v13, v2
	v_lshlrev_b32_e32 v136, 16, v18
	v_and_b32_e32 v137, 0xffff0000, v18
	v_lshlrev_b32_e32 v138, 16, v22
	v_pk_fma_f32 v[6:7], v[108:109], s[6:7], v[6:7] op_sel_hi:[1,0,1]
	v_add_f32_e32 v2, v14, v2
	v_and_b32_e32 v139, 0xffff0000, v22
	v_pk_add_f32 v[38:39], v[6:7], v[38:39]
	v_add_f32_e32 v6, v15, v2
	v_pk_fma_f32 v[2:3], v[136:137], s[6:7], v[138:139] op_sel_hi:[1,0,1]
	v_and_b32_e32 v7, 0xffff0000, v19
	v_pk_add_f32 v[44:45], v[2:3], v[50:51]
	v_cvt_f32_f16_sdwa v3, v131 dst_sel:DWORD dst_unused:UNUSED_PAD src0_sel:WORD_1
	v_add_f32_e32 v2, v44, v6
	v_add_f32_e32 v22, v45, v2
	v_cvt_f32_f16_e32 v2, v131
	v_lshlrev_b32_e32 v6, 16, v19
	v_lshlrev_b32_e32 v18, 16, v23
	v_and_b32_e32 v19, 0xffff0000, v23
	v_pk_fma_f32 v[6:7], v[6:7], s[6:7], v[18:19] op_sel_hi:[1,0,1]
	v_pk_add_f32 v[16:17], v[52:53], v[32:33]
	v_pk_add_f32 v[18:19], v[6:7], v[2:3]
	v_cvt_f32_f16_sdwa v3, v130 dst_sel:DWORD dst_unused:UNUSED_PAD src0_sel:WORD_1
	v_add_f32_e32 v2, v18, v22
	v_add_f32_e32 v32, v19, v2
	v_cvt_f32_f16_e32 v2, v130
	s_waitcnt vmcnt(0)
	v_lshlrev_b32_e32 v6, 16, v28
	v_and_b32_e32 v7, 0xffff0000, v28
	v_lshlrev_b32_e32 v22, 16, v24
	v_and_b32_e32 v23, 0xffff0000, v24
	v_pk_fma_f32 v[6:7], v[6:7], s[6:7], v[22:23] op_sel_hi:[1,0,1]
	v_lshlrev_b32_e32 v24, 16, v25
	v_pk_add_f32 v[22:23], v[6:7], v[2:3]
	v_cvt_f32_f16_sdwa v3, v129 dst_sel:DWORD dst_unused:UNUSED_PAD src0_sel:WORD_1
	v_add_f32_e32 v2, v22, v32
	v_add_f32_e32 v28, v23, v2
	v_cvt_f32_f16_e32 v2, v129
	v_lshlrev_b32_e32 v6, 16, v29
	v_and_b32_e32 v7, 0xffff0000, v29
	v_and_b32_e32 v25, 0xffff0000, v25
	v_pk_fma_f32 v[6:7], v[6:7], s[6:7], v[24:25] op_sel_hi:[1,0,1]
	v_and_b32_e32 v29, 0xffff0000, v26
	v_pk_add_f32 v[24:25], v[6:7], v[2:3]
	v_cvt_f32_f16_sdwa v3, v128 dst_sel:DWORD dst_unused:UNUSED_PAD src0_sel:WORD_1
	v_add_f32_e32 v2, v24, v28
	v_add_f32_e32 v32, v25, v2
	v_cvt_f32_f16_e32 v2, v128
	v_lshlrev_b32_e32 v6, 16, v30
	v_and_b32_e32 v7, 0xffff0000, v30
	v_lshlrev_b32_e32 v28, 16, v26
	v_pk_fma_f32 v[6:7], v[6:7], s[6:7], v[28:29] op_sel_hi:[1,0,1]
	v_lshlrev_b32_e32 v26, 16, v27
	v_pk_add_f32 v[28:29], v[6:7], v[2:3]
	v_cvt_f32_f16_sdwa v3, v127 dst_sel:DWORD dst_unused:UNUSED_PAD src0_sel:WORD_1
	v_add_f32_e32 v2, v28, v32
	v_add_f32_e32 v30, v29, v2
	v_cvt_f32_f16_e32 v2, v127
	v_lshlrev_b32_e32 v6, 16, v31
	v_and_b32_e32 v7, 0xffff0000, v31
	v_and_b32_e32 v27, 0xffff0000, v27
	v_pk_fma_f32 v[6:7], v[6:7], s[6:7], v[26:27] op_sel_hi:[1,0,1]
	v_and_b32_e32 v31, 0xffff0000, v0
	v_pk_add_f32 v[26:27], v[6:7], v[2:3]
	v_cvt_f32_f16_sdwa v3, v126 dst_sel:DWORD dst_unused:UNUSED_PAD src0_sel:WORD_1
	v_add_f32_e32 v2, v26, v30
	v_add_f32_e32 v32, v27, v2
	v_cvt_f32_f16_e32 v2, v126
	v_lshlrev_b32_e32 v6, 16, v4
	v_and_b32_e32 v7, 0xffff0000, v4
	v_lshlrev_b32_e32 v30, 16, v0
	v_pk_fma_f32 v[6:7], v[6:7], s[6:7], v[30:31] op_sel_hi:[1,0,1]
	v_lshlrev_b32_e32 v4, 16, v5
	v_pk_add_f32 v[30:31], v[6:7], v[2:3]
	v_cvt_f32_f16_sdwa v3, v114 dst_sel:DWORD dst_unused:UNUSED_PAD src0_sel:WORD_1
	v_cvt_f32_f16_e32 v2, v114
	v_add_f32_e32 v0, v30, v32
	v_add_f32_e32 v6, v31, v0
	v_and_b32_e32 v5, 0xffff0000, v5
	v_lshlrev_b32_e32 v0, 16, v1
	v_and_b32_e32 v1, 0xffff0000, v1
	v_pk_fma_f32 v[0:1], v[4:5], s[6:7], v[0:1] op_sel_hi:[1,0,1]
	v_lshlrev_b64 v[36:37], 2, v[42:43]
	v_pk_add_f32 v[46:47], v[0:1], v[2:3]
	v_lshl_add_u64 v[32:33], s[16:17], 0, v[36:37]
	v_add_f32_e32 v0, v46, v6
	v_add_f32_e32 v0, v47, v0
	v_add_f32_e32 v0, v16, v0
	v_add_f32_e32 v0, v17, v0
	v_add_f32_e32 v0, v38, v0
	v_add_f32_e32 v0, v39, v0
	ds_bpermute_b32 v1, v79, v0
	v_lshl_add_u64 v[34:35], s[18:19], 0, v[36:37]
	s_waitcnt lgkmcnt(0)
	v_add_f32_e32 v0, v0, v1
	ds_bpermute_b32 v1, v80, v0
	s_waitcnt lgkmcnt(0)
	v_add_f32_e32 v0, v0, v1
	ds_bpermute_b32 v1, v81, v0
	s_waitcnt lgkmcnt(0)
	v_add_f32_e32 v0, v0, v1
	ds_bpermute_b32 v1, v82, v0
	s_waitcnt lgkmcnt(0)
	v_add_f32_e32 v0, v0, v1
	ds_bpermute_b32 v1, v83, v0
	s_waitcnt lgkmcnt(0)
	v_add_f32_e32 v48, v0, v1
	ds_bpermute_b32 v49, v84, v48
	s_waitcnt lgkmcnt(0)
	v_add_f32_e32 v48, v48, v49
	v_mul_f32_e32 v48, 0x3a000000, v48
	v_pk_add_f32 v[20:21], v[20:21], v[48:49] op_sel_hi:[1,0] neg_lo:[0,1] neg_hi:[0,1]
	v_pk_add_f32 v[8:9], v[8:9], v[48:49] op_sel_hi:[1,0] neg_lo:[0,1] neg_hi:[0,1]
	v_pk_mul_f32 v[50:51], v[20:21], v[20:21]
	v_pk_mul_f32 v[52:53], v[8:9], v[8:9]
	v_add_f32_e32 v50, v50, v51
	v_pk_add_f32 v[40:41], v[40:41], v[48:49] op_sel_hi:[1,0] neg_lo:[0,1] neg_hi:[0,1]
	v_add_f32_e32 v50, v52, v50
	v_pk_mul_f32 v[54:55], v[40:41], v[40:41]
	v_add_f32_e32 v50, v53, v50
	v_pk_add_f32 v[10:11], v[10:11], v[48:49] op_sel_hi:[1,0] neg_lo:[0,1] neg_hi:[0,1]
	v_add_f32_e32 v50, v54, v50
	v_pk_mul_f32 v[104:105], v[10:11], v[10:11]
	v_add_f32_e32 v50, v55, v50
	v_pk_add_f32 v[12:13], v[12:13], v[48:49] op_sel_hi:[1,0] neg_lo:[0,1] neg_hi:[0,1]
	v_add_f32_e32 v50, v104, v50
	v_pk_mul_f32 v[106:107], v[12:13], v[12:13]
	v_add_f32_e32 v50, v105, v50
	v_pk_add_f32 v[14:15], v[14:15], v[48:49] op_sel_hi:[1,0] neg_lo:[0,1] neg_hi:[0,1]
	v_add_f32_e32 v50, v106, v50
	v_pk_mul_f32 v[108:109], v[14:15], v[14:15]
	v_add_f32_e32 v50, v107, v50
	v_pk_add_f32 v[44:45], v[44:45], v[48:49] op_sel_hi:[1,0] neg_lo:[0,1] neg_hi:[0,1]
	v_add_f32_e32 v50, v108, v50
	v_pk_mul_f32 v[110:111], v[44:45], v[44:45]
	v_add_f32_e32 v50, v109, v50
	v_pk_add_f32 v[18:19], v[18:19], v[48:49] op_sel_hi:[1,0] neg_lo:[0,1] neg_hi:[0,1]
	v_add_f32_e32 v50, v110, v50
	v_pk_mul_f32 v[114:115], v[18:19], v[18:19]
	v_add_f32_e32 v50, v111, v50
	v_pk_add_f32 v[22:23], v[22:23], v[48:49] op_sel_hi:[1,0] neg_lo:[0,1] neg_hi:[0,1]
	v_add_f32_e32 v50, v114, v50
	v_pk_mul_f32 v[126:127], v[22:23], v[22:23]
	v_add_f32_e32 v50, v115, v50
	v_pk_add_f32 v[24:25], v[24:25], v[48:49] op_sel_hi:[1,0] neg_lo:[0,1] neg_hi:[0,1]
	v_add_f32_e32 v50, v126, v50
	v_pk_mul_f32 v[128:129], v[24:25], v[24:25]
	v_add_f32_e32 v50, v127, v50
	v_pk_add_f32 v[28:29], v[28:29], v[48:49] op_sel_hi:[1,0] neg_lo:[0,1] neg_hi:[0,1]
	v_add_f32_e32 v50, v128, v50
	v_pk_mul_f32 v[130:131], v[28:29], v[28:29]
	v_add_f32_e32 v50, v129, v50
	v_pk_add_f32 v[26:27], v[26:27], v[48:49] op_sel_hi:[1,0] neg_lo:[0,1] neg_hi:[0,1]
	v_add_f32_e32 v50, v130, v50
	v_pk_mul_f32 v[132:133], v[26:27], v[26:27]
	v_add_f32_e32 v50, v131, v50
	v_pk_add_f32 v[30:31], v[30:31], v[48:49] op_sel_hi:[1,0] neg_lo:[0,1] neg_hi:[0,1]
	v_add_f32_e32 v50, v132, v50
	v_pk_mul_f32 v[134:135], v[30:31], v[30:31]
	v_add_f32_e32 v50, v133, v50
	v_pk_add_f32 v[46:47], v[46:47], v[48:49] op_sel_hi:[1,0] neg_lo:[0,1] neg_hi:[0,1]
	v_add_f32_e32 v50, v134, v50
	v_pk_mul_f32 v[136:137], v[46:47], v[46:47]
	v_add_f32_e32 v50, v135, v50
	v_pk_add_f32 v[16:17], v[16:17], v[48:49] op_sel_hi:[1,0] neg_lo:[0,1] neg_hi:[0,1]
	v_add_f32_e32 v50, v136, v50
	v_pk_add_f32 v[138:139], v[38:39], v[48:49] op_sel_hi:[1,0] neg_lo:[0,1] neg_hi:[0,1]
	v_pk_mul_f32 v[48:49], v[16:17], v[16:17]
	v_add_f32_e32 v50, v137, v50
	v_add_f32_e32 v48, v48, v50
	v_pk_mul_f32 v[38:39], v[138:139], v[138:139]
	v_add_f32_e32 v48, v49, v48
	v_add_f32_e32 v38, v38, v48
	v_add_f32_e32 v38, v39, v38
	ds_bpermute_b32 v39, v79, v38
	v_cvt_f32_f16_sdwa v105, v119 dst_sel:DWORD dst_unused:UNUSED_PAD src0_sel:WORD_1
	v_cvt_f32_f16_e32 v104, v119
	v_cvt_f32_f16_sdwa v107, v118 dst_sel:DWORD dst_unused:UNUSED_PAD src0_sel:WORD_1
	v_cvt_f32_f16_e32 v106, v118
	s_waitcnt lgkmcnt(0)
	v_add_f32_e32 v38, v38, v39
	ds_bpermute_b32 v39, v80, v38
	v_cvt_f32_f16_sdwa v119, v65 dst_sel:DWORD dst_unused:UNUSED_PAD src0_sel:WORD_1
	v_cvt_f32_f16_e32 v118, v65
	v_cvt_f32_f16_sdwa v65, v64 dst_sel:DWORD dst_unused:UNUSED_PAD src0_sel:WORD_1
	v_cvt_f32_f16_e32 v64, v64
	s_waitcnt lgkmcnt(0)
	v_add_f32_e32 v38, v38, v39
	ds_bpermute_b32 v39, v81, v38
	v_cvt_f32_f16_sdwa v55, v120 dst_sel:DWORD dst_unused:UNUSED_PAD src0_sel:WORD_1
	v_cvt_f32_f16_e32 v54, v120
	v_cvt_f32_f16_sdwa v109, v117 dst_sel:DWORD dst_unused:UNUSED_PAD src0_sel:WORD_1
	v_cvt_f32_f16_e32 v108, v117
	s_waitcnt lgkmcnt(0)
	v_add_f32_e32 v38, v38, v39
	ds_bpermute_b32 v39, v82, v38
	v_cvt_f32_f16_sdwa v111, v116 dst_sel:DWORD dst_unused:UNUSED_PAD src0_sel:WORD_1
	v_cvt_f32_f16_e32 v110, v116
	v_cvt_f32_f16_sdwa v115, v113 dst_sel:DWORD dst_unused:UNUSED_PAD src0_sel:WORD_1
	v_cvt_f32_f16_e32 v114, v113
	s_waitcnt lgkmcnt(0)
	v_add_f32_e32 v38, v38, v39
	ds_bpermute_b32 v39, v83, v38
	v_cvt_f32_f16_sdwa v113, v112 dst_sel:DWORD dst_unused:UNUSED_PAD src0_sel:WORD_1
	v_cvt_f32_f16_e32 v112, v112
	v_cvt_f32_f16_sdwa v117, v67 dst_sel:DWORD dst_unused:UNUSED_PAD src0_sel:WORD_1
	v_cvt_f32_f16_e32 v116, v67
	s_waitcnt lgkmcnt(0)
	v_add_f32_e32 v38, v38, v39
	ds_bpermute_b32 v39, v84, v38
	v_cvt_f32_f16_sdwa v67, v66 dst_sel:DWORD dst_unused:UNUSED_PAD src0_sel:WORD_1
	v_cvt_f32_f16_e32 v66, v66
	s_waitcnt lgkmcnt(0)
	v_add_f32_e32 v38, v38, v39
	v_fmamk_f32 v38, v38, 0x3a000000, v101
	v_mul_f32_e32 v39, 0x4f800000, v38
	v_cmp_gt_f32_e32 vcc, s7, v38
	s_nop 1
	v_cndmask_b32_e32 v38, v38, v39, vcc
	v_sqrt_f32_e32 v39, v38
	s_nop 0
	v_add_u32_e32 v48, -1, v39
	v_fma_f32 v49, -v48, v39, v38
	v_cmp_ge_f32_e64 s[0:1], 0, v49
	v_add_u32_e32 v49, 1, v39
	s_nop 0
	v_cndmask_b32_e64 v48, v39, v48, s[0:1]
	v_fma_f32 v39, -v49, v39, v38
	v_cmp_lt_f32_e64 s[0:1], 0, v39
	s_nop 1
	v_cndmask_b32_e64 v39, v48, v49, s[0:1]
	v_mul_f32_e32 v48, 0x37800000, v39
	v_cndmask_b32_e32 v39, v39, v48, vcc
	v_cmp_class_f32_e32 vcc, v38, v102
	s_nop 1
	v_cndmask_b32_e32 v38, v39, v38, vcc
	v_div_scale_f32 v39, s[0:1], v38, v38, 1.0
	v_rcp_f32_e32 v50, v39
	s_add_u32 s0, s20, s14
	s_addc_u32 s1, s21, s15
	v_lshl_add_u64 v[48:49], s[0:1], 0, v[36:37]
	v_fma_f32 v51, -v39, v50, 1.0
	v_fmac_f32_e32 v50, v51, v50
	v_div_scale_f32 v51, vcc, 1.0, v38, 1.0
	v_mul_f32_e32 v52, v51, v50
	v_fma_f32 v53, -v39, v52, v51
	v_fmac_f32_e32 v52, v53, v50
	v_fma_f32 v39, -v39, v52, v51
	v_div_fmas_f32 v39, v39, v50, v52
	v_div_fixup_f32 v50, v39, v38, 1.0
	v_pk_mul_f32 v[20:21], v[20:21], v[50:51] op_sel_hi:[1,0]
	v_pk_mul_f32 v[8:9], v[8:9], v[50:51] op_sel_hi:[1,0]
	v_pk_fma_f32 v[0:1], v[172:173], v[20:21], v[204:205]
	v_pk_fma_f32 v[2:3], v[174:175], v[8:9], v[206:207]
	global_store_dwordx4 v[48:49], v[0:3], off
	s_nop 1
	s_nop 0
	v_pk_mul_f32 v[8:9], v[10:11], v[50:51] op_sel_hi:[1,0]
	v_pk_mul_f32 v[10:11], v[40:41], v[50:51] op_sel_hi:[1,0]
	v_add_co_u32_e32 v38, vcc, s12, v32
	s_or_b32 s0, s10, 1
	s_nop 0
	v_addc_co_u32_e32 v39, vcc, 0, v33, vcc
	v_add_co_u32_e32 v40, vcc, s12, v34
	s_ashr_i32 s1, s0, 31
	s_nop 0
	v_addc_co_u32_e32 v41, vcc, 0, v35, vcc
	s_lshl_b64 s[14:15], s[0:1], 11
	v_cvt_f32_f16_sdwa v53, v121 dst_sel:DWORD dst_unused:UNUSED_PAD src0_sel:WORD_1
	v_cvt_f32_f16_e32 v52, v121
	s_lshl_b64 s[0:1], s[0:1], 13
	v_pk_fma_f32 v[0:1], v[176:177], v[10:11], v[208:209]
	v_pk_fma_f32 v[2:3], v[178:179], v[8:9], v[210:211]
	global_store_dwordx4 v[48:49], v[0:3], off offset:16
	s_nop 1
	s_nop 0
	v_pk_mul_f32 v[8:9], v[14:15], v[50:51] op_sel_hi:[1,0]
	v_pk_mul_f32 v[10:11], v[12:13], v[50:51] op_sel_hi:[1,0]
	v_pk_mul_f32 v[12:13], v[22:23], v[50:51] op_sel_hi:[1,0]
	v_pk_mul_f32 v[14:15], v[16:17], v[50:51] op_sel_hi:[1,0]
	v_pk_fma_f32 v[0:1], v[180:181], v[10:11], v[212:213]
	v_pk_fma_f32 v[2:3], v[182:183], v[8:9], v[214:215]
	global_store_dwordx4 v[48:49], v[0:3], off offset:32
	s_nop 1
	s_nop 0
	v_pk_mul_f32 v[8:9], v[18:19], v[50:51] op_sel_hi:[1,0]
	v_pk_mul_f32 v[10:11], v[44:45], v[50:51] op_sel_hi:[1,0]
	v_pk_fma_f32 v[2:3], v[186:187], v[8:9], v[218:219]
	v_pk_fma_f32 v[0:1], v[184:185], v[10:11], v[216:217]
	global_store_dwordx4 v[48:49], v[0:3], off offset:48
	s_nop 1
	s_nop 0
	v_add_co_u32_e32 v8, vcc, s12, v48
	v_pk_mul_f32 v[10:11], v[24:25], v[50:51] op_sel_hi:[1,0]
	s_nop 0
	v_addc_co_u32_e32 v9, vcc, 0, v49, vcc
	v_cvt_f32_f16_sdwa v49, v123 dst_sel:DWORD dst_unused:UNUSED_PAD src0_sel:WORD_1
	v_cvt_f32_f16_e32 v48, v123
	v_pk_fma_f32 v[0:1], v[188:189], v[12:13], v[220:221]
	v_pk_fma_f32 v[2:3], v[190:191], v[10:11], v[222:223]
	global_store_dwordx4 v[8:9], v[0:3], off
	s_nop 1
	s_nop 0
	v_pk_mul_f32 v[10:11], v[26:27], v[50:51] op_sel_hi:[1,0]
	v_pk_mul_f32 v[12:13], v[28:29], v[50:51] op_sel_hi:[1,0]
	v_pk_fma_f32 v[2:3], v[194:195], v[10:11], v[226:227]
	v_pk_fma_f32 v[0:1], v[192:193], v[12:13], v[224:225]
	global_store_dwordx4 v[8:9], v[0:3], off offset:16
	s_nop 1
	s_nop 0
	v_pk_mul_f32 v[10:11], v[46:47], v[50:51] op_sel_hi:[1,0]
	v_pk_mul_f32 v[12:13], v[30:31], v[50:51] op_sel_hi:[1,0]
	v_pk_fma_f32 v[2:3], v[198:199], v[10:11], v[230:231]
	v_pk_fma_f32 v[0:1], v[196:197], v[12:13], v[228:229]
	global_store_dwordx4 v[8:9], v[0:3], off offset:32
	s_nop 1
	s_nop 0
	v_lshl_add_u64 v[10:11], s[14:15], 0, v[42:43]
	v_pk_mul_f32 v[12:13], v[138:139], v[50:51] op_sel_hi:[1,0]
	v_lshlrev_b64 v[10:11], 1, v[10:11]
	v_lshl_add_u64 v[44:45], s[70:71], 0, v[10:11]
	v_lshl_add_u64 v[46:47], s[2:3], 0, v[10:11]
	v_cvt_f32_f16_sdwa v51, v122 dst_sel:DWORD dst_unused:UNUSED_PAD src0_sel:WORD_1
	v_cvt_f32_f16_e32 v50, v122
	s_add_u32 s14, s20, s0
	s_addc_u32 s15, s21, s1
	v_pk_fma_f32 v[0:1], v[200:201], v[14:15], v[232:233]
	v_pk_fma_f32 v[2:3], v[202:203], v[12:13], v[234:235]
	global_store_dwordx4 v[8:9], v[0:3], off offset:48
	s_nop 1
	global_load_dwordx4 v[4:7], v[44:45], off offset:2064
	s_nop 0
	global_load_dwordx4 v[0:3], v[46:47], off offset:2064
	global_load_dwordx4 v[28:31], v[44:45], off
	global_load_dwordx4 v[24:27], v[46:47], off
	global_load_dwordx4 v[20:23], v[44:45], off offset:16
	global_load_dwordx4 v[16:19], v[46:47], off offset:16
	global_load_dwordx4 v[12:15], v[44:45], off offset:2048
	global_load_dwordx4 v[8:11], v[46:47], off offset:2048
	v_cvt_f32_f16_sdwa v45, v125 dst_sel:DWORD dst_unused:UNUSED_PAD src0_sel:WORD_1
	v_cvt_f32_f16_e32 v44, v125
	v_cvt_f32_f16_sdwa v47, v124 dst_sel:DWORD dst_unused:UNUSED_PAD src0_sel:WORD_1
	v_cvt_f32_f16_e32 v46, v124
	s_waitcnt vmcnt(6)
	v_and_b32_e32 v123, 0xffff0000, v2
	v_lshlrev_b32_e32 v122, 16, v2
	s_waitcnt vmcnt(5)
	v_lshlrev_b32_e32 v124, 16, v28
	v_and_b32_e32 v125, 0xffff0000, v28
	s_waitcnt vmcnt(4)
	v_lshlrev_b32_e32 v126, 16, v24
	v_and_b32_e32 v121, 0xffff0000, v6
	v_lshlrev_b32_e32 v120, 16, v6
	v_and_b32_e32 v127, 0xffff0000, v24
	v_and_b32_e32 v129, 0xffff0000, v7
	v_lshlrev_b32_e32 v128, 16, v7
	v_and_b32_e32 v7, 0xffff0000, v3
	v_lshlrev_b32_e32 v6, 16, v3
	v_lshlrev_b32_e32 v2, 16, v30
	v_and_b32_e32 v3, 0xffff0000, v30
	v_lshlrev_b32_e32 v130, 16, v26
	v_and_b32_e32 v131, 0xffff0000, v26
	v_lshlrev_b32_e32 v30, 16, v31
	v_and_b32_e32 v31, 0xffff0000, v31
	v_lshlrev_b32_e32 v26, 16, v27
	v_and_b32_e32 v27, 0xffff0000, v27
	v_lshlrev_b32_e32 v166, 16, v4
	v_and_b32_e32 v167, 0xffff0000, v4
	v_lshlrev_b32_e32 v168, 16, v0
	v_and_b32_e32 v169, 0xffff0000, v0
	v_lshlrev_b32_e32 v4, 16, v5
	v_and_b32_e32 v5, 0xffff0000, v5
	v_lshlrev_b32_e32 v0, 16, v1
	v_and_b32_e32 v1, 0xffff0000, v1
	v_pk_fma_f32 v[120:121], v[120:121], s[6:7], v[122:123] op_sel_hi:[1,0,1]
	v_pk_fma_f32 v[122:123], v[124:125], s[6:7], v[126:127] op_sel_hi:[1,0,1]
	v_lshlrev_b32_e32 v28, 16, v29
	v_and_b32_e32 v29, 0xffff0000, v29
	v_lshlrev_b32_e32 v24, 16, v25
	v_and_b32_e32 v25, 0xffff0000, v25
	v_pk_fma_f32 v[6:7], v[128:129], s[6:7], v[6:7] op_sel_hi:[1,0,1]
	v_pk_fma_f32 v[26:27], v[30:31], s[6:7], v[26:27] op_sel_hi:[1,0,1]
	v_pk_fma_f32 v[0:1], v[4:5], s[6:7], v[0:1] op_sel_hi:[1,0,1]
	v_pk_add_f32 v[30:31], v[120:121], v[44:45]
	v_pk_add_f32 v[44:45], v[122:123], v[46:47]
	v_pk_fma_f32 v[24:25], v[28:29], s[6:7], v[24:25] op_sel_hi:[1,0,1]
	v_pk_add_f32 v[46:47], v[6:7], v[50:51]
	v_pk_add_f32 v[50:51], v[0:1], v[64:65]
	v_add_f32_e32 v0, 0, v44
	v_pk_add_f32 v[24:25], v[24:25], v[48:49]
	v_add_f32_e32 v0, v45, v0
	v_pk_fma_f32 v[2:3], v[2:3], s[6:7], v[130:131] op_sel_hi:[1,0,1]
	v_add_f32_e32 v0, v24, v0
	v_pk_add_f32 v[48:49], v[2:3], v[52:53]
	v_add_f32_e32 v0, v25, v0
	v_add_f32_e32 v0, v48, v0
	s_waitcnt vmcnt(3)
	v_lshlrev_b32_e32 v132, 16, v20
	v_and_b32_e32 v133, 0xffff0000, v20
	s_waitcnt vmcnt(2)
	v_lshlrev_b32_e32 v134, 16, v16
	v_and_b32_e32 v135, 0xffff0000, v16
	v_pk_add_f32 v[26:27], v[26:27], v[54:55]
	v_add_f32_e32 v0, v49, v0
	v_pk_fma_f32 v[28:29], v[132:133], s[6:7], v[134:135] op_sel_hi:[1,0,1]
	v_add_f32_e32 v0, v26, v0
	v_lshlrev_b32_e32 v20, 16, v21
	v_and_b32_e32 v21, 0xffff0000, v21
	v_lshlrev_b32_e32 v16, 16, v17
	v_and_b32_e32 v17, 0xffff0000, v17
	v_pk_add_f32 v[28:29], v[28:29], v[104:105]
	v_add_f32_e32 v0, v27, v0
	v_pk_fma_f32 v[16:17], v[20:21], s[6:7], v[16:17] op_sel_hi:[1,0,1]
	v_add_f32_e32 v0, v28, v0
	v_lshlrev_b32_e32 v136, 16, v22
	v_and_b32_e32 v137, 0xffff0000, v22
	v_lshlrev_b32_e32 v138, 16, v18
	v_and_b32_e32 v139, 0xffff0000, v18
	v_pk_add_f32 v[16:17], v[16:17], v[106:107]
	v_add_f32_e32 v0, v29, v0
	v_pk_fma_f32 v[20:21], v[136:137], s[6:7], v[138:139] op_sel_hi:[1,0,1]
	v_add_f32_e32 v0, v16, v0
	v_lshlrev_b32_e32 v22, 16, v23
	v_and_b32_e32 v23, 0xffff0000, v23
	v_lshlrev_b32_e32 v18, 16, v19
	v_and_b32_e32 v19, 0xffff0000, v19
	v_pk_add_f32 v[20:21], v[20:21], v[108:109]
	v_add_f32_e32 v0, v17, v0
	v_pk_fma_f32 v[18:19], v[22:23], s[6:7], v[18:19] op_sel_hi:[1,0,1]
	v_add_f32_e32 v0, v20, v0
	s_waitcnt vmcnt(1)
	v_lshlrev_b32_e32 v150, 16, v12
	v_and_b32_e32 v151, 0xffff0000, v12
	s_waitcnt vmcnt(0)
	v_lshlrev_b32_e32 v152, 16, v8
	v_and_b32_e32 v153, 0xffff0000, v8
	v_pk_add_f32 v[18:19], v[18:19], v[110:111]
	v_add_f32_e32 v0, v21, v0
	v_pk_fma_f32 v[22:23], v[150:151], s[6:7], v[152:153] op_sel_hi:[1,0,1]
	v_add_f32_e32 v0, v18, v0
	v_lshlrev_b32_e32 v12, 16, v13
	v_and_b32_e32 v13, 0xffff0000, v13
	v_lshlrev_b32_e32 v8, 16, v9
	v_and_b32_e32 v9, 0xffff0000, v9
	v_pk_add_f32 v[22:23], v[22:23], v[114:115]
	v_add_f32_e32 v0, v19, v0
	v_pk_fma_f32 v[8:9], v[12:13], s[6:7], v[8:9] op_sel_hi:[1,0,1]
	v_add_f32_e32 v0, v22, v0
	v_lshlrev_b32_e32 v154, 16, v14
	v_and_b32_e32 v155, 0xffff0000, v14
	v_lshlrev_b32_e32 v164, 16, v10
	v_and_b32_e32 v165, 0xffff0000, v10
	v_pk_add_f32 v[8:9], v[8:9], v[112:113]
	v_add_f32_e32 v0, v23, v0
	v_pk_fma_f32 v[12:13], v[154:155], s[6:7], v[164:165] op_sel_hi:[1,0,1]
	v_add_f32_e32 v0, v8, v0
	v_lshlrev_b32_e32 v14, 16, v15
	v_and_b32_e32 v15, 0xffff0000, v15
	v_lshlrev_b32_e32 v10, 16, v11
	v_and_b32_e32 v11, 0xffff0000, v11
	v_pk_add_f32 v[12:13], v[12:13], v[116:117]
	v_add_f32_e32 v0, v9, v0
	v_pk_fma_f32 v[10:11], v[14:15], s[6:7], v[10:11] op_sel_hi:[1,0,1]
	v_add_f32_e32 v0, v12, v0
	v_pk_add_f32 v[10:11], v[10:11], v[66:67]
	v_add_f32_e32 v0, v13, v0
	v_pk_fma_f32 v[14:15], v[166:167], s[6:7], v[168:169] op_sel_hi:[1,0,1]
	v_add_f32_e32 v0, v10, v0
	v_pk_add_f32 v[14:15], v[14:15], v[118:119]
	v_add_f32_e32 v0, v11, v0
	v_add_f32_e32 v0, v14, v0
	v_add_f32_e32 v0, v15, v0
	v_add_f32_e32 v0, v50, v0
	v_add_f32_e32 v0, v51, v0
	v_add_f32_e32 v0, v30, v0
	v_add_f32_e32 v0, v31, v0
	v_add_f32_e32 v0, v46, v0
	v_add_f32_e32 v0, v47, v0
	ds_bpermute_b32 v1, v79, v0
	s_waitcnt lgkmcnt(0)
	v_add_f32_e32 v0, v0, v1
	ds_bpermute_b32 v1, v80, v0
	s_waitcnt lgkmcnt(0)
	v_add_f32_e32 v0, v0, v1
	ds_bpermute_b32 v1, v81, v0
	s_waitcnt lgkmcnt(0)
	v_add_f32_e32 v0, v0, v1
	ds_bpermute_b32 v1, v82, v0
	s_waitcnt lgkmcnt(0)
	v_add_f32_e32 v0, v0, v1
	ds_bpermute_b32 v1, v83, v0
	s_waitcnt lgkmcnt(0)
	v_add_f32_e32 v52, v0, v1
	ds_bpermute_b32 v53, v84, v52
	s_waitcnt lgkmcnt(0)
	v_add_f32_e32 v52, v52, v53
	v_mul_f32_e32 v52, 0x3a000000, v52
	v_pk_add_f32 v[44:45], v[44:45], v[52:53] op_sel_hi:[1,0] neg_lo:[0,1] neg_hi:[0,1]
	v_pk_add_f32 v[24:25], v[24:25], v[52:53] op_sel_hi:[1,0] neg_lo:[0,1] neg_hi:[0,1]
	v_pk_add_f32 v[48:49], v[48:49], v[52:53] op_sel_hi:[1,0] neg_lo:[0,1] neg_hi:[0,1]
	v_pk_add_f32 v[26:27], v[26:27], v[52:53] op_sel_hi:[1,0] neg_lo:[0,1] neg_hi:[0,1]
	v_pk_add_f32 v[28:29], v[28:29], v[52:53] op_sel_hi:[1,0] neg_lo:[0,1] neg_hi:[0,1]
	v_pk_add_f32 v[16:17], v[16:17], v[52:53] op_sel_hi:[1,0] neg_lo:[0,1] neg_hi:[0,1]
	v_pk_add_f32 v[20:21], v[20:21], v[52:53] op_sel_hi:[1,0] neg_lo:[0,1] neg_hi:[0,1]
	v_pk_add_f32 v[18:19], v[18:19], v[52:53] op_sel_hi:[1,0] neg_lo:[0,1] neg_hi:[0,1]
	v_pk_add_f32 v[22:23], v[22:23], v[52:53] op_sel_hi:[1,0] neg_lo:[0,1] neg_hi:[0,1]
	v_pk_add_f32 v[8:9], v[8:9], v[52:53] op_sel_hi:[1,0] neg_lo:[0,1] neg_hi:[0,1]
	v_pk_add_f32 v[12:13], v[12:13], v[52:53] op_sel_hi:[1,0] neg_lo:[0,1] neg_hi:[0,1]
	v_pk_add_f32 v[10:11], v[10:11], v[52:53] op_sel_hi:[1,0] neg_lo:[0,1] neg_hi:[0,1]
	v_pk_add_f32 v[14:15], v[14:15], v[52:53] op_sel_hi:[1,0] neg_lo:[0,1] neg_hi:[0,1]
	v_pk_add_f32 v[50:51], v[50:51], v[52:53] op_sel_hi:[1,0] neg_lo:[0,1] neg_hi:[0,1]
	v_pk_add_f32 v[46:47], v[46:47], v[52:53] op_sel_hi:[1,0] neg_lo:[0,1] neg_hi:[0,1]
	v_pk_add_f32 v[30:31], v[30:31], v[52:53] op_sel_hi:[1,0] neg_lo:[0,1] neg_hi:[0,1]
	v_pk_mul_f32 v[52:53], v[44:45], v[44:45]
	v_pk_mul_f32 v[54:55], v[24:25], v[24:25]
	v_add_f32_e32 v52, v52, v53
	v_add_f32_e32 v52, v54, v52
	v_pk_mul_f32 v[64:65], v[48:49], v[48:49]
	v_add_f32_e32 v52, v55, v52
	v_add_f32_e32 v52, v64, v52
	v_pk_mul_f32 v[66:67], v[26:27], v[26:27]
	v_add_f32_e32 v52, v65, v52
	v_add_f32_e32 v52, v66, v52
	v_pk_mul_f32 v[104:105], v[28:29], v[28:29]
	v_add_f32_e32 v52, v67, v52
	v_add_f32_e32 v52, v104, v52
	v_pk_mul_f32 v[106:107], v[16:17], v[16:17]
	v_add_f32_e32 v52, v105, v52
	v_add_f32_e32 v52, v106, v52
	v_pk_mul_f32 v[108:109], v[20:21], v[20:21]
	v_add_f32_e32 v52, v107, v52
	v_add_f32_e32 v52, v108, v52
	v_pk_mul_f32 v[110:111], v[18:19], v[18:19]
	v_add_f32_e32 v52, v109, v52
	v_add_f32_e32 v52, v110, v52
	v_pk_mul_f32 v[112:113], v[22:23], v[22:23]
	v_add_f32_e32 v52, v111, v52
	v_add_f32_e32 v52, v112, v52
	v_pk_mul_f32 v[114:115], v[8:9], v[8:9]
	v_add_f32_e32 v52, v113, v52
	v_add_f32_e32 v52, v114, v52
	v_pk_mul_f32 v[116:117], v[12:13], v[12:13]
	v_add_f32_e32 v52, v115, v52
	v_add_f32_e32 v52, v116, v52
	v_pk_mul_f32 v[118:119], v[10:11], v[10:11]
	v_add_f32_e32 v52, v117, v52
	v_add_f32_e32 v52, v118, v52
	v_pk_mul_f32 v[120:121], v[14:15], v[14:15]
	v_add_f32_e32 v52, v119, v52
	v_add_f32_e32 v52, v120, v52
	v_pk_mul_f32 v[122:123], v[50:51], v[50:51]
	v_add_f32_e32 v52, v121, v52
	v_add_f32_e32 v52, v122, v52
	v_pk_mul_f32 v[126:127], v[30:31], v[30:31]
	v_add_f32_e32 v52, v123, v52
	v_add_f32_e32 v52, v126, v52
	v_pk_mul_f32 v[124:125], v[46:47], v[46:47]
	v_add_f32_e32 v52, v127, v52
	v_add_f32_e32 v52, v124, v52
	v_add_f32_e32 v52, v125, v52
	ds_bpermute_b32 v53, v79, v52
	s_waitcnt lgkmcnt(0)
	v_add_f32_e32 v52, v52, v53
	ds_bpermute_b32 v53, v80, v52
	s_waitcnt lgkmcnt(0)
	v_add_f32_e32 v52, v52, v53
	ds_bpermute_b32 v53, v81, v52
	s_waitcnt lgkmcnt(0)
	v_add_f32_e32 v52, v52, v53
	ds_bpermute_b32 v53, v82, v52
	s_waitcnt lgkmcnt(0)
	v_add_f32_e32 v52, v52, v53
	ds_bpermute_b32 v53, v83, v52
	s_waitcnt lgkmcnt(0)
	v_add_f32_e32 v52, v52, v53
	ds_bpermute_b32 v53, v84, v52
	s_waitcnt lgkmcnt(0)
	v_add_f32_e32 v52, v52, v53
	v_fmamk_f32 v52, v52, 0x3a000000, v101
	v_mul_f32_e32 v53, 0x4f800000, v52
	v_cmp_gt_f32_e32 vcc, s7, v52
	s_nop 1
	v_cndmask_b32_e32 v52, v52, v53, vcc
	v_sqrt_f32_e32 v53, v52
	s_nop 0
	v_add_u32_e32 v54, -1, v53
	v_add_u32_e32 v55, 1, v53
	v_fma_f32 v64, -v54, v53, v52
	v_fma_f32 v65, -v55, v53, v52
	v_cmp_ge_f32_e64 s[0:1], 0, v64
	s_nop 1
	v_cndmask_b32_e64 v53, v53, v54, s[0:1]
	v_cmp_lt_f32_e64 s[0:1], 0, v65
	s_nop 1
	v_cndmask_b32_e64 v53, v53, v55, s[0:1]
	v_mul_f32_e32 v54, 0x37800000, v53
	v_cndmask_b32_e32 v53, v53, v54, vcc
	v_cmp_class_f32_e32 vcc, v52, v102
	s_nop 1
	v_cndmask_b32_e32 v54, v53, v52, vcc
	v_div_scale_f32 v55, s[0:1], v54, v54, 1.0
	v_rcp_f32_e32 v64, v55
	v_div_scale_f32 v65, vcc, 1.0, v54, 1.0
	v_lshl_add_u64 v[52:53], s[14:15], 0, v[36:37]
	v_fma_f32 v66, -v55, v64, 1.0
	v_fmac_f32_e32 v64, v66, v64
	v_mul_f32_e32 v66, v65, v64
	v_fma_f32 v67, -v55, v66, v65
	v_fmac_f32_e32 v66, v67, v64
	v_fma_f32 v55, -v55, v66, v65
	v_div_fmas_f32 v55, v55, v64, v66
	v_div_fixup_f32 v54, v55, v54, 1.0
	v_pk_mul_f32 v[44:45], v[44:45], v[54:55] op_sel_hi:[1,0]
	v_pk_mul_f32 v[24:25], v[24:25], v[54:55] op_sel_hi:[1,0]
	v_pk_fma_f32 v[0:1], v[172:173], v[44:45], v[204:205]
	v_pk_fma_f32 v[2:3], v[174:175], v[24:25], v[206:207]
	global_store_dwordx4 v[52:53], v[0:3], off
	s_nop 1
	s_nop 0
	v_pk_mul_f32 v[24:25], v[26:27], v[54:55] op_sel_hi:[1,0]
	v_pk_mul_f32 v[26:27], v[48:49], v[54:55] op_sel_hi:[1,0]
	v_pk_mul_f32 v[16:17], v[16:17], v[54:55] op_sel_hi:[1,0]
	v_pk_mul_f32 v[8:9], v[8:9], v[54:55] op_sel_hi:[1,0]
	s_or_b32 s0, s10, 2
	s_ashr_i32 s1, s0, 31
	s_lshl_b64 s[14:15], s[0:1], 11
	v_cvt_f32_f16_sdwa v49, v73 dst_sel:DWORD dst_unused:UNUSED_PAD src0_sel:WORD_1
	v_cvt_f32_f16_e32 v48, v73
	v_cvt_f32_f16_sdwa v65, v69 dst_sel:DWORD dst_unused:UNUSED_PAD src0_sel:WORD_1
	v_cvt_f32_f16_e32 v64, v69
	v_cvt_f32_f16_sdwa v67, v68 dst_sel:DWORD dst_unused:UNUSED_PAD src0_sel:WORD_1
	v_cvt_f32_f16_e32 v66, v68
	v_cvt_f32_f16_sdwa v69, v63 dst_sel:DWORD dst_unused:UNUSED_PAD src0_sel:WORD_1
	v_cvt_f32_f16_e32 v68, v63
	v_cvt_f32_f16_sdwa v63, v62 dst_sel:DWORD dst_unused:UNUSED_PAD src0_sel:WORD_1
	v_cvt_f32_f16_e32 v62, v62
	v_cvt_f32_f16_sdwa v73, v59 dst_sel:DWORD dst_unused:UNUSED_PAD src0_sel:WORD_1
	s_lshl_b64 s[0:1], s[0:1], 13
	v_pk_fma_f32 v[0:1], v[176:177], v[26:27], v[208:209]
	v_pk_fma_f32 v[2:3], v[178:179], v[24:25], v[210:211]
	global_store_dwordx4 v[52:53], v[0:3], off offset:16
	s_nop 1
	s_nop 0
	v_pk_mul_f32 v[24:25], v[28:29], v[54:55] op_sel_hi:[1,0]
	v_pk_fma_f32 v[2:3], v[182:183], v[16:17], v[214:215]
	v_pk_fma_f32 v[0:1], v[180:181], v[24:25], v[212:213]
	global_store_dwordx4 v[52:53], v[0:3], off offset:32
	s_nop 1
	s_nop 0
	v_pk_mul_f32 v[16:17], v[18:19], v[54:55] op_sel_hi:[1,0]
	v_pk_mul_f32 v[18:19], v[20:21], v[54:55] op_sel_hi:[1,0]
	v_pk_fma_f32 v[2:3], v[186:187], v[16:17], v[218:219]
	v_pk_fma_f32 v[0:1], v[184:185], v[18:19], v[216:217]
	global_store_dwordx4 v[52:53], v[0:3], off offset:48
	s_nop 1
	s_nop 0
	v_add_co_u32_e32 v16, vcc, s12, v52
	v_pk_mul_f32 v[18:19], v[22:23], v[54:55] op_sel_hi:[1,0]
	s_nop 0
	v_addc_co_u32_e32 v17, vcc, 0, v53, vcc
	v_cvt_f32_f16_sdwa v53, v71 dst_sel:DWORD dst_unused:UNUSED_PAD src0_sel:WORD_1
	v_cvt_f32_f16_e32 v52, v71
	v_cvt_f32_f16_sdwa v71, v61 dst_sel:DWORD dst_unused:UNUSED_PAD src0_sel:WORD_1
	v_pk_fma_f32 v[0:1], v[188:189], v[18:19], v[220:221]
	v_pk_fma_f32 v[2:3], v[190:191], v[8:9], v[222:223]
	global_store_dwordx4 v[16:17], v[0:3], off
	s_nop 1
	s_nop 0
	v_pk_mul_f32 v[8:9], v[10:11], v[54:55] op_sel_hi:[1,0]
	v_pk_mul_f32 v[10:11], v[12:13], v[54:55] op_sel_hi:[1,0]
	v_pk_mul_f32 v[12:13], v[30:31], v[54:55] op_sel_hi:[1,0]
	v_pk_fma_f32 v[0:1], v[192:193], v[10:11], v[224:225]
	v_pk_fma_f32 v[2:3], v[194:195], v[8:9], v[226:227]
	global_store_dwordx4 v[16:17], v[0:3], off offset:16
	s_nop 1
	s_nop 0
	v_pk_mul_f32 v[8:9], v[50:51], v[54:55] op_sel_hi:[1,0]
	v_pk_mul_f32 v[10:11], v[14:15], v[54:55] op_sel_hi:[1,0]
	v_cvt_f32_f16_sdwa v51, v72 dst_sel:DWORD dst_unused:UNUSED_PAD src0_sel:WORD_1
	v_cvt_f32_f16_e32 v50, v72
	v_cvt_f32_f16_e32 v72, v59
	v_cvt_f32_f16_sdwa v59, v58 dst_sel:DWORD dst_unused:UNUSED_PAD src0_sel:WORD_1
	v_cvt_f32_f16_e32 v58, v58
	v_pk_fma_f32 v[0:1], v[196:197], v[10:11], v[228:229]
	v_pk_fma_f32 v[2:3], v[198:199], v[8:9], v[230:231]
	global_store_dwordx4 v[16:17], v[0:3], off offset:32
	s_nop 1
	s_nop 0
	v_lshl_add_u64 v[8:9], s[14:15], 0, v[42:43]
	v_pk_mul_f32 v[10:11], v[46:47], v[54:55] op_sel_hi:[1,0]
	v_lshlrev_b64 v[8:9], 1, v[8:9]
	v_lshl_add_u64 v[44:45], s[70:71], 0, v[8:9]
	v_lshl_add_u64 v[46:47], s[2:3], 0, v[8:9]
	v_cvt_f32_f16_sdwa v55, v70 dst_sel:DWORD dst_unused:UNUSED_PAD src0_sel:WORD_1
	v_cvt_f32_f16_e32 v54, v70
	v_cvt_f32_f16_e32 v70, v61
	v_cvt_f32_f16_sdwa v61, v60 dst_sel:DWORD dst_unused:UNUSED_PAD src0_sel:WORD_1
	v_cvt_f32_f16_e32 v60, v60
	s_add_u32 s14, s20, s0
	s_addc_u32 s15, s21, s1
	v_pk_fma_f32 v[0:1], v[200:201], v[12:13], v[232:233]
	v_pk_fma_f32 v[2:3], v[202:203], v[10:11], v[234:235]
	global_store_dwordx4 v[16:17], v[0:3], off offset:48
	s_nop 1
	global_load_dwordx4 v[4:7], v[44:45], off offset:2064
	s_nop 0
	global_load_dwordx4 v[0:3], v[46:47], off offset:2064
	global_load_dwordx4 v[28:31], v[44:45], off
	global_load_dwordx4 v[24:27], v[46:47], off
	global_load_dwordx4 v[20:23], v[44:45], off offset:16
	global_load_dwordx4 v[16:19], v[46:47], off offset:16
	global_load_dwordx4 v[12:15], v[44:45], off offset:2048
	global_load_dwordx4 v[8:11], v[46:47], off offset:2048
	v_cvt_f32_f16_sdwa v45, v75 dst_sel:DWORD dst_unused:UNUSED_PAD src0_sel:WORD_1
	v_cvt_f32_f16_e32 v44, v75
	v_cvt_f32_f16_sdwa v47, v74 dst_sel:DWORD dst_unused:UNUSED_PAD src0_sel:WORD_1
	v_cvt_f32_f16_e32 v46, v74
	v_cvt_f32_f16_sdwa v75, v57 dst_sel:DWORD dst_unused:UNUSED_PAD src0_sel:WORD_1
	v_cvt_f32_f16_e32 v74, v57
	v_cvt_f32_f16_sdwa v57, v56 dst_sel:DWORD dst_unused:UNUSED_PAD src0_sel:WORD_1
	v_cvt_f32_f16_e32 v56, v56
	s_waitcnt vmcnt(6)
	v_and_b32_e32 v107, 0xffff0000, v2
	v_lshlrev_b32_e32 v106, 16, v2
	s_waitcnt vmcnt(5)
	v_lshlrev_b32_e32 v108, 16, v28
	v_and_b32_e32 v109, 0xffff0000, v28
	s_waitcnt vmcnt(4)
	v_lshlrev_b32_e32 v110, 16, v24
	v_and_b32_e32 v105, 0xffff0000, v6
	v_lshlrev_b32_e32 v104, 16, v6
	v_and_b32_e32 v111, 0xffff0000, v24
	v_and_b32_e32 v113, 0xffff0000, v7
	v_lshlrev_b32_e32 v112, 16, v7
	v_and_b32_e32 v7, 0xffff0000, v3
	v_lshlrev_b32_e32 v6, 16, v3
	v_lshlrev_b32_e32 v2, 16, v30
	v_and_b32_e32 v3, 0xffff0000, v30
	v_lshlrev_b32_e32 v114, 16, v26
	v_and_b32_e32 v115, 0xffff0000, v26
	v_lshlrev_b32_e32 v30, 16, v31
	v_and_b32_e32 v31, 0xffff0000, v31
	v_lshlrev_b32_e32 v26, 16, v27
	v_and_b32_e32 v27, 0xffff0000, v27
	v_lshlrev_b32_e32 v132, 16, v4
	v_and_b32_e32 v133, 0xffff0000, v4
	v_lshlrev_b32_e32 v134, 16, v0
	v_and_b32_e32 v135, 0xffff0000, v0
	v_lshlrev_b32_e32 v4, 16, v5
	v_and_b32_e32 v5, 0xffff0000, v5
	v_lshlrev_b32_e32 v0, 16, v1
	v_and_b32_e32 v1, 0xffff0000, v1
	v_pk_fma_f32 v[104:105], v[104:105], s[6:7], v[106:107] op_sel_hi:[1,0,1]
	v_pk_fma_f32 v[106:107], v[108:109], s[6:7], v[110:111] op_sel_hi:[1,0,1]
	v_lshlrev_b32_e32 v28, 16, v29
	v_and_b32_e32 v29, 0xffff0000, v29
	v_lshlrev_b32_e32 v24, 16, v25
	v_and_b32_e32 v25, 0xffff0000, v25
	v_pk_fma_f32 v[6:7], v[112:113], s[6:7], v[6:7] op_sel_hi:[1,0,1]
	v_pk_fma_f32 v[26:27], v[30:31], s[6:7], v[26:27] op_sel_hi:[1,0,1]
	v_pk_fma_f32 v[0:1], v[4:5], s[6:7], v[0:1] op_sel_hi:[1,0,1]
	v_pk_add_f32 v[30:31], v[104:105], v[44:45]
	v_pk_add_f32 v[44:45], v[106:107], v[46:47]
	v_pk_fma_f32 v[24:25], v[28:29], s[6:7], v[24:25] op_sel_hi:[1,0,1]
	v_pk_add_f32 v[46:47], v[6:7], v[50:51]
	v_pk_add_f32 v[50:51], v[0:1], v[56:57]
	v_add_f32_e32 v0, 0, v44
	v_pk_add_f32 v[24:25], v[24:25], v[48:49]
	v_add_f32_e32 v0, v45, v0
	v_pk_fma_f32 v[2:3], v[2:3], s[6:7], v[114:115] op_sel_hi:[1,0,1]
	v_add_f32_e32 v0, v24, v0
	v_pk_add_f32 v[48:49], v[2:3], v[52:53]
	v_add_f32_e32 v0, v25, v0
	v_add_f32_e32 v0, v48, v0
	s_waitcnt vmcnt(3)
	v_lshlrev_b32_e32 v116, 16, v20
	v_and_b32_e32 v117, 0xffff0000, v20
	s_waitcnt vmcnt(2)
	v_lshlrev_b32_e32 v118, 16, v16
	v_and_b32_e32 v119, 0xffff0000, v16
	v_pk_add_f32 v[26:27], v[26:27], v[54:55]
	v_add_f32_e32 v0, v49, v0
	v_pk_fma_f32 v[28:29], v[116:117], s[6:7], v[118:119] op_sel_hi:[1,0,1]
	v_add_f32_e32 v0, v26, v0
	v_lshlrev_b32_e32 v20, 16, v21
	v_and_b32_e32 v21, 0xffff0000, v21
	v_lshlrev_b32_e32 v16, 16, v17
	v_and_b32_e32 v17, 0xffff0000, v17
	v_pk_add_f32 v[28:29], v[28:29], v[64:65]
	v_add_f32_e32 v0, v27, v0
	v_pk_fma_f32 v[16:17], v[20:21], s[6:7], v[16:17] op_sel_hi:[1,0,1]
	v_add_f32_e32 v0, v28, v0
	v_lshlrev_b32_e32 v120, 16, v22
	v_and_b32_e32 v121, 0xffff0000, v22
	v_lshlrev_b32_e32 v122, 16, v18
	v_and_b32_e32 v123, 0xffff0000, v18
	v_pk_add_f32 v[16:17], v[16:17], v[66:67]
	v_add_f32_e32 v0, v29, v0
	v_pk_fma_f32 v[20:21], v[120:121], s[6:7], v[122:123] op_sel_hi:[1,0,1]
	v_add_f32_e32 v0, v16, v0
	v_lshlrev_b32_e32 v22, 16, v23
	v_and_b32_e32 v23, 0xffff0000, v23
	v_lshlrev_b32_e32 v18, 16, v19
	v_and_b32_e32 v19, 0xffff0000, v19
	v_pk_add_f32 v[20:21], v[20:21], v[68:69]
	v_add_f32_e32 v0, v17, v0
	v_pk_fma_f32 v[18:19], v[22:23], s[6:7], v[18:19] op_sel_hi:[1,0,1]
	v_add_f32_e32 v0, v20, v0
	s_waitcnt vmcnt(1)
	v_lshlrev_b32_e32 v124, 16, v12
	v_and_b32_e32 v125, 0xffff0000, v12
	s_waitcnt vmcnt(0)
	v_lshlrev_b32_e32 v126, 16, v8
	v_and_b32_e32 v127, 0xffff0000, v8
	v_pk_add_f32 v[18:19], v[18:19], v[62:63]
	v_add_f32_e32 v0, v21, v0
	v_pk_fma_f32 v[22:23], v[124:125], s[6:7], v[126:127] op_sel_hi:[1,0,1]
	v_add_f32_e32 v0, v18, v0
	v_lshlrev_b32_e32 v12, 16, v13
	v_and_b32_e32 v13, 0xffff0000, v13
	v_lshlrev_b32_e32 v8, 16, v9
	v_and_b32_e32 v9, 0xffff0000, v9
	v_pk_add_f32 v[22:23], v[22:23], v[70:71]
	v_add_f32_e32 v0, v19, v0
	v_pk_fma_f32 v[8:9], v[12:13], s[6:7], v[8:9] op_sel_hi:[1,0,1]
	v_add_f32_e32 v0, v22, v0
	v_lshlrev_b32_e32 v128, 16, v14
	v_and_b32_e32 v129, 0xffff0000, v14
	v_lshlrev_b32_e32 v130, 16, v10
	v_and_b32_e32 v131, 0xffff0000, v10
	v_pk_add_f32 v[8:9], v[8:9], v[60:61]
	v_add_f32_e32 v0, v23, v0
	v_pk_fma_f32 v[12:13], v[128:129], s[6:7], v[130:131] op_sel_hi:[1,0,1]
	v_add_f32_e32 v0, v8, v0
	v_lshlrev_b32_e32 v14, 16, v15
	v_and_b32_e32 v15, 0xffff0000, v15
	v_lshlrev_b32_e32 v10, 16, v11
	v_and_b32_e32 v11, 0xffff0000, v11
	v_pk_add_f32 v[12:13], v[12:13], v[72:73]
	v_add_f32_e32 v0, v9, v0
	v_pk_fma_f32 v[10:11], v[14:15], s[6:7], v[10:11] op_sel_hi:[1,0,1]
	v_add_f32_e32 v0, v12, v0
	v_pk_add_f32 v[10:11], v[10:11], v[58:59]
	v_add_f32_e32 v0, v13, v0
	v_pk_fma_f32 v[14:15], v[132:133], s[6:7], v[134:135] op_sel_hi:[1,0,1]
	v_add_f32_e32 v0, v10, v0
	v_pk_add_f32 v[14:15], v[14:15], v[74:75]
	v_add_f32_e32 v0, v11, v0
	v_add_f32_e32 v0, v14, v0
	v_add_f32_e32 v0, v15, v0
	v_add_f32_e32 v0, v50, v0
	v_add_f32_e32 v0, v51, v0
	v_add_f32_e32 v0, v30, v0
	v_add_f32_e32 v0, v31, v0
	v_add_f32_e32 v0, v46, v0
	v_add_f32_e32 v0, v47, v0
	ds_bpermute_b32 v1, v79, v0
	s_waitcnt lgkmcnt(0)
	v_add_f32_e32 v0, v0, v1
	ds_bpermute_b32 v1, v80, v0
	s_waitcnt lgkmcnt(0)
	v_add_f32_e32 v0, v0, v1
	ds_bpermute_b32 v1, v81, v0
	s_waitcnt lgkmcnt(0)
	v_add_f32_e32 v0, v0, v1
	ds_bpermute_b32 v1, v82, v0
	s_waitcnt lgkmcnt(0)
	v_add_f32_e32 v0, v0, v1
	ds_bpermute_b32 v1, v83, v0
	s_waitcnt lgkmcnt(0)
	v_add_f32_e32 v52, v0, v1
	ds_bpermute_b32 v53, v84, v52
	s_waitcnt lgkmcnt(0)
	v_add_f32_e32 v52, v52, v53
	v_mul_f32_e32 v52, 0x3a000000, v52
	v_pk_add_f32 v[44:45], v[44:45], v[52:53] op_sel_hi:[1,0] neg_lo:[0,1] neg_hi:[0,1]
	v_pk_add_f32 v[24:25], v[24:25], v[52:53] op_sel_hi:[1,0] neg_lo:[0,1] neg_hi:[0,1]
	v_pk_add_f32 v[48:49], v[48:49], v[52:53] op_sel_hi:[1,0] neg_lo:[0,1] neg_hi:[0,1]
	v_pk_add_f32 v[26:27], v[26:27], v[52:53] op_sel_hi:[1,0] neg_lo:[0,1] neg_hi:[0,1]
	v_pk_add_f32 v[28:29], v[28:29], v[52:53] op_sel_hi:[1,0] neg_lo:[0,1] neg_hi:[0,1]
	v_pk_add_f32 v[16:17], v[16:17], v[52:53] op_sel_hi:[1,0] neg_lo:[0,1] neg_hi:[0,1]
	v_pk_add_f32 v[20:21], v[20:21], v[52:53] op_sel_hi:[1,0] neg_lo:[0,1] neg_hi:[0,1]
	v_pk_add_f32 v[18:19], v[18:19], v[52:53] op_sel_hi:[1,0] neg_lo:[0,1] neg_hi:[0,1]
	v_pk_add_f32 v[22:23], v[22:23], v[52:53] op_sel_hi:[1,0] neg_lo:[0,1] neg_hi:[0,1]
	v_pk_add_f32 v[8:9], v[8:9], v[52:53] op_sel_hi:[1,0] neg_lo:[0,1] neg_hi:[0,1]
	v_pk_add_f32 v[12:13], v[12:13], v[52:53] op_sel_hi:[1,0] neg_lo:[0,1] neg_hi:[0,1]
	v_pk_add_f32 v[10:11], v[10:11], v[52:53] op_sel_hi:[1,0] neg_lo:[0,1] neg_hi:[0,1]
	v_pk_add_f32 v[14:15], v[14:15], v[52:53] op_sel_hi:[1,0] neg_lo:[0,1] neg_hi:[0,1]
	v_pk_add_f32 v[50:51], v[50:51], v[52:53] op_sel_hi:[1,0] neg_lo:[0,1] neg_hi:[0,1]
	v_pk_add_f32 v[46:47], v[46:47], v[52:53] op_sel_hi:[1,0] neg_lo:[0,1] neg_hi:[0,1]
	v_pk_add_f32 v[30:31], v[30:31], v[52:53] op_sel_hi:[1,0] neg_lo:[0,1] neg_hi:[0,1]
	v_pk_mul_f32 v[52:53], v[44:45], v[44:45]
	v_pk_mul_f32 v[54:55], v[24:25], v[24:25]
	v_add_f32_e32 v52, v52, v53
	v_add_f32_e32 v52, v54, v52
	v_pk_mul_f32 v[56:57], v[48:49], v[48:49]
	v_add_f32_e32 v52, v55, v52
	v_add_f32_e32 v52, v56, v52
	v_pk_mul_f32 v[58:59], v[26:27], v[26:27]
	v_add_f32_e32 v52, v57, v52
	v_add_f32_e32 v52, v58, v52
	v_pk_mul_f32 v[60:61], v[28:29], v[28:29]
	v_add_f32_e32 v52, v59, v52
	v_add_f32_e32 v52, v60, v52
	v_pk_mul_f32 v[62:63], v[16:17], v[16:17]
	v_add_f32_e32 v52, v61, v52
	v_add_f32_e32 v52, v62, v52
	v_pk_mul_f32 v[64:65], v[20:21], v[20:21]
	v_add_f32_e32 v52, v63, v52
	v_add_f32_e32 v52, v64, v52
	v_pk_mul_f32 v[66:67], v[18:19], v[18:19]
	v_add_f32_e32 v52, v65, v52
	v_add_f32_e32 v52, v66, v52
	v_pk_mul_f32 v[68:69], v[22:23], v[22:23]
	v_add_f32_e32 v52, v67, v52
	v_add_f32_e32 v52, v68, v52
	v_pk_mul_f32 v[70:71], v[8:9], v[8:9]
	v_add_f32_e32 v52, v69, v52
	v_add_f32_e32 v52, v70, v52
	v_pk_mul_f32 v[72:73], v[12:13], v[12:13]
	v_add_f32_e32 v52, v71, v52
	v_add_f32_e32 v52, v72, v52
	v_pk_mul_f32 v[74:75], v[10:11], v[10:11]
	v_add_f32_e32 v52, v73, v52
	v_add_f32_e32 v52, v74, v52
	v_pk_mul_f32 v[104:105], v[14:15], v[14:15]
	v_add_f32_e32 v52, v75, v52
	v_add_f32_e32 v52, v104, v52
	v_pk_mul_f32 v[106:107], v[50:51], v[50:51]
	v_add_f32_e32 v52, v105, v52
	v_add_f32_e32 v52, v106, v52
	v_pk_mul_f32 v[110:111], v[30:31], v[30:31]
	v_add_f32_e32 v52, v107, v52
	v_add_f32_e32 v52, v110, v52
	v_pk_mul_f32 v[108:109], v[46:47], v[46:47]
	v_add_f32_e32 v52, v111, v52
	v_add_f32_e32 v52, v108, v52
	v_add_f32_e32 v52, v109, v52
	ds_bpermute_b32 v53, v79, v52
	v_cvt_f32_f16_sdwa v73, v141 dst_sel:DWORD dst_unused:UNUSED_PAD src0_sel:WORD_1
	v_cvt_f32_f16_e32 v72, v141
	v_cvt_f32_f16_sdwa v61, v147 dst_sel:DWORD dst_unused:UNUSED_PAD src0_sel:WORD_1
	v_cvt_f32_f16_e32 v60, v147
	s_waitcnt lgkmcnt(0)
	v_add_f32_e32 v52, v52, v53
	ds_bpermute_b32 v53, v80, v52
	v_cvt_f32_f16_sdwa v63, v146 dst_sel:DWORD dst_unused:UNUSED_PAD src0_sel:WORD_1
	v_cvt_f32_f16_e32 v62, v146
	v_cvt_f32_f16_sdwa v65, v145 dst_sel:DWORD dst_unused:UNUSED_PAD src0_sel:WORD_1
	v_cvt_f32_f16_e32 v64, v145
	s_waitcnt lgkmcnt(0)
	v_add_f32_e32 v52, v52, v53
	ds_bpermute_b32 v53, v81, v52
	v_cvt_f32_f16_sdwa v67, v144 dst_sel:DWORD dst_unused:UNUSED_PAD src0_sel:WORD_1
	v_cvt_f32_f16_e32 v66, v144
	v_cvt_f32_f16_sdwa v69, v143 dst_sel:DWORD dst_unused:UNUSED_PAD src0_sel:WORD_1
	v_cvt_f32_f16_e32 v68, v143
	s_waitcnt lgkmcnt(0)
	v_add_f32_e32 v52, v52, v53
	ds_bpermute_b32 v53, v82, v52
	v_cvt_f32_f16_sdwa v71, v142 dst_sel:DWORD dst_unused:UNUSED_PAD src0_sel:WORD_1
	v_cvt_f32_f16_e32 v70, v142
	s_waitcnt lgkmcnt(0)
	v_add_f32_e32 v52, v52, v53
	ds_bpermute_b32 v53, v83, v52
	s_waitcnt lgkmcnt(0)
	v_add_f32_e32 v52, v52, v53
	ds_bpermute_b32 v53, v84, v52
	s_waitcnt lgkmcnt(0)
	v_add_f32_e32 v52, v52, v53
	v_fmamk_f32 v52, v52, 0x3a000000, v101
	v_mul_f32_e32 v53, 0x4f800000, v52
	v_cmp_gt_f32_e32 vcc, s7, v52
	s_nop 1
	v_cndmask_b32_e32 v52, v52, v53, vcc
	v_sqrt_f32_e32 v53, v52
	s_nop 0
	v_add_u32_e32 v54, -1, v53
	v_add_u32_e32 v55, 1, v53
	v_fma_f32 v56, -v54, v53, v52
	v_fma_f32 v57, -v55, v53, v52
	v_cmp_ge_f32_e64 s[0:1], 0, v56
	s_nop 1
	v_cndmask_b32_e64 v53, v53, v54, s[0:1]
	v_cmp_lt_f32_e64 s[0:1], 0, v57
	s_nop 1
	v_cndmask_b32_e64 v53, v53, v55, s[0:1]
	v_mul_f32_e32 v54, 0x37800000, v53
	v_cndmask_b32_e32 v53, v53, v54, vcc
	v_cmp_class_f32_e32 vcc, v52, v102
	s_nop 1
	v_cndmask_b32_e32 v54, v53, v52, vcc
	v_div_scale_f32 v55, s[0:1], v54, v54, 1.0
	v_rcp_f32_e32 v56, v55
	v_div_scale_f32 v57, vcc, 1.0, v54, 1.0
	v_lshl_add_u64 v[52:53], s[14:15], 0, v[36:37]
	v_fma_f32 v58, -v55, v56, 1.0
	v_fmac_f32_e32 v56, v58, v56
	v_mul_f32_e32 v58, v57, v56
	v_fma_f32 v59, -v55, v58, v57
	v_fmac_f32_e32 v58, v59, v56
	v_fma_f32 v55, -v55, v58, v57
	v_div_fmas_f32 v55, v55, v56, v58
	v_div_fixup_f32 v54, v55, v54, 1.0
	v_pk_mul_f32 v[44:45], v[44:45], v[54:55] op_sel_hi:[1,0]
	v_pk_mul_f32 v[24:25], v[24:25], v[54:55] op_sel_hi:[1,0]
	v_pk_fma_f32 v[0:1], v[172:173], v[44:45], v[204:205]
	v_pk_fma_f32 v[2:3], v[174:175], v[24:25], v[206:207]
	global_store_dwordx4 v[52:53], v[0:3], off
	s_nop 1
	s_nop 0
	v_pk_mul_f32 v[24:25], v[26:27], v[54:55] op_sel_hi:[1,0]
	v_pk_mul_f32 v[26:27], v[48:49], v[54:55] op_sel_hi:[1,0]
	v_pk_mul_f32 v[16:17], v[16:17], v[54:55] op_sel_hi:[1,0]
	v_pk_mul_f32 v[8:9], v[8:9], v[54:55] op_sel_hi:[1,0]
	s_or_b32 s0, s10, 3
	s_ashr_i32 s1, s0, 31
	s_lshl_b64 s[10:11], s[0:1], 11
	v_cvt_f32_f16_sdwa v49, v148 dst_sel:DWORD dst_unused:UNUSED_PAD src0_sel:WORD_1
	v_cvt_f32_f16_e32 v48, v148
	v_cvt_f32_f16_sdwa v57, v157 dst_sel:DWORD dst_unused:UNUSED_PAD src0_sel:WORD_1
	v_cvt_f32_f16_e32 v56, v157
	v_cvt_f32_f16_sdwa v59, v156 dst_sel:DWORD dst_unused:UNUSED_PAD src0_sel:WORD_1
	v_cvt_f32_f16_e32 v58, v156
	s_lshl_b64 s[0:1], s[0:1], 13
	v_pk_fma_f32 v[0:1], v[176:177], v[26:27], v[208:209]
	v_pk_fma_f32 v[2:3], v[178:179], v[24:25], v[210:211]
	global_store_dwordx4 v[52:53], v[0:3], off offset:16
	s_nop 1
	s_nop 0
	v_pk_mul_f32 v[24:25], v[28:29], v[54:55] op_sel_hi:[1,0]
	v_pk_fma_f32 v[2:3], v[182:183], v[16:17], v[214:215]
	v_pk_fma_f32 v[0:1], v[180:181], v[24:25], v[212:213]
	global_store_dwordx4 v[52:53], v[0:3], off offset:32
	s_nop 1
	s_nop 0
	v_pk_mul_f32 v[16:17], v[18:19], v[54:55] op_sel_hi:[1,0]
	v_pk_mul_f32 v[18:19], v[20:21], v[54:55] op_sel_hi:[1,0]
	v_pk_fma_f32 v[2:3], v[186:187], v[16:17], v[218:219]
	v_pk_fma_f32 v[0:1], v[184:185], v[18:19], v[216:217]
	global_store_dwordx4 v[52:53], v[0:3], off offset:48
	s_nop 1
	s_nop 0
	v_add_co_u32_e32 v16, vcc, s12, v52
	v_pk_mul_f32 v[18:19], v[22:23], v[54:55] op_sel_hi:[1,0]
	s_nop 0
	v_addc_co_u32_e32 v17, vcc, 0, v53, vcc
	v_cvt_f32_f16_sdwa v53, v159 dst_sel:DWORD dst_unused:UNUSED_PAD src0_sel:WORD_1
	v_cvt_f32_f16_e32 v52, v159
	v_pk_fma_f32 v[0:1], v[188:189], v[18:19], v[220:221]
	v_pk_fma_f32 v[2:3], v[190:191], v[8:9], v[222:223]
	global_store_dwordx4 v[16:17], v[0:3], off
	s_nop 1
	s_nop 0
	v_pk_mul_f32 v[8:9], v[10:11], v[54:55] op_sel_hi:[1,0]
	v_pk_mul_f32 v[10:11], v[12:13], v[54:55] op_sel_hi:[1,0]
	v_pk_mul_f32 v[12:13], v[30:31], v[54:55] op_sel_hi:[1,0]
	v_pk_fma_f32 v[0:1], v[192:193], v[10:11], v[224:225]
	v_pk_fma_f32 v[2:3], v[194:195], v[8:9], v[226:227]
	global_store_dwordx4 v[16:17], v[0:3], off offset:16
	s_nop 1
	s_nop 0
	v_pk_mul_f32 v[8:9], v[50:51], v[54:55] op_sel_hi:[1,0]
	v_pk_mul_f32 v[10:11], v[14:15], v[54:55] op_sel_hi:[1,0]
	v_cvt_f32_f16_sdwa v51, v160 dst_sel:DWORD dst_unused:UNUSED_PAD src0_sel:WORD_1
	v_cvt_f32_f16_e32 v50, v160
	v_pk_fma_f32 v[0:1], v[196:197], v[10:11], v[228:229]
	v_pk_fma_f32 v[2:3], v[198:199], v[8:9], v[230:231]
	global_store_dwordx4 v[16:17], v[0:3], off offset:32
	s_nop 1
	s_nop 0
	v_lshl_add_u64 v[8:9], s[10:11], 0, v[42:43]
	v_pk_mul_f32 v[10:11], v[46:47], v[54:55] op_sel_hi:[1,0]
	v_lshlrev_b64 v[8:9], 1, v[8:9]
	v_lshl_add_u64 v[42:43], s[70:71], 0, v[8:9]
	v_lshl_add_u64 v[44:45], s[2:3], 0, v[8:9]
	v_cvt_f32_f16_sdwa v47, v161 dst_sel:DWORD dst_unused:UNUSED_PAD src0_sel:WORD_1
	v_cvt_f32_f16_e32 v46, v161
	v_cvt_f32_f16_sdwa v55, v158 dst_sel:DWORD dst_unused:UNUSED_PAD src0_sel:WORD_1
	v_cvt_f32_f16_e32 v54, v158
	s_add_u32 s10, s20, s0
	s_addc_u32 s11, s21, s1
	v_lshl_add_u64 v[36:37], s[10:11], 0, v[36:37]
	s_mov_b32 s10, 1
	v_pk_fma_f32 v[0:1], v[200:201], v[12:13], v[232:233]
	v_pk_fma_f32 v[2:3], v[202:203], v[10:11], v[234:235]
	global_store_dwordx4 v[16:17], v[0:3], off offset:48
	s_nop 1
	global_load_dwordx4 v[4:7], v[42:43], off offset:2064
	s_nop 0
	global_load_dwordx4 v[0:3], v[44:45], off offset:2064
	global_load_dwordx4 v[28:31], v[42:43], off
	global_load_dwordx4 v[24:27], v[44:45], off
	global_load_dwordx4 v[20:23], v[42:43], off offset:16
	global_load_dwordx4 v[16:19], v[44:45], off offset:16
	global_load_dwordx4 v[12:15], v[42:43], off offset:2048
	global_load_dwordx4 v[8:11], v[44:45], off offset:2048
	v_cvt_f32_f16_sdwa v43, v149 dst_sel:DWORD dst_unused:UNUSED_PAD src0_sel:WORD_1
	v_cvt_f32_f16_e32 v42, v149
	v_cvt_f32_f16_sdwa v45, v162 dst_sel:DWORD dst_unused:UNUSED_PAD src0_sel:WORD_1
	v_cvt_f32_f16_e32 v44, v162
	s_waitcnt vmcnt(6)
	v_and_b32_e32 v105, 0xffff0000, v2
	v_lshlrev_b32_e32 v104, 16, v2
	s_waitcnt vmcnt(5)
	v_lshlrev_b32_e32 v106, 16, v28
	v_and_b32_e32 v107, 0xffff0000, v28
	s_waitcnt vmcnt(4)
	v_lshlrev_b32_e32 v108, 16, v24
	v_and_b32_e32 v75, 0xffff0000, v6
	v_lshlrev_b32_e32 v74, 16, v6
	v_and_b32_e32 v109, 0xffff0000, v24
	v_and_b32_e32 v111, 0xffff0000, v7
	v_lshlrev_b32_e32 v110, 16, v7
	v_and_b32_e32 v7, 0xffff0000, v3
	v_lshlrev_b32_e32 v6, 16, v3
	v_lshlrev_b32_e32 v2, 16, v30
	v_and_b32_e32 v3, 0xffff0000, v30
	v_lshlrev_b32_e32 v112, 16, v26
	v_and_b32_e32 v113, 0xffff0000, v26
	v_lshlrev_b32_e32 v30, 16, v31
	v_and_b32_e32 v31, 0xffff0000, v31
	v_lshlrev_b32_e32 v26, 16, v27
	v_and_b32_e32 v27, 0xffff0000, v27
	v_lshlrev_b32_e32 v130, 16, v4
	v_and_b32_e32 v131, 0xffff0000, v4
	v_lshlrev_b32_e32 v132, 16, v0
	v_and_b32_e32 v133, 0xffff0000, v0
	v_lshlrev_b32_e32 v4, 16, v5
	v_and_b32_e32 v5, 0xffff0000, v5
	v_lshlrev_b32_e32 v0, 16, v1
	v_and_b32_e32 v1, 0xffff0000, v1
	v_pk_fma_f32 v[74:75], v[74:75], s[6:7], v[104:105] op_sel_hi:[1,0,1]
	v_pk_fma_f32 v[104:105], v[106:107], s[6:7], v[108:109] op_sel_hi:[1,0,1]
	v_lshlrev_b32_e32 v28, 16, v29
	v_and_b32_e32 v29, 0xffff0000, v29
	v_lshlrev_b32_e32 v24, 16, v25
	v_and_b32_e32 v25, 0xffff0000, v25
	v_pk_fma_f32 v[6:7], v[110:111], s[6:7], v[6:7] op_sel_hi:[1,0,1]
	v_pk_fma_f32 v[26:27], v[30:31], s[6:7], v[26:27] op_sel_hi:[1,0,1]
	v_pk_fma_f32 v[0:1], v[4:5], s[6:7], v[0:1] op_sel_hi:[1,0,1]
	v_pk_add_f32 v[30:31], v[74:75], v[42:43]
	v_pk_add_f32 v[42:43], v[104:105], v[44:45]
	v_pk_fma_f32 v[24:25], v[28:29], s[6:7], v[24:25] op_sel_hi:[1,0,1]
	v_pk_add_f32 v[44:45], v[6:7], v[48:49]
	v_pk_add_f32 v[48:49], v[0:1], v[72:73]
	v_add_f32_e32 v0, 0, v42
	v_pk_add_f32 v[24:25], v[24:25], v[46:47]
	v_add_f32_e32 v0, v43, v0
	v_pk_fma_f32 v[2:3], v[2:3], s[6:7], v[112:113] op_sel_hi:[1,0,1]
	v_add_f32_e32 v0, v24, v0
	v_pk_add_f32 v[46:47], v[2:3], v[50:51]
	v_add_f32_e32 v0, v25, v0
	v_add_f32_e32 v0, v46, v0
	s_waitcnt vmcnt(3)
	v_lshlrev_b32_e32 v114, 16, v20
	v_and_b32_e32 v115, 0xffff0000, v20
	s_waitcnt vmcnt(2)
	v_lshlrev_b32_e32 v116, 16, v16
	v_and_b32_e32 v117, 0xffff0000, v16
	v_pk_add_f32 v[26:27], v[26:27], v[52:53]
	v_add_f32_e32 v0, v47, v0
	v_pk_fma_f32 v[28:29], v[114:115], s[6:7], v[116:117] op_sel_hi:[1,0,1]
	v_add_f32_e32 v0, v26, v0
	v_lshlrev_b32_e32 v20, 16, v21
	v_and_b32_e32 v21, 0xffff0000, v21
	v_lshlrev_b32_e32 v16, 16, v17
	v_and_b32_e32 v17, 0xffff0000, v17
	v_pk_add_f32 v[28:29], v[28:29], v[54:55]
	v_add_f32_e32 v0, v27, v0
	v_pk_fma_f32 v[16:17], v[20:21], s[6:7], v[16:17] op_sel_hi:[1,0,1]
	v_add_f32_e32 v0, v28, v0
	v_lshlrev_b32_e32 v118, 16, v22
	v_and_b32_e32 v119, 0xffff0000, v22
	v_lshlrev_b32_e32 v120, 16, v18
	v_and_b32_e32 v121, 0xffff0000, v18
	v_pk_add_f32 v[16:17], v[16:17], v[56:57]
	v_add_f32_e32 v0, v29, v0
	v_pk_fma_f32 v[20:21], v[118:119], s[6:7], v[120:121] op_sel_hi:[1,0,1]
	v_add_f32_e32 v0, v16, v0
	v_lshlrev_b32_e32 v22, 16, v23
	v_and_b32_e32 v23, 0xffff0000, v23
	v_lshlrev_b32_e32 v18, 16, v19
	v_and_b32_e32 v19, 0xffff0000, v19
	v_pk_add_f32 v[20:21], v[20:21], v[58:59]
	v_add_f32_e32 v0, v17, v0
	v_pk_fma_f32 v[18:19], v[22:23], s[6:7], v[18:19] op_sel_hi:[1,0,1]
	v_add_f32_e32 v0, v20, v0
	s_waitcnt vmcnt(1)
	v_lshlrev_b32_e32 v122, 16, v12
	v_and_b32_e32 v123, 0xffff0000, v12
	s_waitcnt vmcnt(0)
	v_lshlrev_b32_e32 v124, 16, v8
	v_and_b32_e32 v125, 0xffff0000, v8
	v_pk_add_f32 v[18:19], v[18:19], v[60:61]
	v_add_f32_e32 v0, v21, v0
	v_pk_fma_f32 v[22:23], v[122:123], s[6:7], v[124:125] op_sel_hi:[1,0,1]
	v_add_f32_e32 v0, v18, v0
	v_lshlrev_b32_e32 v12, 16, v13
	v_and_b32_e32 v13, 0xffff0000, v13
	v_lshlrev_b32_e32 v8, 16, v9
	v_and_b32_e32 v9, 0xffff0000, v9
	v_pk_add_f32 v[22:23], v[22:23], v[62:63]
	v_add_f32_e32 v0, v19, v0
	v_pk_fma_f32 v[8:9], v[12:13], s[6:7], v[8:9] op_sel_hi:[1,0,1]
	v_add_f32_e32 v0, v22, v0
	v_lshlrev_b32_e32 v126, 16, v14
	v_and_b32_e32 v127, 0xffff0000, v14
	v_lshlrev_b32_e32 v128, 16, v10
	v_and_b32_e32 v129, 0xffff0000, v10
	v_pk_add_f32 v[8:9], v[8:9], v[64:65]
	v_add_f32_e32 v0, v23, v0
	v_pk_fma_f32 v[12:13], v[126:127], s[6:7], v[128:129] op_sel_hi:[1,0,1]
	v_add_f32_e32 v0, v8, v0
	v_lshlrev_b32_e32 v14, 16, v15
	v_and_b32_e32 v15, 0xffff0000, v15
	v_lshlrev_b32_e32 v10, 16, v11
	v_and_b32_e32 v11, 0xffff0000, v11
	v_pk_add_f32 v[12:13], v[12:13], v[66:67]
	v_add_f32_e32 v0, v9, v0
	v_pk_fma_f32 v[10:11], v[14:15], s[6:7], v[10:11] op_sel_hi:[1,0,1]
	v_add_f32_e32 v0, v12, v0
	v_pk_add_f32 v[10:11], v[10:11], v[68:69]
	v_add_f32_e32 v0, v13, v0
	v_pk_fma_f32 v[14:15], v[130:131], s[6:7], v[132:133] op_sel_hi:[1,0,1]
	v_add_f32_e32 v0, v10, v0
	v_pk_add_f32 v[14:15], v[14:15], v[70:71]
	v_add_f32_e32 v0, v11, v0
	v_add_f32_e32 v0, v14, v0
	v_add_f32_e32 v0, v15, v0
	v_add_f32_e32 v0, v48, v0
	v_add_f32_e32 v0, v49, v0
	v_add_f32_e32 v0, v30, v0
	v_add_f32_e32 v0, v31, v0
	v_add_f32_e32 v0, v44, v0
	v_add_f32_e32 v0, v45, v0
	ds_bpermute_b32 v1, v79, v0
	s_waitcnt lgkmcnt(0)
	v_add_f32_e32 v0, v0, v1
	ds_bpermute_b32 v1, v80, v0
	s_waitcnt lgkmcnt(0)
	v_add_f32_e32 v0, v0, v1
	ds_bpermute_b32 v1, v81, v0
	s_waitcnt lgkmcnt(0)
	v_add_f32_e32 v0, v0, v1
	ds_bpermute_b32 v1, v82, v0
	s_waitcnt lgkmcnt(0)
	v_add_f32_e32 v0, v0, v1
	ds_bpermute_b32 v1, v83, v0
	s_waitcnt lgkmcnt(0)
	v_add_f32_e32 v50, v0, v1
	ds_bpermute_b32 v51, v84, v50
	s_waitcnt lgkmcnt(0)
	v_add_f32_e32 v50, v50, v51
	v_mul_f32_e32 v50, 0x3a000000, v50
	v_pk_add_f32 v[42:43], v[42:43], v[50:51] op_sel_hi:[1,0] neg_lo:[0,1] neg_hi:[0,1]
	v_pk_add_f32 v[24:25], v[24:25], v[50:51] op_sel_hi:[1,0] neg_lo:[0,1] neg_hi:[0,1]
	v_pk_add_f32 v[46:47], v[46:47], v[50:51] op_sel_hi:[1,0] neg_lo:[0,1] neg_hi:[0,1]
	v_pk_add_f32 v[26:27], v[26:27], v[50:51] op_sel_hi:[1,0] neg_lo:[0,1] neg_hi:[0,1]
	v_pk_add_f32 v[28:29], v[28:29], v[50:51] op_sel_hi:[1,0] neg_lo:[0,1] neg_hi:[0,1]
	v_pk_add_f32 v[16:17], v[16:17], v[50:51] op_sel_hi:[1,0] neg_lo:[0,1] neg_hi:[0,1]
	v_pk_add_f32 v[20:21], v[20:21], v[50:51] op_sel_hi:[1,0] neg_lo:[0,1] neg_hi:[0,1]
	v_pk_add_f32 v[18:19], v[18:19], v[50:51] op_sel_hi:[1,0] neg_lo:[0,1] neg_hi:[0,1]
	v_pk_add_f32 v[22:23], v[22:23], v[50:51] op_sel_hi:[1,0] neg_lo:[0,1] neg_hi:[0,1]
	v_pk_add_f32 v[8:9], v[8:9], v[50:51] op_sel_hi:[1,0] neg_lo:[0,1] neg_hi:[0,1]
	v_pk_add_f32 v[12:13], v[12:13], v[50:51] op_sel_hi:[1,0] neg_lo:[0,1] neg_hi:[0,1]
	v_pk_add_f32 v[10:11], v[10:11], v[50:51] op_sel_hi:[1,0] neg_lo:[0,1] neg_hi:[0,1]
	v_pk_add_f32 v[14:15], v[14:15], v[50:51] op_sel_hi:[1,0] neg_lo:[0,1] neg_hi:[0,1]
	v_pk_add_f32 v[48:49], v[48:49], v[50:51] op_sel_hi:[1,0] neg_lo:[0,1] neg_hi:[0,1]
	v_pk_add_f32 v[44:45], v[44:45], v[50:51] op_sel_hi:[1,0] neg_lo:[0,1] neg_hi:[0,1]
	v_pk_add_f32 v[30:31], v[30:31], v[50:51] op_sel_hi:[1,0] neg_lo:[0,1] neg_hi:[0,1]
	v_pk_mul_f32 v[50:51], v[42:43], v[42:43]
	v_pk_mul_f32 v[52:53], v[24:25], v[24:25]
	v_add_f32_e32 v50, v50, v51
	v_add_f32_e32 v50, v52, v50
	v_pk_mul_f32 v[54:55], v[46:47], v[46:47]
	v_add_f32_e32 v50, v53, v50
	v_add_f32_e32 v50, v54, v50
	v_pk_mul_f32 v[56:57], v[26:27], v[26:27]
	v_add_f32_e32 v50, v55, v50
	v_add_f32_e32 v50, v56, v50
	v_pk_mul_f32 v[58:59], v[28:29], v[28:29]
	v_add_f32_e32 v50, v57, v50
	v_add_f32_e32 v50, v58, v50
	v_pk_mul_f32 v[60:61], v[16:17], v[16:17]
	v_add_f32_e32 v50, v59, v50
	v_add_f32_e32 v50, v60, v50
	v_pk_mul_f32 v[62:63], v[20:21], v[20:21]
	v_add_f32_e32 v50, v61, v50
	v_add_f32_e32 v50, v62, v50
	v_pk_mul_f32 v[64:65], v[18:19], v[18:19]
	v_add_f32_e32 v50, v63, v50
	v_add_f32_e32 v50, v64, v50
	v_pk_mul_f32 v[66:67], v[22:23], v[22:23]
	v_add_f32_e32 v50, v65, v50
	v_add_f32_e32 v50, v66, v50
	v_pk_mul_f32 v[68:69], v[8:9], v[8:9]
	v_add_f32_e32 v50, v67, v50
	v_add_f32_e32 v50, v68, v50
	v_pk_mul_f32 v[70:71], v[12:13], v[12:13]
	v_add_f32_e32 v50, v69, v50
	v_add_f32_e32 v50, v70, v50
	v_pk_mul_f32 v[72:73], v[10:11], v[10:11]
	v_add_f32_e32 v50, v71, v50
	v_add_f32_e32 v50, v72, v50
	v_pk_mul_f32 v[74:75], v[14:15], v[14:15]
	v_add_f32_e32 v50, v73, v50
	v_add_f32_e32 v50, v74, v50
	v_pk_mul_f32 v[104:105], v[48:49], v[48:49]
	v_add_f32_e32 v50, v75, v50
	v_add_f32_e32 v50, v104, v50
	v_pk_mul_f32 v[108:109], v[30:31], v[30:31]
	v_add_f32_e32 v50, v105, v50
	v_add_f32_e32 v50, v108, v50
	v_pk_mul_f32 v[106:107], v[44:45], v[44:45]
	v_add_f32_e32 v50, v109, v50
	v_add_f32_e32 v50, v106, v50
	v_add_f32_e32 v50, v107, v50
	ds_bpermute_b32 v51, v79, v50
	s_waitcnt lgkmcnt(0)
	v_add_f32_e32 v50, v50, v51
	ds_bpermute_b32 v51, v80, v50
	s_waitcnt lgkmcnt(0)
	v_add_f32_e32 v50, v50, v51
	ds_bpermute_b32 v51, v81, v50
	s_waitcnt lgkmcnt(0)
	v_add_f32_e32 v50, v50, v51
	ds_bpermute_b32 v51, v82, v50
	s_waitcnt lgkmcnt(0)
	v_add_f32_e32 v50, v50, v51
	ds_bpermute_b32 v51, v83, v50
	s_waitcnt lgkmcnt(0)
	v_add_f32_e32 v50, v50, v51
	ds_bpermute_b32 v51, v84, v50
	s_waitcnt lgkmcnt(0)
	v_add_f32_e32 v50, v50, v51
	v_fmamk_f32 v50, v50, 0x3a000000, v101
	v_mul_f32_e32 v51, 0x4f800000, v50
	v_cmp_gt_f32_e32 vcc, s7, v50
	s_nop 1
	v_cndmask_b32_e32 v50, v50, v51, vcc
	v_sqrt_f32_e32 v51, v50
	s_nop 0
	v_add_u32_e32 v52, -1, v51
	v_add_u32_e32 v53, 1, v51
	v_fma_f32 v54, -v52, v51, v50
	v_fma_f32 v55, -v53, v51, v50
	v_cmp_ge_f32_e64 s[0:1], 0, v54
	s_nop 1
	v_cndmask_b32_e64 v51, v51, v52, s[0:1]
	v_cmp_lt_f32_e64 s[0:1], 0, v55
	s_nop 1
	v_cndmask_b32_e64 v51, v51, v53, s[0:1]
	v_mul_f32_e32 v52, 0x37800000, v51
	v_cndmask_b32_e32 v51, v51, v52, vcc
	v_cmp_class_f32_e32 vcc, v50, v102
	s_nop 1
	v_cndmask_b32_e32 v50, v51, v50, vcc
	v_div_scale_f32 v51, s[0:1], v50, v50, 1.0
	v_rcp_f32_e32 v52, v51
	v_div_scale_f32 v53, vcc, 1.0, v50, 1.0
	s_mov_b64 s[0:1], 0
	v_fma_f32 v54, -v51, v52, 1.0
	v_fmac_f32_e32 v52, v54, v52
	v_mul_f32_e32 v54, v53, v52
	v_fma_f32 v55, -v51, v54, v53
	v_fmac_f32_e32 v54, v55, v52
	v_fma_f32 v51, -v51, v54, v53
	v_div_fmas_f32 v51, v51, v52, v54
	v_div_fixup_f32 v50, v51, v50, 1.0
	v_pk_mul_f32 v[42:43], v[42:43], v[50:51] op_sel_hi:[1,0]
	v_pk_mul_f32 v[24:25], v[24:25], v[50:51] op_sel_hi:[1,0]
	v_pk_fma_f32 v[0:1], v[172:173], v[42:43], v[204:205]
	v_pk_fma_f32 v[2:3], v[174:175], v[24:25], v[206:207]
	global_store_dwordx4 v[36:37], v[0:3], off
	s_nop 1
	s_nop 0
	v_pk_mul_f32 v[24:25], v[26:27], v[50:51] op_sel_hi:[1,0]
	v_pk_mul_f32 v[26:27], v[46:47], v[50:51] op_sel_hi:[1,0]
	v_pk_mul_f32 v[16:17], v[16:17], v[50:51] op_sel_hi:[1,0]
	v_pk_mul_f32 v[8:9], v[8:9], v[50:51] op_sel_hi:[1,0]
	v_pk_fma_f32 v[0:1], v[176:177], v[26:27], v[208:209]
	v_pk_fma_f32 v[2:3], v[178:179], v[24:25], v[210:211]
	global_store_dwordx4 v[36:37], v[0:3], off offset:16
	s_nop 1
	s_nop 0
	v_pk_mul_f32 v[24:25], v[28:29], v[50:51] op_sel_hi:[1,0]
	v_pk_fma_f32 v[2:3], v[182:183], v[16:17], v[214:215]
	v_pk_fma_f32 v[0:1], v[180:181], v[24:25], v[212:213]
	global_store_dwordx4 v[36:37], v[0:3], off offset:32
	s_nop 1
	s_nop 0
	v_pk_mul_f32 v[16:17], v[18:19], v[50:51] op_sel_hi:[1,0]
	v_pk_mul_f32 v[18:19], v[20:21], v[50:51] op_sel_hi:[1,0]
	v_pk_fma_f32 v[2:3], v[186:187], v[16:17], v[218:219]
	v_pk_fma_f32 v[0:1], v[184:185], v[18:19], v[216:217]
	global_store_dwordx4 v[36:37], v[0:3], off offset:48
	s_nop 1
	s_nop 0
	v_add_co_u32_e32 v16, vcc, s12, v36
	v_pk_mul_f32 v[18:19], v[22:23], v[50:51] op_sel_hi:[1,0]
	s_nop 0
	v_addc_co_u32_e32 v17, vcc, 0, v37, vcc
	s_and_b64 vcc, exec, s[8:9]
	v_pk_fma_f32 v[0:1], v[188:189], v[18:19], v[220:221]
	v_pk_fma_f32 v[2:3], v[190:191], v[8:9], v[222:223]
	global_store_dwordx4 v[16:17], v[0:3], off
	s_nop 1
	s_nop 0
	v_pk_mul_f32 v[8:9], v[10:11], v[50:51] op_sel_hi:[1,0]
	v_pk_mul_f32 v[10:11], v[12:13], v[50:51] op_sel_hi:[1,0]
	v_pk_fma_f32 v[2:3], v[194:195], v[8:9], v[226:227]
	v_pk_fma_f32 v[0:1], v[192:193], v[10:11], v[224:225]
	global_store_dwordx4 v[16:17], v[0:3], off offset:16
	s_nop 1
	s_nop 0
	v_pk_mul_f32 v[8:9], v[48:49], v[50:51] op_sel_hi:[1,0]
	v_pk_mul_f32 v[10:11], v[14:15], v[50:51] op_sel_hi:[1,0]
	v_pk_fma_f32 v[2:3], v[198:199], v[8:9], v[230:231]
	v_pk_fma_f32 v[0:1], v[196:197], v[10:11], v[228:229]
	global_store_dwordx4 v[16:17], v[0:3], off offset:32
	s_nop 1
	s_nop 0
	v_pk_mul_f32 v[8:9], v[44:45], v[50:51] op_sel_hi:[1,0]
	v_pk_mul_f32 v[10:11], v[30:31], v[50:51] op_sel_hi:[1,0]
	v_pk_fma_f32 v[2:3], v[202:203], v[8:9], v[234:235]
	v_pk_fma_f32 v[0:1], v[200:201], v[10:11], v[232:233]
	global_store_dwordx4 v[16:17], v[0:3], off offset:48
	s_nop 1
	s_waitcnt vmcnt(0)
	s_cbranch_vccz .LBB0_1012
